# v19 + q-latent GEMM epilogue grouped loads + forget-gate cumsum loads hoisted
# speedup vs baseline: 1.0170x; 1.0005x over previous
; __device__ __forceinline__ void phase_small(const Params& P, int l) {
;     ...
;     for (int sid = (bx - fb0) * 8 + wid; sid < 32 && bx >= fb0; sid += G * 8) { const int b = sid >> 3, h = sid & 7; const float bias = P.fox_bias[l * 8 + h];
;         float loc[32]; float run = 0.f;
; #pragma unroll
;         for (int i = 0; i < 32; ++i) { const int s = lane * 32 + i; const float xx = misc[(size_t)(b * 2048 + s) * 128 + 64 + h] + bias;
;             const float ls = -(fmaxf(-xx, 0.f) + log1pf(expf(-fabsf(xx)))); run += ls; loc[i] = run; }
.LBB0_900:
	s_movk_i32 s1, 0xf800
	v_and_or_b32 v10, v3, s1, v12
	v_ashrrev_i32_e32 v11, 31, v10
	v_lshlrev_b64 v[18:19], 9, v[10:11]
	v_lshl_add_u64 v[18:19], v[6:7], 0, v[18:19]
	v_mov_b32_e32 v136, 0x1000
	v_mov_b32_e32 v137, 0
	v_mov_b64_e32 v[128:129], v[18:19]
	v_lshl_add_u64 v[130:131], v[128:129], 0, v[136:137]
	v_lshl_add_u64 v[132:133], v[130:131], 0, v[136:137]
	v_lshl_add_u64 v[134:135], v[132:133], 0, v[136:137]
	global_load_dword v96, v[128:129], off offset:256
	global_load_dword v97, v[128:129], off offset:768
	global_load_dword v98, v[128:129], off offset:1280
	global_load_dword v99, v[128:129], off offset:1792
	global_load_dword v100, v[128:129], off offset:2304
	global_load_dword v101, v[128:129], off offset:2816
	global_load_dword v102, v[128:129], off offset:3328
	global_load_dword v103, v[128:129], off offset:3840
	global_load_dword v104, v[130:131], off offset:256
	global_load_dword v105, v[130:131], off offset:768
	global_load_dword v106, v[130:131], off offset:1280
	global_load_dword v107, v[130:131], off offset:1792
	global_load_dword v108, v[130:131], off offset:2304
	global_load_dword v109, v[130:131], off offset:2816
	global_load_dword v110, v[130:131], off offset:3328
	global_load_dword v111, v[130:131], off offset:3840
	global_load_dword v112, v[132:133], off offset:256
	global_load_dword v113, v[132:133], off offset:768
	global_load_dword v114, v[132:133], off offset:1280
	global_load_dword v115, v[132:133], off offset:1792
	global_load_dword v116, v[132:133], off offset:2304
	global_load_dword v117, v[132:133], off offset:2816
	global_load_dword v118, v[132:133], off offset:3328
	global_load_dword v119, v[132:133], off offset:3840
	global_load_dword v120, v[134:135], off offset:256
	global_load_dword v121, v[134:135], off offset:768
	global_load_dword v122, v[134:135], off offset:1280
	global_load_dword v123, v[134:135], off offset:1792
	global_load_dword v124, v[134:135], off offset:2304
	global_load_dword v125, v[134:135], off offset:2816
	global_load_dword v126, v[134:135], off offset:3328
	global_load_dword v127, v[134:135], off offset:3840
	global_load_dword v27, v[4:5], off
	v_add_u32_e32 v2, s8, v2
	v_add_u32_e32 v3, s0, v3
	s_waitcnt vmcnt(0) lgkmcnt(0)
	v_add_f32_e32 v11, v27, v96
	v_mul_f32_e64 v18, |v11|, s33
	v_fma_f32 v19, |v11|, s33, -v18
	v_rndne_f32_e32 v20, v18
	v_fma_f32 v19, |v11|, s71, v19
	v_sub_f32_e32 v18, v18, v20
	v_add_f32_e32 v18, v18, v19
	v_exp_f32_e32 v18, v18
	v_cvt_i32_f32_e32 v19, v20
	v_cmp_ngt_f32_e64 s[4:5], |v11|, s72
	v_max_f32_e64 v26, -v11, 0
	v_ldexp_f32 v18, v18, v19
	v_cndmask_b32_e64 v18, 0, v18, s[4:5]
	v_cmp_nlt_f32_e64 s[4:5], |v11|, s73
	s_nop 1
	v_cndmask_b32_e64 v11, v222, v18, s[4:5]
	v_add_f32_e32 v20, 1.0, v11
	v_add_f32_e32 v18, -1.0, v20
	v_sub_f32_e32 v19, v18, v20
	v_add_f32_e32 v19, 1.0, v19
	v_sub_f32_e32 v18, v11, v18
	v_add_f32_e32 v21, v18, v19
	v_frexp_mant_f32_e32 v18, v20
	v_cmp_gt_f32_e64 s[4:5], s75, v18
	v_cvt_f64_f32_e32 v[18:19], v20
	v_frexp_exp_i32_f64_e32 v18, v[18:19]
	v_subbrev_co_u32_e64 v28, s[4:5], 0, v18, s[4:5]
	v_sub_u32_e32 v18, 0, v28
	v_ldexp_f32 v19, v20, v18
	v_add_f32_e32 v20, -1.0, v19
	v_add_f32_e32 v22, 1.0, v19
	v_ldexp_f32 v18, v21, v18
	v_add_f32_e32 v21, 1.0, v20
	v_add_f32_e32 v23, -1.0, v22
	v_sub_f32_e32 v21, v19, v21
	v_sub_f32_e32 v19, v19, v23
	v_add_f32_e32 v21, v18, v21
	v_add_f32_e32 v18, v18, v19
	v_add_f32_e32 v29, v22, v18
	v_rcp_f32_e32 v31, v29
	v_sub_f32_e32 v19, v22, v29
	v_add_f32_e32 v30, v18, v19
	v_add_f32_e32 v19, v20, v21
	v_mul_f32_e32 v33, v19, v31
	v_sub_f32_e32 v18, v20, v19
	v_mul_f32_e32 v20, v29, v33
	v_fma_f32 v22, v33, v29, -v20
	v_fmac_f32_e32 v22, v33, v30
	v_add_f32_e32 v32, v21, v18
	v_add_f32_e32 v18, v20, v22
	v_sub_f32_e32 v21, v19, v18
	v_pk_add_f32 v[24:25], v[18:19], v[20:21] neg_lo:[0,1] neg_hi:[0,1]
	v_mov_b32_e32 v23, v18
	v_pk_add_f32 v[18:19], v[24:25], v[22:23] neg_lo:[0,1] neg_hi:[0,1]
	v_cmp_neq_f32_e64 s[4:5], s74, v11
	v_add_f32_e32 v19, v32, v19
	v_add_f32_e32 v18, v18, v19
	v_add_f32_e32 v19, v21, v18
	v_mul_f32_e32 v32, v31, v19
	v_mul_f32_e32 v20, v29, v32
	v_fma_f32 v22, v32, v29, -v20
	v_fmac_f32_e32 v22, v32, v30
	v_sub_f32_e32 v21, v21, v19
	v_add_f32_e32 v29, v18, v21
	v_add_f32_e32 v18, v20, v22
	v_sub_f32_e32 v21, v19, v18
	v_pk_add_f32 v[24:25], v[18:19], v[20:21] neg_lo:[0,1] neg_hi:[0,1]
	v_mov_b32_e32 v23, v18
	v_pk_add_f32 v[18:19], v[24:25], v[22:23] neg_lo:[0,1] neg_hi:[0,1]
	s_nop 0
	v_add_f32_e32 v19, v29, v19
	v_add_f32_e32 v18, v18, v19
	v_add_f32_e32 v19, v33, v32
	v_add_f32_e32 v18, v21, v18
	v_sub_f32_e32 v20, v19, v33
	v_mul_f32_e32 v18, v31, v18
	v_sub_f32_e32 v20, v32, v20
	v_add_f32_e32 v20, v20, v18
	v_add_f32_e32 v22, v19, v20
	v_mul_f32_e32 v23, v22, v22
	v_fmamk_f32 v18, v23, 0x3e9b6dac, v219
	v_fmaak_f32 v167, v23, v18, 0x3f2aaada
	v_cvt_f32_i32_e32 v18, v28
	v_sub_f32_e32 v19, v22, v19
	v_sub_f32_e32 v19, v20, v19
	v_ldexp_f32 v24, v19, 1
	v_mul_f32_e32 v19, v22, v23
	v_ldexp_f32 v21, v22, 1
	v_pk_mul_f32 v[22:23], v[18:19], v[166:167]
	s_nop 0
	v_fma_f32 v20, v18, s76, -v22
	v_fmac_f32_e32 v20, 0xb102e308, v18
	v_pk_add_f32 v[18:19], v[22:23], v[20:21]
	s_nop 0
	v_sub_f32_e32 v21, v19, v21
	v_sub_f32_e32 v21, v23, v21
	v_add_f32_e32 v25, v24, v21
	v_mov_b32_e32 v24, v22
	v_pk_add_f32 v[22:23], v[18:19], v[22:23] neg_lo:[0,1] neg_hi:[0,1]
	v_pk_add_f32 v[28:29], v[18:19], v[24:25]
	v_mov_b32_e32 v21, v18
	v_mov_b32_e32 v23, v29
	v_pk_add_f32 v[30:31], v[20:21], v[22:23] neg_lo:[0,1] neg_hi:[0,1]
	v_pk_add_f32 v[20:21], v[20:21], v[22:23]
	v_mov_b32_e32 v24, v25
	v_pk_add_f32 v[22:23], v[20:21], v[18:19] op_sel:[1,0] op_sel_hi:[0,1] neg_lo:[0,1] neg_hi:[0,1]
; __device__ __forceinline__ void phase_small(const Params& P, int l) {
;     ...
;         for (int i = 0; i < 32; ++i) { const int s = lane * 32 + i; const float xx = misc[(size_t)(b * 2048 + s) * 128 + 64 + h] + bias;
;             const float ls = -(fmaxf(-xx, 0.f) + log1pf(expf(-fabsf(xx)))); run += ls; loc[i] = run; }
	v_pk_add_f32 v[32:33], v[28:29], v[22:23] op_sel_hi:[1,0] neg_lo:[0,1] neg_hi:[0,1]
	v_mov_b32_e32 v28, v29
	v_mov_b32_e32 v29, v21
	v_pk_mov_b32 v[22:23], v[18:19], v[22:23] op_sel:[1,0]
	v_mov_b32_e32 v25, v18
	v_pk_add_f32 v[22:23], v[28:29], v[22:23] neg_lo:[0,1] neg_hi:[0,1]
	v_mov_b32_e32 v32, v30
	v_pk_add_f32 v[18:19], v[24:25], v[22:23] neg_lo:[0,1] neg_hi:[0,1]
	v_mov_b32_e32 v31, v21
	v_pk_add_f32 v[22:23], v[32:33], v[18:19]
	s_nop 0
	v_pk_add_f32 v[24:25], v[22:23], v[22:23] op_sel:[0,1] op_sel_hi:[1,0]
	s_nop 0
	v_pk_add_f32 v[20:21], v[20:21], v[24:25] op_sel:[1,0] op_sel_hi:[0,1]
	v_mov_b32_e32 v23, v20
	v_pk_add_f32 v[28:29], v[22:23], v[30:31] neg_lo:[0,1] neg_hi:[0,1]
	v_mov_b32_e32 v19, v24
	v_sub_f32_e32 v21, v22, v28
	v_pk_add_f32 v[18:19], v[18:19], v[28:29] neg_lo:[0,1] neg_hi:[0,1]
	v_sub_f32_e32 v21, v30, v21
	v_add_f32_e32 v18, v18, v21
	v_add_f32_e32 v18, v18, v19
	v_add_f32_e32 v18, v20, v18
	v_or_b32_e32 v20, 1, v10
	v_ashrrev_i32_e32 v21, 31, v20
	v_cndmask_b32_e64 v18, v222, v18, s[4:5]
	v_cmp_lt_f32_e64 s[4:5], |v11|, s77
	v_lshlrev_b64 v[20:21], 9, v[20:21]
	v_lshl_add_u64 v[20:21], v[6:7], 0, v[20:21]
	v_cndmask_b32_e64 v11, v18, v11, s[4:5]
	v_add_f32_e32 v18, v26, v11
	v_add_f32_e32 v11, v27, v97
	v_mul_f32_e64 v20, |v11|, s33
	v_fma_f32 v21, |v11|, s33, -v20
	v_rndne_f32_e32 v22, v20
	v_fma_f32 v21, |v11|, s71, v21
	v_sub_f32_e32 v20, v20, v22
	v_add_f32_e32 v20, v20, v21
	v_exp_f32_e32 v20, v20
	v_cvt_i32_f32_e32 v21, v22
	v_cmp_ngt_f32_e64 s[4:5], |v11|, s72
	v_max_f32_e64 v19, -v11, 0
	v_ldexp_f32 v20, v20, v21
	v_cndmask_b32_e64 v20, 0, v20, s[4:5]
	v_cmp_nlt_f32_e64 s[4:5], |v11|, s73
	s_nop 1
	v_cndmask_b32_e64 v11, v222, v20, s[4:5]
	v_add_f32_e32 v22, 1.0, v11
	v_add_f32_e32 v20, -1.0, v22
	v_sub_f32_e32 v21, v20, v22
	v_add_f32_e32 v21, 1.0, v21
	v_sub_f32_e32 v20, v11, v20
	v_add_f32_e32 v23, v20, v21
	v_frexp_mant_f32_e32 v20, v22
	v_cmp_gt_f32_e64 s[4:5], s75, v20
	v_cvt_f64_f32_e32 v[20:21], v22
	v_frexp_exp_i32_f64_e32 v20, v[20:21]
	v_subbrev_co_u32_e64 v26, s[4:5], 0, v20, s[4:5]
	v_sub_u32_e32 v20, 0, v26
	v_ldexp_f32 v21, v22, v20
	v_add_f32_e32 v22, -1.0, v21
	v_add_f32_e32 v24, 1.0, v21
	v_ldexp_f32 v20, v23, v20
	v_add_f32_e32 v23, 1.0, v22
	v_add_f32_e32 v25, -1.0, v24
	v_sub_f32_e32 v23, v21, v23
	v_sub_f32_e32 v21, v21, v25
	v_add_f32_e32 v23, v20, v23
	v_add_f32_e32 v20, v20, v21
	v_add_f32_e32 v30, v24, v20
	v_rcp_f32_e32 v32, v30
	v_sub_f32_e32 v21, v24, v30
	v_add_f32_e32 v31, v20, v21
	v_add_f32_e32 v21, v22, v23
	v_mul_f32_e32 v34, v21, v32
	v_sub_f32_e32 v20, v22, v21
	v_mul_f32_e32 v22, v30, v34
	v_fma_f32 v24, v34, v30, -v22
	v_fmac_f32_e32 v24, v34, v31
	v_add_f32_e32 v33, v23, v20
	v_add_f32_e32 v20, v22, v24
	v_sub_f32_e32 v23, v21, v20
	v_pk_add_f32 v[28:29], v[20:21], v[22:23] neg_lo:[0,1] neg_hi:[0,1]
	v_mov_b32_e32 v25, v20
	v_pk_add_f32 v[20:21], v[28:29], v[24:25] neg_lo:[0,1] neg_hi:[0,1]
	v_cmp_neq_f32_e64 s[4:5], s74, v11
	v_add_f32_e32 v21, v33, v21
	v_add_f32_e32 v20, v20, v21
	v_add_f32_e32 v21, v23, v20
	v_mul_f32_e32 v33, v32, v21
	v_mul_f32_e32 v22, v30, v33
	v_fma_f32 v24, v33, v30, -v22
	v_fmac_f32_e32 v24, v33, v31
	v_sub_f32_e32 v23, v23, v21
	v_add_f32_e32 v30, v20, v23
	v_add_f32_e32 v20, v22, v24
	v_sub_f32_e32 v23, v21, v20
	v_pk_add_f32 v[28:29], v[20:21], v[22:23] neg_lo:[0,1] neg_hi:[0,1]
	v_mov_b32_e32 v25, v20
	v_pk_add_f32 v[20:21], v[28:29], v[24:25] neg_lo:[0,1] neg_hi:[0,1]
	s_nop 0
	v_add_f32_e32 v21, v30, v21
	v_add_f32_e32 v20, v20, v21
	v_add_f32_e32 v21, v34, v33
	v_add_f32_e32 v20, v23, v20
	v_sub_f32_e32 v22, v21, v34
	v_mul_f32_e32 v20, v32, v20
	v_sub_f32_e32 v22, v33, v22
	v_add_f32_e32 v22, v22, v20
	v_add_f32_e32 v24, v21, v22
	v_mul_f32_e32 v25, v24, v24
	v_fmamk_f32 v20, v25, 0x3e9b6dac, v219
	v_fmaak_f32 v167, v25, v20, 0x3f2aaada
	v_cvt_f32_i32_e32 v20, v26
	v_sub_f32_e32 v21, v24, v21
	v_sub_f32_e32 v21, v22, v21
	v_ldexp_f32 v26, v21, 1
	v_mul_f32_e32 v21, v24, v25
	v_ldexp_f32 v23, v24, 1
	v_pk_mul_f32 v[24:25], v[20:21], v[166:167]
	s_nop 0
	v_fma_f32 v22, v20, s76, -v24
	v_fmac_f32_e32 v22, 0xb102e308, v20
	v_pk_add_f32 v[20:21], v[24:25], v[22:23]
	v_mov_b32_e32 v28, v24
	v_sub_f32_e32 v23, v21, v23
	v_sub_f32_e32 v23, v25, v23
	v_add_f32_e32 v29, v26, v23
	v_pk_add_f32 v[24:25], v[20:21], v[24:25] neg_lo:[0,1] neg_hi:[0,1]
	v_pk_add_f32 v[30:31], v[20:21], v[28:29]
	v_mov_b32_e32 v23, v20
	v_mov_b32_e32 v25, v31
	v_pk_add_f32 v[32:33], v[22:23], v[24:25] neg_lo:[0,1] neg_hi:[0,1]
	v_pk_add_f32 v[22:23], v[22:23], v[24:25]
	v_mov_b32_e32 v28, v29
	v_pk_add_f32 v[24:25], v[22:23], v[20:21] op_sel:[1,0] op_sel_hi:[0,1] neg_lo:[0,1] neg_hi:[0,1]
	v_pk_add_f32 v[34:35], v[30:31], v[24:25] op_sel_hi:[1,0] neg_lo:[0,1] neg_hi:[0,1]
	v_mov_b32_e32 v30, v31
	v_mov_b32_e32 v31, v23
	v_pk_mov_b32 v[24:25], v[20:21], v[24:25] op_sel:[1,0]
	v_mov_b32_e32 v29, v20
	v_pk_add_f32 v[24:25], v[30:31], v[24:25] neg_lo:[0,1] neg_hi:[0,1]
	v_mov_b32_e32 v34, v32
	v_pk_add_f32 v[20:21], v[28:29], v[24:25] neg_lo:[0,1] neg_hi:[0,1]
	v_mov_b32_e32 v33, v23
	v_pk_add_f32 v[24:25], v[34:35], v[20:21]
	s_nop 0
	v_pk_add_f32 v[28:29], v[24:25], v[24:25] op_sel:[0,1] op_sel_hi:[1,0]
	s_nop 0
	v_pk_add_f32 v[22:23], v[22:23], v[28:29] op_sel:[1,0] op_sel_hi:[0,1]
	v_mov_b32_e32 v25, v22
	v_pk_add_f32 v[30:31], v[24:25], v[32:33] neg_lo:[0,1] neg_hi:[0,1]
	v_mov_b32_e32 v21, v28
	v_sub_f32_e32 v23, v24, v30
	v_pk_add_f32 v[20:21], v[20:21], v[30:31] neg_lo:[0,1] neg_hi:[0,1]
	v_sub_f32_e32 v23, v32, v23
	v_add_f32_e32 v20, v20, v23
	v_add_f32_e32 v20, v20, v21
	v_add_f32_e32 v20, v22, v20
	v_cndmask_b32_e64 v20, v222, v20, s[4:5]
; __device__ __forceinline__ void phase_small(const Params& P, int l) {
;     ...
;         for (int i = 0; i < 32; ++i) { const int s = lane * 32 + i; const float xx = misc[(size_t)(b * 2048 + s) * 128 + 64 + h] + bias;
;             const float ls = -(fmaxf(-xx, 0.f) + log1pf(expf(-fabsf(xx)))); run += ls; loc[i] = run; }
	v_cmp_lt_f32_e64 s[4:5], |v11|, s77
	s_nop 1
	v_cndmask_b32_e64 v11, v20, v11, s[4:5]
	v_or_b32_e32 v20, 2, v10
	v_ashrrev_i32_e32 v21, 31, v20
	v_lshlrev_b64 v[20:21], 9, v[20:21]
	v_lshl_add_u64 v[20:21], v[6:7], 0, v[20:21]
	v_add_f32_e32 v19, v19, v11
	v_add_f32_e32 v11, v27, v98
	v_mul_f32_e64 v20, |v11|, s33
	v_fma_f32 v21, |v11|, s33, -v20
	v_rndne_f32_e32 v22, v20
	v_fma_f32 v21, |v11|, s71, v21
	v_sub_f32_e32 v20, v20, v22
	v_add_f32_e32 v20, v20, v21
	v_exp_f32_e32 v20, v20
	v_cvt_i32_f32_e32 v21, v22
	v_cmp_ngt_f32_e64 s[4:5], |v11|, s72
	v_max_f32_e64 v26, -v11, 0
	v_ldexp_f32 v20, v20, v21
	v_cndmask_b32_e64 v20, 0, v20, s[4:5]
	v_cmp_nlt_f32_e64 s[4:5], |v11|, s73
	s_nop 1
	v_cndmask_b32_e64 v11, v222, v20, s[4:5]
	v_add_f32_e32 v22, 1.0, v11
	v_add_f32_e32 v20, -1.0, v22
	v_sub_f32_e32 v21, v20, v22
	v_add_f32_e32 v21, 1.0, v21
	v_sub_f32_e32 v20, v11, v20
	v_add_f32_e32 v23, v20, v21
	v_frexp_mant_f32_e32 v20, v22
	v_cmp_gt_f32_e64 s[4:5], s75, v20
	v_cvt_f64_f32_e32 v[20:21], v22
	v_frexp_exp_i32_f64_e32 v20, v[20:21]
	v_subbrev_co_u32_e64 v30, s[4:5], 0, v20, s[4:5]
	v_sub_u32_e32 v20, 0, v30
	v_ldexp_f32 v21, v22, v20
	v_add_f32_e32 v22, -1.0, v21
	v_add_f32_e32 v24, 1.0, v21
	v_ldexp_f32 v20, v23, v20
	v_add_f32_e32 v23, 1.0, v22
	v_add_f32_e32 v25, -1.0, v24
	v_sub_f32_e32 v23, v21, v23
	v_sub_f32_e32 v21, v21, v25
	v_add_f32_e32 v23, v20, v23
	v_add_f32_e32 v20, v20, v21
	v_add_f32_e32 v31, v24, v20
	v_rcp_f32_e32 v33, v31
	v_sub_f32_e32 v21, v24, v31
	v_add_f32_e32 v32, v20, v21
	v_add_f32_e32 v21, v22, v23
	v_mul_f32_e32 v35, v21, v33
	v_sub_f32_e32 v20, v22, v21
	v_mul_f32_e32 v22, v31, v35
	v_fma_f32 v24, v35, v31, -v22
	v_fmac_f32_e32 v24, v35, v32
	v_add_f32_e32 v34, v23, v20
	v_add_f32_e32 v20, v22, v24
	v_sub_f32_e32 v23, v21, v20
	v_pk_add_f32 v[28:29], v[20:21], v[22:23] neg_lo:[0,1] neg_hi:[0,1]
	v_mov_b32_e32 v25, v20
	v_pk_add_f32 v[20:21], v[28:29], v[24:25] neg_lo:[0,1] neg_hi:[0,1]
	v_cmp_neq_f32_e64 s[4:5], s74, v11
	v_add_f32_e32 v21, v34, v21
	v_add_f32_e32 v20, v20, v21
	v_add_f32_e32 v21, v23, v20
	v_mul_f32_e32 v34, v33, v21
	v_mul_f32_e32 v22, v31, v34
	v_fma_f32 v24, v34, v31, -v22
	v_fmac_f32_e32 v24, v34, v32
	v_sub_f32_e32 v23, v23, v21
	v_add_f32_e32 v31, v20, v23
	v_add_f32_e32 v20, v22, v24
	v_sub_f32_e32 v23, v21, v20
	v_pk_add_f32 v[28:29], v[20:21], v[22:23] neg_lo:[0,1] neg_hi:[0,1]
	v_mov_b32_e32 v25, v20
	v_pk_add_f32 v[20:21], v[28:29], v[24:25] neg_lo:[0,1] neg_hi:[0,1]
	s_nop 0
	v_add_f32_e32 v21, v31, v21
	v_add_f32_e32 v20, v20, v21
	v_add_f32_e32 v21, v35, v34
	v_add_f32_e32 v20, v23, v20
	v_sub_f32_e32 v22, v21, v35
	v_mul_f32_e32 v20, v33, v20
	v_sub_f32_e32 v22, v34, v22
	v_add_f32_e32 v22, v22, v20
	v_add_f32_e32 v24, v21, v22
	v_mul_f32_e32 v25, v24, v24
	v_fmamk_f32 v20, v25, 0x3e9b6dac, v219
	v_fmaak_f32 v167, v25, v20, 0x3f2aaada
	v_cvt_f32_i32_e32 v20, v30
	v_sub_f32_e32 v21, v24, v21
	v_sub_f32_e32 v21, v22, v21
	v_ldexp_f32 v28, v21, 1
	v_mul_f32_e32 v21, v24, v25
	v_ldexp_f32 v23, v24, 1
	v_pk_mul_f32 v[24:25], v[20:21], v[166:167]
	s_nop 0
	v_fma_f32 v22, v20, s76, -v24
	v_fmac_f32_e32 v22, 0xb102e308, v20
	v_pk_add_f32 v[20:21], v[24:25], v[22:23]
	s_nop 0
	v_sub_f32_e32 v23, v21, v23
	v_sub_f32_e32 v23, v25, v23
	v_add_f32_e32 v29, v28, v23
	v_mov_b32_e32 v28, v24
	v_pk_add_f32 v[24:25], v[20:21], v[24:25] neg_lo:[0,1] neg_hi:[0,1]
	v_pk_add_f32 v[30:31], v[20:21], v[28:29]
	v_mov_b32_e32 v23, v20
	v_mov_b32_e32 v25, v31
	v_pk_add_f32 v[32:33], v[22:23], v[24:25] neg_lo:[0,1] neg_hi:[0,1]
	v_pk_add_f32 v[22:23], v[22:23], v[24:25]
	v_mov_b32_e32 v28, v29
	v_pk_add_f32 v[24:25], v[22:23], v[20:21] op_sel:[1,0] op_sel_hi:[0,1] neg_lo:[0,1] neg_hi:[0,1]
	v_pk_add_f32 v[34:35], v[30:31], v[24:25] op_sel_hi:[1,0] neg_lo:[0,1] neg_hi:[0,1]
	v_mov_b32_e32 v30, v31
	v_mov_b32_e32 v31, v23
	v_pk_mov_b32 v[24:25], v[20:21], v[24:25] op_sel:[1,0]
	v_mov_b32_e32 v29, v20
	v_pk_add_f32 v[24:25], v[30:31], v[24:25] neg_lo:[0,1] neg_hi:[0,1]
	v_mov_b32_e32 v34, v32
	v_pk_add_f32 v[20:21], v[28:29], v[24:25] neg_lo:[0,1] neg_hi:[0,1]
	v_mov_b32_e32 v33, v23
	v_pk_add_f32 v[24:25], v[34:35], v[20:21]
	s_nop 0
	v_pk_add_f32 v[28:29], v[24:25], v[24:25] op_sel:[0,1] op_sel_hi:[1,0]
	s_nop 0
	v_pk_add_f32 v[22:23], v[22:23], v[28:29] op_sel:[1,0] op_sel_hi:[0,1]
	v_mov_b32_e32 v25, v22
	v_pk_add_f32 v[30:31], v[24:25], v[32:33] neg_lo:[0,1] neg_hi:[0,1]
	v_mov_b32_e32 v21, v28
	v_sub_f32_e32 v23, v24, v30
	v_pk_add_f32 v[20:21], v[20:21], v[30:31] neg_lo:[0,1] neg_hi:[0,1]
	v_sub_f32_e32 v23, v32, v23
	v_add_f32_e32 v20, v20, v23
	v_add_f32_e32 v20, v20, v21
	v_add_f32_e32 v20, v22, v20
	v_or_b32_e32 v22, 3, v10
	v_ashrrev_i32_e32 v23, 31, v22
	v_cndmask_b32_e64 v20, v222, v20, s[4:5]
	v_cmp_lt_f32_e64 s[4:5], |v11|, s77
	v_lshlrev_b64 v[22:23], 9, v[22:23]
	v_lshl_add_u64 v[22:23], v[6:7], 0, v[22:23]
	v_cndmask_b32_e64 v11, v20, v11, s[4:5]
	v_add_f32_e32 v20, v26, v11
	v_add_f32_e32 v11, v27, v99
	v_mul_f32_e64 v22, |v11|, s33
	v_fma_f32 v23, |v11|, s33, -v22
	v_rndne_f32_e32 v24, v22
	v_fma_f32 v23, |v11|, s71, v23
	v_sub_f32_e32 v22, v22, v24
	v_add_f32_e32 v22, v22, v23
	v_exp_f32_e32 v22, v22
	v_cvt_i32_f32_e32 v23, v24
	v_cmp_ngt_f32_e64 s[4:5], |v11|, s72
	v_max_f32_e64 v21, -v11, 0
	v_ldexp_f32 v22, v22, v23
	v_cndmask_b32_e64 v22, 0, v22, s[4:5]
	v_cmp_nlt_f32_e64 s[4:5], |v11|, s73
	s_nop 1
	v_cndmask_b32_e64 v11, v222, v22, s[4:5]
	v_add_f32_e32 v24, 1.0, v11
	v_add_f32_e32 v22, -1.0, v24
	v_sub_f32_e32 v23, v22, v24
	v_add_f32_e32 v23, 1.0, v23
	v_sub_f32_e32 v22, v11, v22
	v_add_f32_e32 v25, v22, v23
	v_frexp_mant_f32_e32 v22, v24
	v_cmp_gt_f32_e64 s[4:5], s75, v22
; __device__ __forceinline__ void phase_small(const Params& P, int l) {
;     ...
;         for (int i = 0; i < 32; ++i) { const int s = lane * 32 + i; const float xx = misc[(size_t)(b * 2048 + s) * 128 + 64 + h] + bias;
;             const float ls = -(fmaxf(-xx, 0.f) + log1pf(expf(-fabsf(xx)))); run += ls; loc[i] = run; }
	v_cvt_f64_f32_e32 v[22:23], v24
	v_frexp_exp_i32_f64_e32 v22, v[22:23]
	v_subbrev_co_u32_e64 v26, s[4:5], 0, v22, s[4:5]
	v_sub_u32_e32 v22, 0, v26
	v_ldexp_f32 v23, v24, v22
	v_add_f32_e32 v24, -1.0, v23
	v_add_f32_e32 v28, 1.0, v23
	v_ldexp_f32 v22, v25, v22
	v_add_f32_e32 v25, 1.0, v24
	v_add_f32_e32 v29, -1.0, v28
	v_sub_f32_e32 v25, v23, v25
	v_sub_f32_e32 v23, v23, v29
	v_add_f32_e32 v25, v22, v25
	v_add_f32_e32 v22, v22, v23
	v_add_f32_e32 v32, v28, v22
	v_rcp_f32_e32 v34, v32
	v_sub_f32_e32 v23, v28, v32
	v_add_f32_e32 v33, v22, v23
	v_add_f32_e32 v23, v24, v25
	v_mul_f32_e32 v36, v23, v34
	v_sub_f32_e32 v22, v24, v23
	v_mul_f32_e32 v24, v32, v36
	v_fma_f32 v28, v36, v32, -v24
	v_fmac_f32_e32 v28, v36, v33
	v_add_f32_e32 v35, v25, v22
	v_add_f32_e32 v22, v24, v28
	v_sub_f32_e32 v25, v23, v22
	v_pk_add_f32 v[30:31], v[22:23], v[24:25] neg_lo:[0,1] neg_hi:[0,1]
	v_mov_b32_e32 v29, v22
	v_pk_add_f32 v[22:23], v[30:31], v[28:29] neg_lo:[0,1] neg_hi:[0,1]
	v_cmp_neq_f32_e64 s[4:5], s74, v11
	v_add_f32_e32 v23, v35, v23
	v_add_f32_e32 v22, v22, v23
	v_add_f32_e32 v23, v25, v22
	v_mul_f32_e32 v35, v34, v23
	v_mul_f32_e32 v24, v32, v35
	v_fma_f32 v28, v35, v32, -v24
	v_fmac_f32_e32 v28, v35, v33
	v_sub_f32_e32 v25, v25, v23
	v_add_f32_e32 v32, v22, v25
	v_add_f32_e32 v22, v24, v28
	v_sub_f32_e32 v25, v23, v22
	v_pk_add_f32 v[30:31], v[22:23], v[24:25] neg_lo:[0,1] neg_hi:[0,1]
	v_mov_b32_e32 v29, v22
	v_pk_add_f32 v[22:23], v[30:31], v[28:29] neg_lo:[0,1] neg_hi:[0,1]
	s_nop 0
	v_add_f32_e32 v23, v32, v23
	v_add_f32_e32 v22, v22, v23
	v_add_f32_e32 v23, v36, v35
	v_add_f32_e32 v22, v25, v22
	v_sub_f32_e32 v24, v23, v36
	v_mul_f32_e32 v22, v34, v22
	v_sub_f32_e32 v24, v35, v24
	v_add_f32_e32 v24, v24, v22
	v_add_f32_e32 v28, v23, v24
	v_mul_f32_e32 v29, v28, v28
	v_fmamk_f32 v22, v29, 0x3e9b6dac, v219
	v_fmaak_f32 v167, v29, v22, 0x3f2aaada
	v_cvt_f32_i32_e32 v22, v26
	v_sub_f32_e32 v23, v28, v23
	v_sub_f32_e32 v23, v24, v23
	v_ldexp_f32 v26, v23, 1
	v_mul_f32_e32 v23, v28, v29
	v_ldexp_f32 v25, v28, 1
	v_pk_mul_f32 v[28:29], v[22:23], v[166:167]
	s_nop 0
	v_fma_f32 v24, v22, s76, -v28
	v_fmac_f32_e32 v24, 0xb102e308, v22
	v_pk_add_f32 v[22:23], v[28:29], v[24:25]
	v_mov_b32_e32 v30, v28
	v_sub_f32_e32 v25, v23, v25
	v_sub_f32_e32 v25, v29, v25
	v_add_f32_e32 v31, v26, v25
	v_pk_add_f32 v[28:29], v[22:23], v[28:29] neg_lo:[0,1] neg_hi:[0,1]
	v_pk_add_f32 v[32:33], v[22:23], v[30:31]
	v_mov_b32_e32 v25, v22
	v_mov_b32_e32 v29, v33
	v_pk_add_f32 v[34:35], v[24:25], v[28:29] neg_lo:[0,1] neg_hi:[0,1]
	v_pk_add_f32 v[24:25], v[24:25], v[28:29]
	v_mov_b32_e32 v30, v31
	v_pk_add_f32 v[28:29], v[24:25], v[22:23] op_sel:[1,0] op_sel_hi:[0,1] neg_lo:[0,1] neg_hi:[0,1]
	v_pk_add_f32 v[36:37], v[32:33], v[28:29] op_sel_hi:[1,0] neg_lo:[0,1] neg_hi:[0,1]
	v_mov_b32_e32 v32, v33
	v_mov_b32_e32 v33, v25
	v_pk_mov_b32 v[28:29], v[22:23], v[28:29] op_sel:[1,0]
	v_mov_b32_e32 v31, v22
	v_pk_add_f32 v[28:29], v[32:33], v[28:29] neg_lo:[0,1] neg_hi:[0,1]
	v_mov_b32_e32 v36, v34
	v_pk_add_f32 v[22:23], v[30:31], v[28:29] neg_lo:[0,1] neg_hi:[0,1]
	v_mov_b32_e32 v35, v25
	v_pk_add_f32 v[28:29], v[36:37], v[22:23]
	s_nop 0
	v_pk_add_f32 v[30:31], v[28:29], v[28:29] op_sel:[0,1] op_sel_hi:[1,0]
	s_nop 0
	v_pk_add_f32 v[24:25], v[24:25], v[30:31] op_sel:[1,0] op_sel_hi:[0,1]
	v_mov_b32_e32 v29, v24
	v_pk_add_f32 v[32:33], v[28:29], v[34:35] neg_lo:[0,1] neg_hi:[0,1]
	v_mov_b32_e32 v23, v30
	v_sub_f32_e32 v25, v28, v32
	v_pk_add_f32 v[22:23], v[22:23], v[32:33] neg_lo:[0,1] neg_hi:[0,1]
	v_sub_f32_e32 v25, v34, v25
	v_add_f32_e32 v22, v22, v25
	v_add_f32_e32 v22, v22, v23
	v_add_f32_e32 v22, v24, v22
	v_cndmask_b32_e64 v22, v222, v22, s[4:5]
	v_cmp_lt_f32_e64 s[4:5], |v11|, s77
	s_nop 1
	v_cndmask_b32_e64 v11, v22, v11, s[4:5]
	v_or_b32_e32 v22, 4, v10
	v_ashrrev_i32_e32 v23, 31, v22
	v_lshlrev_b64 v[22:23], 9, v[22:23]
	v_lshl_add_u64 v[22:23], v[6:7], 0, v[22:23]
	v_add_f32_e32 v21, v21, v11
	v_add_f32_e32 v11, v27, v100
	v_mul_f32_e64 v22, |v11|, s33
	v_fma_f32 v23, |v11|, s33, -v22
	v_rndne_f32_e32 v24, v22
	v_fma_f32 v23, |v11|, s71, v23
	v_sub_f32_e32 v22, v22, v24
	v_add_f32_e32 v22, v22, v23
	v_exp_f32_e32 v22, v22
	v_cvt_i32_f32_e32 v23, v24
	v_cmp_ngt_f32_e64 s[4:5], |v11|, s72
	v_max_f32_e64 v26, -v11, 0
	v_ldexp_f32 v22, v22, v23
	v_cndmask_b32_e64 v22, 0, v22, s[4:5]
	v_cmp_nlt_f32_e64 s[4:5], |v11|, s73
	s_nop 1
	v_cndmask_b32_e64 v11, v222, v22, s[4:5]
	v_add_f32_e32 v24, 1.0, v11
	v_add_f32_e32 v22, -1.0, v24
	v_sub_f32_e32 v23, v22, v24
	v_add_f32_e32 v23, 1.0, v23
	v_sub_f32_e32 v22, v11, v22
	v_add_f32_e32 v25, v22, v23
	v_frexp_mant_f32_e32 v22, v24
	v_cmp_gt_f32_e64 s[4:5], s75, v22
	v_cvt_f64_f32_e32 v[22:23], v24
	v_frexp_exp_i32_f64_e32 v22, v[22:23]
	v_subbrev_co_u32_e64 v32, s[4:5], 0, v22, s[4:5]
	v_sub_u32_e32 v22, 0, v32
	v_ldexp_f32 v23, v24, v22
	v_add_f32_e32 v24, -1.0, v23
	v_add_f32_e32 v28, 1.0, v23
	v_ldexp_f32 v22, v25, v22
	v_add_f32_e32 v25, 1.0, v24
	v_add_f32_e32 v29, -1.0, v28
	v_sub_f32_e32 v25, v23, v25
	v_sub_f32_e32 v23, v23, v29
	v_add_f32_e32 v25, v22, v25
	v_add_f32_e32 v22, v22, v23
	v_add_f32_e32 v33, v28, v22
	v_rcp_f32_e32 v35, v33
	v_sub_f32_e32 v23, v28, v33
	v_add_f32_e32 v34, v22, v23
	v_add_f32_e32 v23, v24, v25
	v_mul_f32_e32 v37, v23, v35
	v_sub_f32_e32 v22, v24, v23
	v_mul_f32_e32 v24, v33, v37
	v_fma_f32 v28, v37, v33, -v24
	v_fmac_f32_e32 v28, v37, v34
	v_add_f32_e32 v36, v25, v22
	v_add_f32_e32 v22, v24, v28
	v_sub_f32_e32 v25, v23, v22
	v_pk_add_f32 v[30:31], v[22:23], v[24:25] neg_lo:[0,1] neg_hi:[0,1]
	v_mov_b32_e32 v29, v22
	v_pk_add_f32 v[22:23], v[30:31], v[28:29] neg_lo:[0,1] neg_hi:[0,1]
; __device__ __forceinline__ void phase_small(const Params& P, int l) {
;     ...
;         for (int i = 0; i < 32; ++i) { const int s = lane * 32 + i; const float xx = misc[(size_t)(b * 2048 + s) * 128 + 64 + h] + bias;
;             const float ls = -(fmaxf(-xx, 0.f) + log1pf(expf(-fabsf(xx)))); run += ls; loc[i] = run; }
	v_cmp_neq_f32_e64 s[4:5], s74, v11
	v_add_f32_e32 v23, v36, v23
	v_add_f32_e32 v22, v22, v23
	v_add_f32_e32 v23, v25, v22
	v_mul_f32_e32 v36, v35, v23
	v_mul_f32_e32 v24, v33, v36
	v_fma_f32 v28, v36, v33, -v24
	v_fmac_f32_e32 v28, v36, v34
	v_sub_f32_e32 v25, v25, v23
	v_add_f32_e32 v33, v22, v25
	v_add_f32_e32 v22, v24, v28
	v_sub_f32_e32 v25, v23, v22
	v_pk_add_f32 v[30:31], v[22:23], v[24:25] neg_lo:[0,1] neg_hi:[0,1]
	v_mov_b32_e32 v29, v22
	v_pk_add_f32 v[22:23], v[30:31], v[28:29] neg_lo:[0,1] neg_hi:[0,1]
	s_nop 0
	v_add_f32_e32 v23, v33, v23
	v_add_f32_e32 v22, v22, v23
	v_add_f32_e32 v23, v37, v36
	v_add_f32_e32 v22, v25, v22
	v_sub_f32_e32 v24, v23, v37
	v_mul_f32_e32 v22, v35, v22
	v_sub_f32_e32 v24, v36, v24
	v_add_f32_e32 v24, v24, v22
	v_add_f32_e32 v28, v23, v24
	v_mul_f32_e32 v29, v28, v28
	v_fmamk_f32 v22, v29, 0x3e9b6dac, v219
	v_fmaak_f32 v167, v29, v22, 0x3f2aaada
	v_cvt_f32_i32_e32 v22, v32
	v_sub_f32_e32 v23, v28, v23
	v_sub_f32_e32 v23, v24, v23
	v_ldexp_f32 v30, v23, 1
	v_mul_f32_e32 v23, v28, v29
	v_ldexp_f32 v25, v28, 1
	v_pk_mul_f32 v[28:29], v[22:23], v[166:167]
	s_nop 0
	v_fma_f32 v24, v22, s76, -v28
	v_fmac_f32_e32 v24, 0xb102e308, v22
	v_pk_add_f32 v[22:23], v[28:29], v[24:25]
	s_nop 0
	v_sub_f32_e32 v25, v23, v25
	v_sub_f32_e32 v25, v29, v25
	v_add_f32_e32 v31, v30, v25
	v_mov_b32_e32 v30, v28
	v_pk_add_f32 v[28:29], v[22:23], v[28:29] neg_lo:[0,1] neg_hi:[0,1]
	v_pk_add_f32 v[32:33], v[22:23], v[30:31]
	v_mov_b32_e32 v25, v22
	v_mov_b32_e32 v29, v33
	v_pk_add_f32 v[34:35], v[24:25], v[28:29] neg_lo:[0,1] neg_hi:[0,1]
	v_pk_add_f32 v[24:25], v[24:25], v[28:29]
	v_mov_b32_e32 v30, v31
	v_pk_add_f32 v[28:29], v[24:25], v[22:23] op_sel:[1,0] op_sel_hi:[0,1] neg_lo:[0,1] neg_hi:[0,1]
	v_pk_add_f32 v[36:37], v[32:33], v[28:29] op_sel_hi:[1,0] neg_lo:[0,1] neg_hi:[0,1]
	v_mov_b32_e32 v32, v33
	v_mov_b32_e32 v33, v25
	v_pk_mov_b32 v[28:29], v[22:23], v[28:29] op_sel:[1,0]
	v_mov_b32_e32 v31, v22
	v_pk_add_f32 v[28:29], v[32:33], v[28:29] neg_lo:[0,1] neg_hi:[0,1]
	v_mov_b32_e32 v36, v34
	v_pk_add_f32 v[22:23], v[30:31], v[28:29] neg_lo:[0,1] neg_hi:[0,1]
	v_mov_b32_e32 v35, v25
	v_pk_add_f32 v[28:29], v[36:37], v[22:23]
	s_nop 0
	v_pk_add_f32 v[30:31], v[28:29], v[28:29] op_sel:[0,1] op_sel_hi:[1,0]
	s_nop 0
	v_pk_add_f32 v[24:25], v[24:25], v[30:31] op_sel:[1,0] op_sel_hi:[0,1]
	v_mov_b32_e32 v29, v24
	v_pk_add_f32 v[32:33], v[28:29], v[34:35] neg_lo:[0,1] neg_hi:[0,1]
	v_mov_b32_e32 v23, v30
	v_sub_f32_e32 v25, v28, v32
	v_pk_add_f32 v[22:23], v[22:23], v[32:33] neg_lo:[0,1] neg_hi:[0,1]
	v_sub_f32_e32 v25, v34, v25
	v_add_f32_e32 v22, v22, v25
	v_add_f32_e32 v22, v22, v23
	v_add_f32_e32 v22, v24, v22
	v_or_b32_e32 v24, 5, v10
	v_ashrrev_i32_e32 v25, 31, v24
	v_cndmask_b32_e64 v22, v222, v22, s[4:5]
	v_cmp_lt_f32_e64 s[4:5], |v11|, s77
	v_lshlrev_b64 v[24:25], 9, v[24:25]
	v_lshl_add_u64 v[24:25], v[6:7], 0, v[24:25]
	v_cndmask_b32_e64 v11, v22, v11, s[4:5]
	v_add_f32_e32 v22, v26, v11
	v_add_f32_e32 v11, v27, v101
	v_mul_f32_e64 v24, |v11|, s33
	v_fma_f32 v25, |v11|, s33, -v24
	v_rndne_f32_e32 v26, v24
	v_fma_f32 v25, |v11|, s71, v25
	v_sub_f32_e32 v24, v24, v26
	v_add_f32_e32 v24, v24, v25
	v_exp_f32_e32 v24, v24
	v_cvt_i32_f32_e32 v25, v26
	v_cmp_ngt_f32_e64 s[4:5], |v11|, s72
	v_max_f32_e64 v23, -v11, 0
	v_ldexp_f32 v24, v24, v25
	v_cndmask_b32_e64 v24, 0, v24, s[4:5]
	v_cmp_nlt_f32_e64 s[4:5], |v11|, s73
	s_nop 1
	v_cndmask_b32_e64 v11, v222, v24, s[4:5]
	v_add_f32_e32 v26, 1.0, v11
	v_add_f32_e32 v24, -1.0, v26
	v_sub_f32_e32 v25, v24, v26
	v_add_f32_e32 v25, 1.0, v25
	v_sub_f32_e32 v24, v11, v24
	v_add_f32_e32 v28, v24, v25
	v_frexp_mant_f32_e32 v24, v26
	v_cmp_gt_f32_e64 s[4:5], s75, v24
	v_cvt_f64_f32_e32 v[24:25], v26
	v_frexp_exp_i32_f64_e32 v24, v[24:25]
	v_subbrev_co_u32_e64 v34, s[4:5], 0, v24, s[4:5]
	v_sub_u32_e32 v24, 0, v34
	v_ldexp_f32 v25, v26, v24
	v_add_f32_e32 v26, -1.0, v25
	v_add_f32_e32 v29, 1.0, v25
	v_ldexp_f32 v24, v28, v24
	v_add_f32_e32 v28, 1.0, v26
	v_add_f32_e32 v30, -1.0, v29
	v_sub_f32_e32 v28, v25, v28
	v_sub_f32_e32 v25, v25, v30
	v_add_f32_e32 v28, v24, v28
	v_add_f32_e32 v24, v24, v25
	v_add_f32_e32 v35, v29, v24
	v_rcp_f32_e32 v37, v35
	v_sub_f32_e32 v25, v29, v35
	v_add_f32_e32 v36, v24, v25
	v_add_f32_e32 v25, v26, v28
	v_sub_f32_e32 v24, v26, v25
	v_mul_f32_e32 v38, v25, v37
	v_add_f32_e32 v26, v28, v24
	v_mul_f32_e32 v28, v35, v38
	v_fma_f32 v30, v38, v35, -v28
	v_fmac_f32_e32 v30, v38, v36
	v_add_f32_e32 v24, v28, v30
	v_sub_f32_e32 v29, v25, v24
	v_pk_add_f32 v[32:33], v[24:25], v[28:29] neg_lo:[0,1] neg_hi:[0,1]
	v_mov_b32_e32 v31, v24
	v_pk_add_f32 v[24:25], v[32:33], v[30:31] neg_lo:[0,1] neg_hi:[0,1]
	v_cmp_neq_f32_e64 s[4:5], s74, v11
	v_add_f32_e32 v25, v26, v25
	v_add_f32_e32 v24, v24, v25
	v_add_f32_e32 v25, v29, v24
	v_mul_f32_e32 v26, v37, v25
	v_mul_f32_e32 v28, v35, v26
	v_fma_f32 v30, v26, v35, -v28
	v_fmac_f32_e32 v30, v26, v36
	v_sub_f32_e32 v29, v29, v25
	v_add_f32_e32 v35, v24, v29
	v_add_f32_e32 v24, v28, v30
	v_sub_f32_e32 v29, v25, v24
	v_pk_add_f32 v[32:33], v[24:25], v[28:29] neg_lo:[0,1] neg_hi:[0,1]
	v_mov_b32_e32 v31, v24
	v_pk_add_f32 v[24:25], v[32:33], v[30:31] neg_lo:[0,1] neg_hi:[0,1]
	s_nop 0
	v_add_f32_e32 v25, v35, v25
	v_add_f32_e32 v24, v24, v25
	v_add_f32_e32 v25, v38, v26
	v_add_f32_e32 v24, v29, v24
	v_sub_f32_e32 v28, v25, v38
	v_mul_f32_e32 v24, v37, v24
	v_sub_f32_e32 v26, v26, v28
	v_add_f32_e32 v26, v26, v24
	v_add_f32_e32 v28, v25, v26
	v_mul_f32_e32 v30, v28, v28
	v_fmamk_f32 v24, v30, 0x3e9b6dac, v219
	v_fmaak_f32 v167, v30, v24, 0x3f2aaada
	v_cvt_f32_i32_e32 v24, v34
	v_sub_f32_e32 v25, v28, v25
	v_sub_f32_e32 v25, v26, v25
; __device__ __forceinline__ void phase_small(const Params& P, int l) {
;     ...
;         for (int i = 0; i < 32; ++i) { const int s = lane * 32 + i; const float xx = misc[(size_t)(b * 2048 + s) * 128 + 64 + h] + bias;
;             const float ls = -(fmaxf(-xx, 0.f) + log1pf(expf(-fabsf(xx)))); run += ls; loc[i] = run; }
	v_ldexp_f32 v26, v25, 1
	v_mul_f32_e32 v25, v28, v30
	v_pk_mul_f32 v[30:31], v[24:25], v[166:167]
	v_ldexp_f32 v29, v28, 1
	v_fma_f32 v28, v24, s76, -v30
	v_fmac_f32_e32 v28, 0xb102e308, v24
	v_pk_add_f32 v[24:25], v[30:31], v[28:29]
	v_mov_b32_e32 v32, v30
	v_sub_f32_e32 v29, v25, v29
	v_sub_f32_e32 v29, v31, v29
	v_add_f32_e32 v33, v26, v29
	v_pk_add_f32 v[30:31], v[24:25], v[30:31] neg_lo:[0,1] neg_hi:[0,1]
	v_pk_add_f32 v[34:35], v[24:25], v[32:33]
	v_mov_b32_e32 v29, v24
	v_mov_b32_e32 v31, v35
	v_pk_add_f32 v[36:37], v[28:29], v[30:31] neg_lo:[0,1] neg_hi:[0,1]
	v_pk_add_f32 v[28:29], v[28:29], v[30:31]
	v_mov_b32_e32 v32, v33
	v_pk_add_f32 v[30:31], v[28:29], v[24:25] op_sel:[1,0] op_sel_hi:[0,1] neg_lo:[0,1] neg_hi:[0,1]
	v_pk_add_f32 v[38:39], v[34:35], v[30:31] op_sel_hi:[1,0] neg_lo:[0,1] neg_hi:[0,1]
	v_mov_b32_e32 v34, v35
	v_mov_b32_e32 v35, v29
	v_pk_mov_b32 v[30:31], v[24:25], v[30:31] op_sel:[1,0]
	v_mov_b32_e32 v33, v24
	v_pk_add_f32 v[30:31], v[34:35], v[30:31] neg_lo:[0,1] neg_hi:[0,1]
	v_mov_b32_e32 v38, v36
	v_pk_add_f32 v[24:25], v[32:33], v[30:31] neg_lo:[0,1] neg_hi:[0,1]
	v_mov_b32_e32 v37, v29
	v_pk_add_f32 v[30:31], v[38:39], v[24:25]
	s_nop 0
	v_pk_add_f32 v[32:33], v[30:31], v[30:31] op_sel:[0,1] op_sel_hi:[1,0]
	s_nop 0
	v_pk_add_f32 v[28:29], v[28:29], v[32:33] op_sel:[1,0] op_sel_hi:[0,1]
	v_mov_b32_e32 v31, v28
	v_pk_add_f32 v[34:35], v[30:31], v[36:37] neg_lo:[0,1] neg_hi:[0,1]
	v_mov_b32_e32 v25, v32
	v_sub_f32_e32 v26, v30, v34
	v_pk_add_f32 v[24:25], v[24:25], v[34:35] neg_lo:[0,1] neg_hi:[0,1]
	v_sub_f32_e32 v26, v36, v26
	v_add_f32_e32 v24, v24, v26
	v_add_f32_e32 v24, v24, v25
	v_add_f32_e32 v24, v28, v24
	v_cndmask_b32_e64 v24, v222, v24, s[4:5]
	v_cmp_lt_f32_e64 s[4:5], |v11|, s77
	s_nop 1
	v_cndmask_b32_e64 v11, v24, v11, s[4:5]
	v_or_b32_e32 v24, 6, v10
	v_ashrrev_i32_e32 v25, 31, v24
	v_lshlrev_b64 v[24:25], 9, v[24:25]
	v_lshl_add_u64 v[24:25], v[6:7], 0, v[24:25]
	v_add_f32_e32 v23, v23, v11
	v_add_f32_e32 v11, v27, v102
	v_mul_f32_e64 v24, |v11|, s33
	v_fma_f32 v25, |v11|, s33, -v24
	v_rndne_f32_e32 v28, v24
	v_fma_f32 v25, |v11|, s71, v25
	v_sub_f32_e32 v24, v24, v28
	v_add_f32_e32 v24, v24, v25
	v_exp_f32_e32 v24, v24
	v_cvt_i32_f32_e32 v25, v28
	v_cmp_ngt_f32_e64 s[4:5], |v11|, s72
	v_max_f32_e64 v26, -v11, 0
	v_ldexp_f32 v24, v24, v25
	v_cndmask_b32_e64 v24, 0, v24, s[4:5]
	v_cmp_nlt_f32_e64 s[4:5], |v11|, s73
	s_nop 1
	v_cndmask_b32_e64 v11, v222, v24, s[4:5]
	v_add_f32_e32 v28, 1.0, v11
	v_add_f32_e32 v24, -1.0, v28
	v_sub_f32_e32 v25, v24, v28
	v_add_f32_e32 v25, 1.0, v25
	v_sub_f32_e32 v24, v11, v24
	v_add_f32_e32 v29, v24, v25
	v_frexp_mant_f32_e32 v24, v28
	v_cmp_gt_f32_e64 s[4:5], s75, v24
	v_cvt_f64_f32_e32 v[24:25], v28
	v_frexp_exp_i32_f64_e32 v24, v[24:25]
	v_subbrev_co_u32_e64 v34, s[4:5], 0, v24, s[4:5]
	v_sub_u32_e32 v24, 0, v34
	v_ldexp_f32 v25, v28, v24
	v_add_f32_e32 v28, -1.0, v25
	v_add_f32_e32 v30, 1.0, v25
	v_ldexp_f32 v24, v29, v24
	v_add_f32_e32 v29, 1.0, v28
	v_add_f32_e32 v31, -1.0, v30
	v_sub_f32_e32 v29, v25, v29
	v_sub_f32_e32 v25, v25, v31
	v_add_f32_e32 v29, v24, v29
	v_add_f32_e32 v24, v24, v25
	v_add_f32_e32 v35, v30, v24
	v_rcp_f32_e32 v37, v35
	v_sub_f32_e32 v25, v30, v35
	v_add_f32_e32 v36, v24, v25
	v_add_f32_e32 v25, v28, v29
	v_mul_f32_e32 v39, v25, v37
	v_sub_f32_e32 v24, v28, v25
	v_mul_f32_e32 v28, v35, v39
	v_fma_f32 v30, v39, v35, -v28
	v_fmac_f32_e32 v30, v39, v36
	v_add_f32_e32 v38, v29, v24
	v_add_f32_e32 v24, v28, v30
	v_sub_f32_e32 v29, v25, v24
	v_pk_add_f32 v[32:33], v[24:25], v[28:29] neg_lo:[0,1] neg_hi:[0,1]
	v_mov_b32_e32 v31, v24
	v_pk_add_f32 v[24:25], v[32:33], v[30:31] neg_lo:[0,1] neg_hi:[0,1]
	v_cmp_neq_f32_e64 s[4:5], s74, v11
	v_add_f32_e32 v25, v38, v25
	v_add_f32_e32 v24, v24, v25
	v_add_f32_e32 v25, v29, v24
	v_mul_f32_e32 v38, v37, v25
	v_mul_f32_e32 v28, v35, v38
	v_fma_f32 v30, v38, v35, -v28
	v_fmac_f32_e32 v30, v38, v36
	v_sub_f32_e32 v29, v29, v25
	v_add_f32_e32 v35, v24, v29
	v_add_f32_e32 v24, v28, v30
	v_sub_f32_e32 v29, v25, v24
	v_pk_add_f32 v[32:33], v[24:25], v[28:29] neg_lo:[0,1] neg_hi:[0,1]
	v_mov_b32_e32 v31, v24
	v_pk_add_f32 v[24:25], v[32:33], v[30:31] neg_lo:[0,1] neg_hi:[0,1]
	s_nop 0
	v_add_f32_e32 v25, v35, v25
	v_add_f32_e32 v24, v24, v25
	v_add_f32_e32 v25, v39, v38
	v_add_f32_e32 v24, v29, v24
	v_sub_f32_e32 v28, v25, v39
	v_mul_f32_e32 v24, v37, v24
	v_sub_f32_e32 v28, v38, v28
	v_add_f32_e32 v28, v28, v24
	v_add_f32_e32 v30, v25, v28
	v_mul_f32_e32 v31, v30, v30
	v_fmamk_f32 v24, v31, 0x3e9b6dac, v219
	v_fmaak_f32 v167, v31, v24, 0x3f2aaada
	v_cvt_f32_i32_e32 v24, v34
	v_sub_f32_e32 v25, v30, v25
	v_sub_f32_e32 v25, v28, v25
	v_ldexp_f32 v32, v25, 1
	v_mul_f32_e32 v25, v30, v31
	v_ldexp_f32 v29, v30, 1
	v_pk_mul_f32 v[30:31], v[24:25], v[166:167]
	s_nop 0
	v_fma_f32 v28, v24, s76, -v30
	v_fmac_f32_e32 v28, 0xb102e308, v24
	v_pk_add_f32 v[24:25], v[30:31], v[28:29]
	s_nop 0
	v_sub_f32_e32 v29, v25, v29
	v_sub_f32_e32 v29, v31, v29
	v_add_f32_e32 v33, v32, v29
	v_mov_b32_e32 v32, v30
	v_pk_add_f32 v[30:31], v[24:25], v[30:31] neg_lo:[0,1] neg_hi:[0,1]
	v_pk_add_f32 v[34:35], v[24:25], v[32:33]
	v_mov_b32_e32 v29, v24
	v_mov_b32_e32 v31, v35
	v_pk_add_f32 v[36:37], v[28:29], v[30:31] neg_lo:[0,1] neg_hi:[0,1]
	v_pk_add_f32 v[28:29], v[28:29], v[30:31]
	v_mov_b32_e32 v32, v33
	v_pk_add_f32 v[30:31], v[28:29], v[24:25] op_sel:[1,0] op_sel_hi:[0,1] neg_lo:[0,1] neg_hi:[0,1]
	v_pk_add_f32 v[38:39], v[34:35], v[30:31] op_sel_hi:[1,0] neg_lo:[0,1] neg_hi:[0,1]
	v_mov_b32_e32 v34, v35
	v_mov_b32_e32 v35, v29
	v_pk_mov_b32 v[30:31], v[24:25], v[30:31] op_sel:[1,0]
	v_mov_b32_e32 v33, v24
; __device__ __forceinline__ void phase_small(const Params& P, int l) {
;     ...
;         for (int i = 0; i < 32; ++i) { const int s = lane * 32 + i; const float xx = misc[(size_t)(b * 2048 + s) * 128 + 64 + h] + bias;
;             const float ls = -(fmaxf(-xx, 0.f) + log1pf(expf(-fabsf(xx)))); run += ls; loc[i] = run; }
	v_pk_add_f32 v[30:31], v[34:35], v[30:31] neg_lo:[0,1] neg_hi:[0,1]
	v_mov_b32_e32 v38, v36
	v_pk_add_f32 v[24:25], v[32:33], v[30:31] neg_lo:[0,1] neg_hi:[0,1]
	v_mov_b32_e32 v37, v29
	v_pk_add_f32 v[30:31], v[38:39], v[24:25]
	s_nop 0
	v_pk_add_f32 v[32:33], v[30:31], v[30:31] op_sel:[0,1] op_sel_hi:[1,0]
	s_nop 0
	v_pk_add_f32 v[28:29], v[28:29], v[32:33] op_sel:[1,0] op_sel_hi:[0,1]
	v_mov_b32_e32 v31, v28
	v_pk_add_f32 v[34:35], v[30:31], v[36:37] neg_lo:[0,1] neg_hi:[0,1]
	v_mov_b32_e32 v25, v32
	v_sub_f32_e32 v29, v30, v34
	v_pk_add_f32 v[24:25], v[24:25], v[34:35] neg_lo:[0,1] neg_hi:[0,1]
	v_sub_f32_e32 v29, v36, v29
	v_add_f32_e32 v24, v24, v29
	v_add_f32_e32 v24, v24, v25
	v_add_f32_e32 v24, v28, v24
	v_or_b32_e32 v28, 7, v10
	v_ashrrev_i32_e32 v29, 31, v28
	v_cndmask_b32_e64 v24, v222, v24, s[4:5]
	v_cmp_lt_f32_e64 s[4:5], |v11|, s77
	v_lshlrev_b64 v[28:29], 9, v[28:29]
	v_lshl_add_u64 v[28:29], v[6:7], 0, v[28:29]
	v_cndmask_b32_e64 v11, v24, v11, s[4:5]
	v_add_f32_e32 v24, v26, v11
	v_add_f32_e32 v11, v27, v103
	v_mul_f32_e64 v26, |v11|, s33
	v_fma_f32 v28, |v11|, s33, -v26
	v_rndne_f32_e32 v29, v26
	v_fma_f32 v28, |v11|, s71, v28
	v_sub_f32_e32 v26, v26, v29
	v_add_f32_e32 v26, v26, v28
	v_exp_f32_e32 v26, v26
	v_cvt_i32_f32_e32 v28, v29
	v_cmp_ngt_f32_e64 s[4:5], |v11|, s72
	v_max_f32_e64 v25, -v11, 0
	v_ldexp_f32 v26, v26, v28
	v_cndmask_b32_e64 v26, 0, v26, s[4:5]
	v_cmp_nlt_f32_e64 s[4:5], |v11|, s73
	s_nop 1
	v_cndmask_b32_e64 v11, v222, v26, s[4:5]
	v_add_f32_e32 v26, 1.0, v11
	v_add_f32_e32 v28, -1.0, v26
	v_sub_f32_e32 v29, v28, v26
	v_add_f32_e32 v29, 1.0, v29
	v_sub_f32_e32 v28, v11, v28
	v_add_f32_e32 v30, v28, v29
	v_frexp_mant_f32_e32 v28, v26
	v_cmp_gt_f32_e64 s[4:5], s75, v28
	v_cvt_f64_f32_e32 v[28:29], v26
	v_frexp_exp_i32_f64_e32 v28, v[28:29]
	v_subbrev_co_u32_e64 v36, s[4:5], 0, v28, s[4:5]
	v_sub_u32_e32 v28, 0, v36
	v_ldexp_f32 v26, v26, v28
	v_ldexp_f32 v28, v30, v28
	v_add_f32_e32 v30, -1.0, v26
	v_add_f32_e32 v29, 1.0, v30
	v_sub_f32_e32 v29, v26, v29
	v_add_f32_e32 v31, v28, v29
	v_add_f32_e32 v29, 1.0, v26
	v_add_f32_e32 v32, -1.0, v29
	v_sub_f32_e32 v26, v26, v32
	v_add_f32_e32 v26, v28, v26
	v_add_f32_e32 v37, v29, v26
	v_rcp_f32_e32 v38, v37
	v_sub_f32_e32 v28, v29, v37
	v_add_f32_e32 v29, v30, v31
	v_add_f32_e32 v26, v26, v28
	v_mul_f32_e32 v40, v29, v38
	v_sub_f32_e32 v28, v30, v29
	v_mul_f32_e32 v30, v37, v40
	v_fma_f32 v32, v40, v37, -v30
	v_fmac_f32_e32 v32, v40, v26
	v_add_f32_e32 v39, v31, v28
	v_add_f32_e32 v28, v30, v32
	v_sub_f32_e32 v31, v29, v28
	v_pk_add_f32 v[34:35], v[28:29], v[30:31] neg_lo:[0,1] neg_hi:[0,1]
	v_mov_b32_e32 v33, v28
	v_pk_add_f32 v[28:29], v[34:35], v[32:33] neg_lo:[0,1] neg_hi:[0,1]
	v_cmp_neq_f32_e64 s[4:5], s74, v11
	v_add_f32_e32 v29, v39, v29
	v_add_f32_e32 v28, v28, v29
	v_add_f32_e32 v29, v31, v28
	v_mul_f32_e32 v39, v38, v29
	v_mul_f32_e32 v30, v37, v39
	v_fma_f32 v32, v39, v37, -v30
	v_fmac_f32_e32 v32, v39, v26
	v_sub_f32_e32 v26, v31, v29
	v_add_f32_e32 v26, v28, v26
	v_add_f32_e32 v28, v30, v32
	v_sub_f32_e32 v31, v29, v28
	v_pk_add_f32 v[34:35], v[28:29], v[30:31] neg_lo:[0,1] neg_hi:[0,1]
	v_mov_b32_e32 v33, v28
	v_pk_add_f32 v[28:29], v[34:35], v[32:33] neg_lo:[0,1] neg_hi:[0,1]
	s_nop 0
	v_add_f32_e32 v26, v26, v29
	v_add_f32_e32 v26, v28, v26
	v_add_f32_e32 v29, v40, v39
	v_add_f32_e32 v26, v31, v26
	v_sub_f32_e32 v28, v29, v40
	v_mul_f32_e32 v26, v38, v26
	v_sub_f32_e32 v28, v39, v28
	v_add_f32_e32 v26, v28, v26
	v_add_f32_e32 v30, v29, v26
	v_mul_f32_e32 v32, v30, v30
	v_fmamk_f32 v28, v32, 0x3e9b6dac, v219
	v_fmaak_f32 v167, v32, v28, 0x3f2aaada
	v_cvt_f32_i32_e32 v28, v36
	v_sub_f32_e32 v29, v30, v29
	v_sub_f32_e32 v26, v26, v29
	v_mul_f32_e32 v29, v30, v32
	v_pk_mul_f32 v[32:33], v[28:29], v[166:167]
	v_ldexp_f32 v31, v30, 1
	v_fma_f32 v30, v28, s76, -v32
	v_fmac_f32_e32 v30, 0xb102e308, v28
	v_pk_add_f32 v[28:29], v[32:33], v[30:31]
	v_ldexp_f32 v26, v26, 1
	v_sub_f32_e32 v31, v29, v31
	v_sub_f32_e32 v31, v33, v31
	v_add_f32_e32 v35, v26, v31
	v_mov_b32_e32 v34, v32
	v_pk_add_f32 v[32:33], v[28:29], v[32:33] neg_lo:[0,1] neg_hi:[0,1]
	v_pk_add_f32 v[36:37], v[28:29], v[34:35]
	v_mov_b32_e32 v31, v28
	v_mov_b32_e32 v33, v37
	v_pk_add_f32 v[38:39], v[30:31], v[32:33] neg_lo:[0,1] neg_hi:[0,1]
	v_pk_add_f32 v[30:31], v[30:31], v[32:33]
	v_mov_b32_e32 v34, v35
	v_pk_add_f32 v[32:33], v[30:31], v[28:29] op_sel:[1,0] op_sel_hi:[0,1] neg_lo:[0,1] neg_hi:[0,1]
	v_pk_add_f32 v[40:41], v[36:37], v[32:33] op_sel_hi:[1,0] neg_lo:[0,1] neg_hi:[0,1]
	v_mov_b32_e32 v36, v37
	v_mov_b32_e32 v37, v31
	v_pk_mov_b32 v[32:33], v[28:29], v[32:33] op_sel:[1,0]
	v_mov_b32_e32 v35, v28
	v_pk_add_f32 v[32:33], v[36:37], v[32:33] neg_lo:[0,1] neg_hi:[0,1]
	v_mov_b32_e32 v40, v38
	v_pk_add_f32 v[28:29], v[34:35], v[32:33] neg_lo:[0,1] neg_hi:[0,1]
	v_mov_b32_e32 v39, v31
	v_pk_add_f32 v[32:33], v[40:41], v[28:29]
	s_nop 0
	v_pk_add_f32 v[34:35], v[32:33], v[32:33] op_sel:[0,1] op_sel_hi:[1,0]
	s_nop 0
	v_pk_add_f32 v[30:31], v[30:31], v[34:35] op_sel:[1,0] op_sel_hi:[0,1]
	v_mov_b32_e32 v33, v30
	v_pk_add_f32 v[36:37], v[32:33], v[38:39] neg_lo:[0,1] neg_hi:[0,1]
	v_mov_b32_e32 v29, v34
	v_sub_f32_e32 v26, v32, v36
	v_pk_add_f32 v[28:29], v[28:29], v[36:37] neg_lo:[0,1] neg_hi:[0,1]
	v_sub_f32_e32 v26, v38, v26
	v_add_f32_e32 v26, v28, v26
	v_add_f32_e32 v26, v26, v29
	v_or_b32_e32 v28, 8, v10
	v_add_f32_e32 v26, v30, v26
	v_ashrrev_i32_e32 v29, 31, v28
	v_cndmask_b32_e64 v26, v222, v26, s[4:5]
	v_cmp_lt_f32_e64 s[4:5], |v11|, s77
	v_lshlrev_b64 v[28:29], 9, v[28:29]
	v_lshl_add_u64 v[28:29], v[6:7], 0, v[28:29]
	v_cndmask_b32_e64 v11, v26, v11, s[4:5]
; __device__ __forceinline__ void phase_small(const Params& P, int l) {
;     ...
;         for (int i = 0; i < 32; ++i) { const int s = lane * 32 + i; const float xx = misc[(size_t)(b * 2048 + s) * 128 + 64 + h] + bias;
;             const float ls = -(fmaxf(-xx, 0.f) + log1pf(expf(-fabsf(xx)))); run += ls; loc[i] = run; }
	v_add_f32_e32 v25, v25, v11
	v_add_f32_e32 v11, v27, v104
	v_mul_f32_e64 v28, |v11|, s33
	v_fma_f32 v29, |v11|, s33, -v28
	v_rndne_f32_e32 v30, v28
	v_fma_f32 v29, |v11|, s71, v29
	v_sub_f32_e32 v28, v28, v30
	v_add_f32_e32 v28, v28, v29
	v_exp_f32_e32 v28, v28
	v_cvt_i32_f32_e32 v29, v30
	v_cmp_ngt_f32_e64 s[4:5], |v11|, s72
	v_max_f32_e64 v26, -v11, 0
	v_ldexp_f32 v28, v28, v29
	v_cndmask_b32_e64 v28, 0, v28, s[4:5]
	v_cmp_nlt_f32_e64 s[4:5], |v11|, s73
	s_nop 1
	v_cndmask_b32_e64 v11, v222, v28, s[4:5]
	v_add_f32_e32 v30, 1.0, v11
	v_add_f32_e32 v28, -1.0, v30
	v_sub_f32_e32 v29, v28, v30
	v_add_f32_e32 v29, 1.0, v29
	v_sub_f32_e32 v28, v11, v28
	v_add_f32_e32 v31, v28, v29
	v_frexp_mant_f32_e32 v28, v30
	v_cmp_gt_f32_e64 s[4:5], s75, v28
	v_cvt_f64_f32_e32 v[28:29], v30
	v_frexp_exp_i32_f64_e32 v28, v[28:29]
	v_subbrev_co_u32_e64 v36, s[4:5], 0, v28, s[4:5]
	v_sub_u32_e32 v28, 0, v36
	v_ldexp_f32 v29, v30, v28
	v_add_f32_e32 v30, -1.0, v29
	v_add_f32_e32 v32, 1.0, v29
	v_ldexp_f32 v28, v31, v28
	v_add_f32_e32 v31, 1.0, v30
	v_add_f32_e32 v33, -1.0, v32
	v_sub_f32_e32 v31, v29, v31
	v_sub_f32_e32 v29, v29, v33
	v_add_f32_e32 v31, v28, v31
	v_add_f32_e32 v28, v28, v29
	v_add_f32_e32 v37, v32, v28
	v_rcp_f32_e32 v39, v37
	v_sub_f32_e32 v29, v32, v37
	v_add_f32_e32 v38, v28, v29
	v_add_f32_e32 v29, v30, v31
	v_mul_f32_e32 v41, v29, v39
	v_sub_f32_e32 v28, v30, v29
	v_mul_f32_e32 v30, v37, v41
	v_fma_f32 v32, v41, v37, -v30
	v_fmac_f32_e32 v32, v41, v38
	v_add_f32_e32 v40, v31, v28
	v_add_f32_e32 v28, v30, v32
	v_sub_f32_e32 v31, v29, v28
	v_pk_add_f32 v[34:35], v[28:29], v[30:31] neg_lo:[0,1] neg_hi:[0,1]
	v_mov_b32_e32 v33, v28
	v_pk_add_f32 v[28:29], v[34:35], v[32:33] neg_lo:[0,1] neg_hi:[0,1]
	v_cmp_neq_f32_e64 s[4:5], s74, v11
	v_add_f32_e32 v29, v40, v29
	v_add_f32_e32 v28, v28, v29
	v_add_f32_e32 v29, v31, v28
	v_mul_f32_e32 v40, v39, v29
	v_mul_f32_e32 v30, v37, v40
	v_fma_f32 v32, v40, v37, -v30
	v_fmac_f32_e32 v32, v40, v38
	v_sub_f32_e32 v31, v31, v29
	v_add_f32_e32 v37, v28, v31
	v_add_f32_e32 v28, v30, v32
	v_sub_f32_e32 v31, v29, v28
	v_pk_add_f32 v[34:35], v[28:29], v[30:31] neg_lo:[0,1] neg_hi:[0,1]
	v_mov_b32_e32 v33, v28
	v_pk_add_f32 v[28:29], v[34:35], v[32:33] neg_lo:[0,1] neg_hi:[0,1]
	s_nop 0
	v_add_f32_e32 v29, v37, v29
	v_add_f32_e32 v28, v28, v29
	v_add_f32_e32 v29, v41, v40
	v_add_f32_e32 v28, v31, v28
	v_sub_f32_e32 v30, v29, v41
	v_mul_f32_e32 v28, v39, v28
	v_sub_f32_e32 v30, v40, v30
	v_add_f32_e32 v30, v30, v28
	v_add_f32_e32 v32, v29, v30
	v_mul_f32_e32 v33, v32, v32
	v_fmamk_f32 v28, v33, 0x3e9b6dac, v219
	v_fmaak_f32 v167, v33, v28, 0x3f2aaada
	v_cvt_f32_i32_e32 v28, v36
	v_sub_f32_e32 v29, v32, v29
	v_sub_f32_e32 v29, v30, v29
	v_ldexp_f32 v34, v29, 1
	v_mul_f32_e32 v29, v32, v33
	v_ldexp_f32 v31, v32, 1
	v_pk_mul_f32 v[32:33], v[28:29], v[166:167]
	s_nop 0
	v_fma_f32 v30, v28, s76, -v32
	v_fmac_f32_e32 v30, 0xb102e308, v28
	v_pk_add_f32 v[28:29], v[32:33], v[30:31]
	s_nop 0
	v_sub_f32_e32 v31, v29, v31
	v_sub_f32_e32 v31, v33, v31
	v_add_f32_e32 v35, v34, v31
	v_mov_b32_e32 v34, v32
	v_pk_add_f32 v[32:33], v[28:29], v[32:33] neg_lo:[0,1] neg_hi:[0,1]
	v_pk_add_f32 v[36:37], v[28:29], v[34:35]
	v_mov_b32_e32 v31, v28
	v_mov_b32_e32 v33, v37
	v_pk_add_f32 v[38:39], v[30:31], v[32:33] neg_lo:[0,1] neg_hi:[0,1]
	v_pk_add_f32 v[30:31], v[30:31], v[32:33]
	v_mov_b32_e32 v34, v35
	v_pk_add_f32 v[32:33], v[30:31], v[28:29] op_sel:[1,0] op_sel_hi:[0,1] neg_lo:[0,1] neg_hi:[0,1]
	v_pk_add_f32 v[40:41], v[36:37], v[32:33] op_sel_hi:[1,0] neg_lo:[0,1] neg_hi:[0,1]
	v_mov_b32_e32 v36, v37
	v_mov_b32_e32 v37, v31
	v_pk_mov_b32 v[32:33], v[28:29], v[32:33] op_sel:[1,0]
	v_mov_b32_e32 v35, v28
	v_pk_add_f32 v[32:33], v[36:37], v[32:33] neg_lo:[0,1] neg_hi:[0,1]
	v_mov_b32_e32 v40, v38
	v_pk_add_f32 v[28:29], v[34:35], v[32:33] neg_lo:[0,1] neg_hi:[0,1]
	v_mov_b32_e32 v39, v31
	v_pk_add_f32 v[32:33], v[40:41], v[28:29]
	s_nop 0
	v_pk_add_f32 v[34:35], v[32:33], v[32:33] op_sel:[0,1] op_sel_hi:[1,0]
	s_nop 0
	v_pk_add_f32 v[30:31], v[30:31], v[34:35] op_sel:[1,0] op_sel_hi:[0,1]
	v_mov_b32_e32 v33, v30
	v_pk_add_f32 v[36:37], v[32:33], v[38:39] neg_lo:[0,1] neg_hi:[0,1]
	v_mov_b32_e32 v29, v34
	v_sub_f32_e32 v31, v32, v36
	v_pk_add_f32 v[28:29], v[28:29], v[36:37] neg_lo:[0,1] neg_hi:[0,1]
	v_sub_f32_e32 v31, v38, v31
	v_add_f32_e32 v28, v28, v31
	v_add_f32_e32 v28, v28, v29
	v_add_f32_e32 v28, v30, v28
	v_cndmask_b32_e64 v28, v222, v28, s[4:5]
	v_cmp_lt_f32_e64 s[4:5], |v11|, s77
	s_nop 1
	v_cndmask_b32_e64 v11, v28, v11, s[4:5]
	v_or_b32_e32 v28, 9, v10
	v_ashrrev_i32_e32 v29, 31, v28
	v_lshlrev_b64 v[28:29], 9, v[28:29]
	v_lshl_add_u64 v[28:29], v[6:7], 0, v[28:29]
	v_add_f32_e32 v26, v26, v11
	v_add_f32_e32 v11, v27, v105
	v_mul_f32_e64 v28, |v11|, s33
	v_fma_f32 v29, |v11|, s33, -v28
	v_rndne_f32_e32 v30, v28
	v_fma_f32 v29, |v11|, s71, v29
	v_sub_f32_e32 v28, v28, v30
	v_add_f32_e32 v28, v28, v29
	v_exp_f32_e32 v28, v28
	v_cvt_i32_f32_e32 v29, v30
	v_cmp_ngt_f32_e64 s[4:5], |v11|, s72
	v_max_f32_e64 v42, -v11, 0
	v_ldexp_f32 v28, v28, v29
	v_cndmask_b32_e64 v28, 0, v28, s[4:5]
	v_cmp_nlt_f32_e64 s[4:5], |v11|, s73
	s_nop 1
	v_cndmask_b32_e64 v11, v222, v28, s[4:5]
	v_add_f32_e32 v30, 1.0, v11
	v_add_f32_e32 v28, -1.0, v30
	v_sub_f32_e32 v29, v28, v30
	v_add_f32_e32 v29, 1.0, v29
	v_sub_f32_e32 v28, v11, v28
	v_add_f32_e32 v31, v28, v29
	v_frexp_mant_f32_e32 v28, v30
	v_cmp_gt_f32_e64 s[4:5], s75, v28
	v_cvt_f64_f32_e32 v[28:29], v30
	v_frexp_exp_i32_f64_e32 v28, v[28:29]
	v_subbrev_co_u32_e64 v36, s[4:5], 0, v28, s[4:5]
	v_sub_u32_e32 v28, 0, v36
	v_ldexp_f32 v29, v30, v28
	v_add_f32_e32 v30, -1.0, v29
; __device__ __forceinline__ void phase_small(const Params& P, int l) {
;     ...
;         for (int i = 0; i < 32; ++i) { const int s = lane * 32 + i; const float xx = misc[(size_t)(b * 2048 + s) * 128 + 64 + h] + bias;
;             const float ls = -(fmaxf(-xx, 0.f) + log1pf(expf(-fabsf(xx)))); run += ls; loc[i] = run; }
	v_add_f32_e32 v32, 1.0, v29
	v_ldexp_f32 v28, v31, v28
	v_add_f32_e32 v31, 1.0, v30
	v_add_f32_e32 v33, -1.0, v32
	v_sub_f32_e32 v31, v29, v31
	v_sub_f32_e32 v29, v29, v33
	v_add_f32_e32 v31, v28, v31
	v_add_f32_e32 v28, v28, v29
	v_add_f32_e32 v37, v32, v28
	v_rcp_f32_e32 v39, v37
	v_sub_f32_e32 v29, v32, v37
	v_add_f32_e32 v38, v28, v29
	v_add_f32_e32 v29, v30, v31
	v_mul_f32_e32 v41, v29, v39
	v_sub_f32_e32 v28, v30, v29
	v_mul_f32_e32 v30, v37, v41
	v_fma_f32 v32, v41, v37, -v30
	v_fmac_f32_e32 v32, v41, v38
	v_add_f32_e32 v40, v31, v28
	v_add_f32_e32 v28, v30, v32
	v_sub_f32_e32 v31, v29, v28
	v_pk_add_f32 v[34:35], v[28:29], v[30:31] neg_lo:[0,1] neg_hi:[0,1]
	v_mov_b32_e32 v33, v28
	v_pk_add_f32 v[28:29], v[34:35], v[32:33] neg_lo:[0,1] neg_hi:[0,1]
	v_cmp_neq_f32_e64 s[4:5], s74, v11
	v_add_f32_e32 v29, v40, v29
	v_add_f32_e32 v28, v28, v29
	v_add_f32_e32 v29, v31, v28
	v_mul_f32_e32 v40, v39, v29
	v_mul_f32_e32 v30, v37, v40
	v_fma_f32 v32, v40, v37, -v30
	v_fmac_f32_e32 v32, v40, v38
	v_sub_f32_e32 v31, v31, v29
	v_add_f32_e32 v37, v28, v31
	v_add_f32_e32 v28, v30, v32
	v_sub_f32_e32 v31, v29, v28
	v_pk_add_f32 v[34:35], v[28:29], v[30:31] neg_lo:[0,1] neg_hi:[0,1]
	v_mov_b32_e32 v33, v28
	v_pk_add_f32 v[28:29], v[34:35], v[32:33] neg_lo:[0,1] neg_hi:[0,1]
	s_nop 0
	v_add_f32_e32 v29, v37, v29
	v_add_f32_e32 v28, v28, v29
	v_add_f32_e32 v29, v41, v40
	v_add_f32_e32 v28, v31, v28
	v_sub_f32_e32 v30, v29, v41
	v_mul_f32_e32 v28, v39, v28
	v_sub_f32_e32 v30, v40, v30
	v_add_f32_e32 v30, v30, v28
	v_add_f32_e32 v32, v29, v30
	v_mul_f32_e32 v33, v32, v32
	v_fmamk_f32 v28, v33, 0x3e9b6dac, v219
	v_fmaak_f32 v167, v33, v28, 0x3f2aaada
	v_cvt_f32_i32_e32 v28, v36
	v_sub_f32_e32 v29, v32, v29
	v_sub_f32_e32 v29, v30, v29
	v_ldexp_f32 v34, v29, 1
	v_mul_f32_e32 v29, v32, v33
	v_ldexp_f32 v31, v32, 1
	v_pk_mul_f32 v[32:33], v[28:29], v[166:167]
	s_nop 0
	v_fma_f32 v30, v28, s76, -v32
	v_fmac_f32_e32 v30, 0xb102e308, v28
	v_pk_add_f32 v[28:29], v[32:33], v[30:31]
	s_nop 0
	v_sub_f32_e32 v31, v29, v31
	v_sub_f32_e32 v31, v33, v31
	v_add_f32_e32 v35, v34, v31
	v_mov_b32_e32 v34, v32
	v_pk_add_f32 v[32:33], v[28:29], v[32:33] neg_lo:[0,1] neg_hi:[0,1]
	v_pk_add_f32 v[36:37], v[28:29], v[34:35]
	v_mov_b32_e32 v31, v28
	v_mov_b32_e32 v33, v37
	v_pk_add_f32 v[38:39], v[30:31], v[32:33] neg_lo:[0,1] neg_hi:[0,1]
	v_pk_add_f32 v[30:31], v[30:31], v[32:33]
	v_mov_b32_e32 v34, v35
	v_pk_add_f32 v[32:33], v[30:31], v[28:29] op_sel:[1,0] op_sel_hi:[0,1] neg_lo:[0,1] neg_hi:[0,1]
	v_pk_add_f32 v[40:41], v[36:37], v[32:33] op_sel_hi:[1,0] neg_lo:[0,1] neg_hi:[0,1]
	v_mov_b32_e32 v36, v37
	v_mov_b32_e32 v37, v31
	v_pk_mov_b32 v[32:33], v[28:29], v[32:33] op_sel:[1,0]
	v_mov_b32_e32 v35, v28
	v_pk_add_f32 v[32:33], v[36:37], v[32:33] neg_lo:[0,1] neg_hi:[0,1]
	v_mov_b32_e32 v40, v38
	v_pk_add_f32 v[28:29], v[34:35], v[32:33] neg_lo:[0,1] neg_hi:[0,1]
	v_mov_b32_e32 v39, v31
	v_pk_add_f32 v[32:33], v[40:41], v[28:29]
	s_nop 0
	v_pk_add_f32 v[34:35], v[32:33], v[32:33] op_sel:[0,1] op_sel_hi:[1,0]
	s_nop 0
	v_pk_add_f32 v[30:31], v[30:31], v[34:35] op_sel:[1,0] op_sel_hi:[0,1]
	v_mov_b32_e32 v33, v30
	v_pk_add_f32 v[36:37], v[32:33], v[38:39] neg_lo:[0,1] neg_hi:[0,1]
	v_mov_b32_e32 v29, v34
	v_sub_f32_e32 v31, v32, v36
	v_pk_add_f32 v[28:29], v[28:29], v[36:37] neg_lo:[0,1] neg_hi:[0,1]
	v_sub_f32_e32 v31, v38, v31
	v_add_f32_e32 v28, v28, v31
	v_add_f32_e32 v28, v28, v29
	v_add_f32_e32 v28, v30, v28
	v_or_b32_e32 v30, 10, v10
	v_ashrrev_i32_e32 v31, 31, v30
	v_cndmask_b32_e64 v28, v222, v28, s[4:5]
	v_cmp_lt_f32_e64 s[4:5], |v11|, s77
	v_lshlrev_b64 v[30:31], 9, v[30:31]
	v_lshl_add_u64 v[30:31], v[6:7], 0, v[30:31]
	v_cndmask_b32_e64 v11, v28, v11, s[4:5]
	v_add_f32_e32 v28, v42, v11
	v_add_f32_e32 v11, v27, v106
	v_mul_f32_e64 v30, |v11|, s33
	v_fma_f32 v31, |v11|, s33, -v30
	v_rndne_f32_e32 v32, v30
	v_fma_f32 v31, |v11|, s71, v31
	v_sub_f32_e32 v30, v30, v32
	v_add_f32_e32 v30, v30, v31
	v_exp_f32_e32 v30, v30
	v_cvt_i32_f32_e32 v31, v32
	v_cmp_ngt_f32_e64 s[4:5], |v11|, s72
	v_max_f32_e64 v29, -v11, 0
	v_ldexp_f32 v30, v30, v31
	v_cndmask_b32_e64 v30, 0, v30, s[4:5]
	v_cmp_nlt_f32_e64 s[4:5], |v11|, s73
	s_nop 1
	v_cndmask_b32_e64 v11, v222, v30, s[4:5]
	v_add_f32_e32 v32, 1.0, v11
	v_add_f32_e32 v30, -1.0, v32
	v_sub_f32_e32 v31, v30, v32
	v_add_f32_e32 v31, 1.0, v31
	v_sub_f32_e32 v30, v11, v30
	v_add_f32_e32 v33, v30, v31
	v_frexp_mant_f32_e32 v30, v32
	v_cmp_gt_f32_e64 s[4:5], s75, v30
	v_cvt_f64_f32_e32 v[30:31], v32
	v_frexp_exp_i32_f64_e32 v30, v[30:31]
	v_subbrev_co_u32_e64 v38, s[4:5], 0, v30, s[4:5]
	v_sub_u32_e32 v30, 0, v38
	v_ldexp_f32 v31, v32, v30
	v_add_f32_e32 v32, -1.0, v31
	v_add_f32_e32 v34, 1.0, v31
	v_ldexp_f32 v30, v33, v30
	v_add_f32_e32 v33, 1.0, v32
	v_add_f32_e32 v35, -1.0, v34
	v_sub_f32_e32 v33, v31, v33
	v_sub_f32_e32 v31, v31, v35
	v_add_f32_e32 v33, v30, v33
	v_add_f32_e32 v30, v30, v31
	v_add_f32_e32 v39, v34, v30
	v_rcp_f32_e32 v41, v39
	v_sub_f32_e32 v31, v34, v39
	v_add_f32_e32 v40, v30, v31
	v_add_f32_e32 v31, v32, v33
	v_mul_f32_e32 v43, v31, v41
	v_sub_f32_e32 v30, v32, v31
	v_mul_f32_e32 v32, v39, v43
	v_fma_f32 v34, v43, v39, -v32
	v_fmac_f32_e32 v34, v43, v40
	v_add_f32_e32 v42, v33, v30
	v_add_f32_e32 v30, v32, v34
	v_sub_f32_e32 v33, v31, v30
	v_pk_add_f32 v[36:37], v[30:31], v[32:33] neg_lo:[0,1] neg_hi:[0,1]
	v_mov_b32_e32 v35, v30
	v_pk_add_f32 v[30:31], v[36:37], v[34:35] neg_lo:[0,1] neg_hi:[0,1]
	v_cmp_neq_f32_e64 s[4:5], s74, v11
	v_add_f32_e32 v31, v42, v31
	v_add_f32_e32 v30, v30, v31
	v_add_f32_e32 v31, v33, v30
	v_mul_f32_e32 v42, v41, v31
	v_mul_f32_e32 v32, v39, v42
	v_fma_f32 v34, v42, v39, -v32
; __device__ __forceinline__ void phase_small(const Params& P, int l) {
;     ...
;         for (int i = 0; i < 32; ++i) { const int s = lane * 32 + i; const float xx = misc[(size_t)(b * 2048 + s) * 128 + 64 + h] + bias;
;             const float ls = -(fmaxf(-xx, 0.f) + log1pf(expf(-fabsf(xx)))); run += ls; loc[i] = run; }
	v_fmac_f32_e32 v34, v42, v40
	v_sub_f32_e32 v33, v33, v31
	v_add_f32_e32 v39, v30, v33
	v_add_f32_e32 v30, v32, v34
	v_sub_f32_e32 v33, v31, v30
	v_pk_add_f32 v[36:37], v[30:31], v[32:33] neg_lo:[0,1] neg_hi:[0,1]
	v_mov_b32_e32 v35, v30
	v_pk_add_f32 v[30:31], v[36:37], v[34:35] neg_lo:[0,1] neg_hi:[0,1]
	s_nop 0
	v_add_f32_e32 v31, v39, v31
	v_add_f32_e32 v30, v30, v31
	v_add_f32_e32 v31, v43, v42
	v_add_f32_e32 v30, v33, v30
	v_sub_f32_e32 v32, v31, v43
	v_mul_f32_e32 v30, v41, v30
	v_sub_f32_e32 v32, v42, v32
	v_add_f32_e32 v32, v32, v30
	v_add_f32_e32 v34, v31, v32
	v_mul_f32_e32 v35, v34, v34
	v_fmamk_f32 v30, v35, 0x3e9b6dac, v219
	v_fmaak_f32 v167, v35, v30, 0x3f2aaada
	v_cvt_f32_i32_e32 v30, v38
	v_sub_f32_e32 v31, v34, v31
	v_sub_f32_e32 v31, v32, v31
	v_ldexp_f32 v36, v31, 1
	v_mul_f32_e32 v31, v34, v35
	v_ldexp_f32 v33, v34, 1
	v_pk_mul_f32 v[34:35], v[30:31], v[166:167]
	s_nop 0
	v_fma_f32 v32, v30, s76, -v34
	v_fmac_f32_e32 v32, 0xb102e308, v30
	v_pk_add_f32 v[30:31], v[34:35], v[32:33]
	s_nop 0
	v_sub_f32_e32 v33, v31, v33
	v_sub_f32_e32 v33, v35, v33
	v_add_f32_e32 v37, v36, v33
	v_mov_b32_e32 v36, v34
	v_pk_add_f32 v[34:35], v[30:31], v[34:35] neg_lo:[0,1] neg_hi:[0,1]
	v_pk_add_f32 v[38:39], v[30:31], v[36:37]
	v_mov_b32_e32 v33, v30
	v_mov_b32_e32 v35, v39
	v_pk_add_f32 v[40:41], v[32:33], v[34:35] neg_lo:[0,1] neg_hi:[0,1]
	v_pk_add_f32 v[32:33], v[32:33], v[34:35]
	v_mov_b32_e32 v36, v37
	v_pk_add_f32 v[34:35], v[32:33], v[30:31] op_sel:[1,0] op_sel_hi:[0,1] neg_lo:[0,1] neg_hi:[0,1]
	v_pk_add_f32 v[42:43], v[38:39], v[34:35] op_sel_hi:[1,0] neg_lo:[0,1] neg_hi:[0,1]
	v_mov_b32_e32 v38, v39
	v_mov_b32_e32 v39, v33
	v_pk_mov_b32 v[34:35], v[30:31], v[34:35] op_sel:[1,0]
	v_mov_b32_e32 v37, v30
	v_pk_add_f32 v[34:35], v[38:39], v[34:35] neg_lo:[0,1] neg_hi:[0,1]
	v_mov_b32_e32 v42, v40
	v_pk_add_f32 v[30:31], v[36:37], v[34:35] neg_lo:[0,1] neg_hi:[0,1]
	v_mov_b32_e32 v41, v33
	v_pk_add_f32 v[34:35], v[42:43], v[30:31]
	s_nop 0
	v_pk_add_f32 v[36:37], v[34:35], v[34:35] op_sel:[0,1] op_sel_hi:[1,0]
	s_nop 0
	v_pk_add_f32 v[32:33], v[32:33], v[36:37] op_sel:[1,0] op_sel_hi:[0,1]
	v_mov_b32_e32 v35, v32
	v_pk_add_f32 v[38:39], v[34:35], v[40:41] neg_lo:[0,1] neg_hi:[0,1]
	v_mov_b32_e32 v31, v36
	v_sub_f32_e32 v33, v34, v38
	v_pk_add_f32 v[30:31], v[30:31], v[38:39] neg_lo:[0,1] neg_hi:[0,1]
	v_sub_f32_e32 v33, v40, v33
	v_add_f32_e32 v30, v30, v33
	v_add_f32_e32 v30, v30, v31
	v_add_f32_e32 v30, v32, v30
	v_cndmask_b32_e64 v30, v222, v30, s[4:5]
	v_cmp_lt_f32_e64 s[4:5], |v11|, s77
	s_nop 1
	v_cndmask_b32_e64 v11, v30, v11, s[4:5]
	v_or_b32_e32 v30, 11, v10
	v_ashrrev_i32_e32 v31, 31, v30
	v_lshlrev_b64 v[30:31], 9, v[30:31]
	v_lshl_add_u64 v[30:31], v[6:7], 0, v[30:31]
	v_add_f32_e32 v29, v29, v11
	v_add_f32_e32 v11, v27, v107
	v_mul_f32_e64 v30, |v11|, s33
	v_fma_f32 v31, |v11|, s33, -v30
	v_rndne_f32_e32 v32, v30
	v_fma_f32 v31, |v11|, s71, v31
	v_sub_f32_e32 v30, v30, v32
	v_add_f32_e32 v30, v30, v31
	v_exp_f32_e32 v30, v30
	v_cvt_i32_f32_e32 v31, v32
	v_cmp_ngt_f32_e64 s[4:5], |v11|, s72
	v_max_f32_e64 v44, -v11, 0
	v_ldexp_f32 v30, v30, v31
	v_cndmask_b32_e64 v30, 0, v30, s[4:5]
	v_cmp_nlt_f32_e64 s[4:5], |v11|, s73
	s_nop 1
	v_cndmask_b32_e64 v11, v222, v30, s[4:5]
	v_add_f32_e32 v32, 1.0, v11
	v_add_f32_e32 v30, -1.0, v32
	v_sub_f32_e32 v31, v30, v32
	v_add_f32_e32 v31, 1.0, v31
	v_sub_f32_e32 v30, v11, v30
	v_add_f32_e32 v33, v30, v31
	v_frexp_mant_f32_e32 v30, v32
	v_cmp_gt_f32_e64 s[4:5], s75, v30
	v_cvt_f64_f32_e32 v[30:31], v32
	v_frexp_exp_i32_f64_e32 v30, v[30:31]
	v_subbrev_co_u32_e64 v38, s[4:5], 0, v30, s[4:5]
	v_sub_u32_e32 v30, 0, v38
	v_ldexp_f32 v31, v32, v30
	v_add_f32_e32 v32, -1.0, v31
	v_add_f32_e32 v34, 1.0, v31
	v_ldexp_f32 v30, v33, v30
	v_add_f32_e32 v33, 1.0, v32
	v_add_f32_e32 v35, -1.0, v34
	v_sub_f32_e32 v33, v31, v33
	v_sub_f32_e32 v31, v31, v35
	v_add_f32_e32 v33, v30, v33
	v_add_f32_e32 v30, v30, v31
	v_add_f32_e32 v39, v34, v30
	v_rcp_f32_e32 v41, v39
	v_sub_f32_e32 v31, v34, v39
	v_add_f32_e32 v40, v30, v31
	v_add_f32_e32 v31, v32, v33
	v_mul_f32_e32 v43, v31, v41
	v_sub_f32_e32 v30, v32, v31
	v_mul_f32_e32 v32, v39, v43
	v_fma_f32 v34, v43, v39, -v32
	v_fmac_f32_e32 v34, v43, v40
	v_add_f32_e32 v42, v33, v30
	v_add_f32_e32 v30, v32, v34
	v_sub_f32_e32 v33, v31, v30
	v_pk_add_f32 v[36:37], v[30:31], v[32:33] neg_lo:[0,1] neg_hi:[0,1]
	v_mov_b32_e32 v35, v30
	v_pk_add_f32 v[30:31], v[36:37], v[34:35] neg_lo:[0,1] neg_hi:[0,1]
	v_cmp_neq_f32_e64 s[4:5], s74, v11
	v_add_f32_e32 v31, v42, v31
	v_add_f32_e32 v30, v30, v31
	v_add_f32_e32 v31, v33, v30
	v_mul_f32_e32 v42, v41, v31
	v_mul_f32_e32 v32, v39, v42
	v_fma_f32 v34, v42, v39, -v32
	v_fmac_f32_e32 v34, v42, v40
	v_sub_f32_e32 v33, v33, v31
	v_add_f32_e32 v39, v30, v33
	v_add_f32_e32 v30, v32, v34
	v_sub_f32_e32 v33, v31, v30
	v_pk_add_f32 v[36:37], v[30:31], v[32:33] neg_lo:[0,1] neg_hi:[0,1]
	v_mov_b32_e32 v35, v30
	v_pk_add_f32 v[30:31], v[36:37], v[34:35] neg_lo:[0,1] neg_hi:[0,1]
	s_nop 0
	v_add_f32_e32 v31, v39, v31
	v_add_f32_e32 v30, v30, v31
	v_add_f32_e32 v31, v43, v42
	v_add_f32_e32 v30, v33, v30
	v_sub_f32_e32 v32, v31, v43
	v_mul_f32_e32 v30, v41, v30
	v_sub_f32_e32 v32, v42, v32
	v_add_f32_e32 v32, v32, v30
	v_add_f32_e32 v34, v31, v32
	v_mul_f32_e32 v35, v34, v34
	v_fmamk_f32 v30, v35, 0x3e9b6dac, v219
	v_fmaak_f32 v167, v35, v30, 0x3f2aaada
	v_cvt_f32_i32_e32 v30, v38
	v_sub_f32_e32 v31, v34, v31
	v_sub_f32_e32 v31, v32, v31
	v_ldexp_f32 v36, v31, 1
	v_mul_f32_e32 v31, v34, v35
	v_ldexp_f32 v33, v34, 1
	v_pk_mul_f32 v[34:35], v[30:31], v[166:167]
	s_nop 0
	v_fma_f32 v32, v30, s76, -v34
	v_fmac_f32_e32 v32, 0xb102e308, v30
; __device__ __forceinline__ void phase_small(const Params& P, int l) {
;     ...
;         for (int i = 0; i < 32; ++i) { const int s = lane * 32 + i; const float xx = misc[(size_t)(b * 2048 + s) * 128 + 64 + h] + bias;
;             const float ls = -(fmaxf(-xx, 0.f) + log1pf(expf(-fabsf(xx)))); run += ls; loc[i] = run; }
	v_pk_add_f32 v[30:31], v[34:35], v[32:33]
	s_nop 0
	v_sub_f32_e32 v33, v31, v33
	v_sub_f32_e32 v33, v35, v33
	v_add_f32_e32 v37, v36, v33
	v_mov_b32_e32 v36, v34
	v_pk_add_f32 v[34:35], v[30:31], v[34:35] neg_lo:[0,1] neg_hi:[0,1]
	v_pk_add_f32 v[38:39], v[30:31], v[36:37]
	v_mov_b32_e32 v33, v30
	v_mov_b32_e32 v35, v39
	v_pk_add_f32 v[40:41], v[32:33], v[34:35] neg_lo:[0,1] neg_hi:[0,1]
	v_pk_add_f32 v[32:33], v[32:33], v[34:35]
	v_mov_b32_e32 v36, v37
	v_pk_add_f32 v[34:35], v[32:33], v[30:31] op_sel:[1,0] op_sel_hi:[0,1] neg_lo:[0,1] neg_hi:[0,1]
	v_pk_add_f32 v[42:43], v[38:39], v[34:35] op_sel_hi:[1,0] neg_lo:[0,1] neg_hi:[0,1]
	v_mov_b32_e32 v38, v39
	v_mov_b32_e32 v39, v33
	v_pk_mov_b32 v[34:35], v[30:31], v[34:35] op_sel:[1,0]
	v_mov_b32_e32 v37, v30
	v_pk_add_f32 v[34:35], v[38:39], v[34:35] neg_lo:[0,1] neg_hi:[0,1]
	v_mov_b32_e32 v42, v40
	v_pk_add_f32 v[30:31], v[36:37], v[34:35] neg_lo:[0,1] neg_hi:[0,1]
	v_mov_b32_e32 v41, v33
	v_pk_add_f32 v[34:35], v[42:43], v[30:31]
	s_nop 0
	v_pk_add_f32 v[36:37], v[34:35], v[34:35] op_sel:[0,1] op_sel_hi:[1,0]
	s_nop 0
	v_pk_add_f32 v[32:33], v[32:33], v[36:37] op_sel:[1,0] op_sel_hi:[0,1]
	v_mov_b32_e32 v35, v32
	v_pk_add_f32 v[38:39], v[34:35], v[40:41] neg_lo:[0,1] neg_hi:[0,1]
	v_mov_b32_e32 v31, v36
	v_sub_f32_e32 v33, v34, v38
	v_pk_add_f32 v[30:31], v[30:31], v[38:39] neg_lo:[0,1] neg_hi:[0,1]
	v_sub_f32_e32 v33, v40, v33
	v_add_f32_e32 v30, v30, v33
	v_add_f32_e32 v30, v30, v31
	v_add_f32_e32 v30, v32, v30
	v_or_b32_e32 v32, 12, v10
	v_ashrrev_i32_e32 v33, 31, v32
	v_cndmask_b32_e64 v30, v222, v30, s[4:5]
	v_cmp_lt_f32_e64 s[4:5], |v11|, s77
	v_lshlrev_b64 v[32:33], 9, v[32:33]
	v_lshl_add_u64 v[32:33], v[6:7], 0, v[32:33]
	v_cndmask_b32_e64 v11, v30, v11, s[4:5]
	v_add_f32_e32 v30, v44, v11
	v_add_f32_e32 v11, v27, v108
	v_mul_f32_e64 v32, |v11|, s33
	v_fma_f32 v33, |v11|, s33, -v32
	v_rndne_f32_e32 v34, v32
	v_fma_f32 v33, |v11|, s71, v33
	v_sub_f32_e32 v32, v32, v34
	v_add_f32_e32 v32, v32, v33
	v_exp_f32_e32 v32, v32
	v_cvt_i32_f32_e32 v33, v34
	v_cmp_ngt_f32_e64 s[4:5], |v11|, s72
	v_max_f32_e64 v31, -v11, 0
	v_ldexp_f32 v32, v32, v33
	v_cndmask_b32_e64 v32, 0, v32, s[4:5]
	v_cmp_nlt_f32_e64 s[4:5], |v11|, s73
	s_nop 1
	v_cndmask_b32_e64 v11, v222, v32, s[4:5]
	v_add_f32_e32 v34, 1.0, v11
	v_add_f32_e32 v32, -1.0, v34
	v_sub_f32_e32 v33, v32, v34
	v_add_f32_e32 v33, 1.0, v33
	v_sub_f32_e32 v32, v11, v32
	v_add_f32_e32 v35, v32, v33
	v_frexp_mant_f32_e32 v32, v34
	v_cmp_gt_f32_e64 s[4:5], s75, v32
	v_cvt_f64_f32_e32 v[32:33], v34
	v_frexp_exp_i32_f64_e32 v32, v[32:33]
	v_subbrev_co_u32_e64 v40, s[4:5], 0, v32, s[4:5]
	v_sub_u32_e32 v32, 0, v40
	v_ldexp_f32 v33, v34, v32
	v_add_f32_e32 v34, -1.0, v33
	v_add_f32_e32 v36, 1.0, v33
	v_ldexp_f32 v32, v35, v32
	v_add_f32_e32 v35, 1.0, v34
	v_add_f32_e32 v37, -1.0, v36
	v_sub_f32_e32 v35, v33, v35
	v_sub_f32_e32 v33, v33, v37
	v_add_f32_e32 v35, v32, v35
	v_add_f32_e32 v32, v32, v33
	v_add_f32_e32 v41, v36, v32
	v_rcp_f32_e32 v43, v41
	v_sub_f32_e32 v33, v36, v41
	v_add_f32_e32 v42, v32, v33
	v_add_f32_e32 v33, v34, v35
	v_mul_f32_e32 v45, v33, v43
	v_sub_f32_e32 v32, v34, v33
	v_mul_f32_e32 v34, v41, v45
	v_fma_f32 v36, v45, v41, -v34
	v_fmac_f32_e32 v36, v45, v42
	v_add_f32_e32 v44, v35, v32
	v_add_f32_e32 v32, v34, v36
	v_sub_f32_e32 v35, v33, v32
	v_pk_add_f32 v[38:39], v[32:33], v[34:35] neg_lo:[0,1] neg_hi:[0,1]
	v_mov_b32_e32 v37, v32
	v_pk_add_f32 v[32:33], v[38:39], v[36:37] neg_lo:[0,1] neg_hi:[0,1]
	v_cmp_neq_f32_e64 s[4:5], s74, v11
	v_add_f32_e32 v33, v44, v33
	v_add_f32_e32 v32, v32, v33
	v_add_f32_e32 v33, v35, v32
	v_mul_f32_e32 v44, v43, v33
	v_mul_f32_e32 v34, v41, v44
	v_fma_f32 v36, v44, v41, -v34
	v_fmac_f32_e32 v36, v44, v42
	v_sub_f32_e32 v35, v35, v33
	v_add_f32_e32 v41, v32, v35
	v_add_f32_e32 v32, v34, v36
	v_sub_f32_e32 v35, v33, v32
	v_pk_add_f32 v[38:39], v[32:33], v[34:35] neg_lo:[0,1] neg_hi:[0,1]
	v_mov_b32_e32 v37, v32
	v_pk_add_f32 v[32:33], v[38:39], v[36:37] neg_lo:[0,1] neg_hi:[0,1]
	s_nop 0
	v_add_f32_e32 v33, v41, v33
	v_add_f32_e32 v32, v32, v33
	v_add_f32_e32 v33, v45, v44
	v_add_f32_e32 v32, v35, v32
	v_sub_f32_e32 v34, v33, v45
	v_mul_f32_e32 v32, v43, v32
	v_sub_f32_e32 v34, v44, v34
	v_add_f32_e32 v34, v34, v32
	v_add_f32_e32 v36, v33, v34
	v_mul_f32_e32 v37, v36, v36
	v_fmamk_f32 v32, v37, 0x3e9b6dac, v219
	v_fmaak_f32 v167, v37, v32, 0x3f2aaada
	v_cvt_f32_i32_e32 v32, v40
	v_sub_f32_e32 v33, v36, v33
	v_sub_f32_e32 v33, v34, v33
	v_ldexp_f32 v38, v33, 1
	v_mul_f32_e32 v33, v36, v37
	v_ldexp_f32 v35, v36, 1
	v_pk_mul_f32 v[36:37], v[32:33], v[166:167]
	s_nop 0
	v_fma_f32 v34, v32, s76, -v36
	v_fmac_f32_e32 v34, 0xb102e308, v32
	v_pk_add_f32 v[32:33], v[36:37], v[34:35]
	s_nop 0
	v_sub_f32_e32 v35, v33, v35
	v_sub_f32_e32 v35, v37, v35
	v_add_f32_e32 v39, v38, v35
	v_mov_b32_e32 v38, v36
	v_pk_add_f32 v[36:37], v[32:33], v[36:37] neg_lo:[0,1] neg_hi:[0,1]
	v_pk_add_f32 v[40:41], v[32:33], v[38:39]
	v_mov_b32_e32 v35, v32
	v_mov_b32_e32 v37, v41
	v_pk_add_f32 v[42:43], v[34:35], v[36:37] neg_lo:[0,1] neg_hi:[0,1]
	v_pk_add_f32 v[34:35], v[34:35], v[36:37]
	v_mov_b32_e32 v38, v39
	v_pk_add_f32 v[36:37], v[34:35], v[32:33] op_sel:[1,0] op_sel_hi:[0,1] neg_lo:[0,1] neg_hi:[0,1]
	v_pk_add_f32 v[44:45], v[40:41], v[36:37] op_sel_hi:[1,0] neg_lo:[0,1] neg_hi:[0,1]
	v_mov_b32_e32 v40, v41
	v_mov_b32_e32 v41, v35
	v_pk_mov_b32 v[36:37], v[32:33], v[36:37] op_sel:[1,0]
	v_mov_b32_e32 v39, v32
	v_pk_add_f32 v[36:37], v[40:41], v[36:37] neg_lo:[0,1] neg_hi:[0,1]
	v_mov_b32_e32 v44, v42
	v_pk_add_f32 v[32:33], v[38:39], v[36:37] neg_lo:[0,1] neg_hi:[0,1]
	v_mov_b32_e32 v43, v35
; __device__ __forceinline__ void phase_small(const Params& P, int l) {
;     ...
;         for (int i = 0; i < 32; ++i) { const int s = lane * 32 + i; const float xx = misc[(size_t)(b * 2048 + s) * 128 + 64 + h] + bias;
;             const float ls = -(fmaxf(-xx, 0.f) + log1pf(expf(-fabsf(xx)))); run += ls; loc[i] = run; }
	v_pk_add_f32 v[36:37], v[44:45], v[32:33]
	s_nop 0
	v_pk_add_f32 v[38:39], v[36:37], v[36:37] op_sel:[0,1] op_sel_hi:[1,0]
	s_nop 0
	v_pk_add_f32 v[34:35], v[34:35], v[38:39] op_sel:[1,0] op_sel_hi:[0,1]
	v_mov_b32_e32 v37, v34
	v_pk_add_f32 v[40:41], v[36:37], v[42:43] neg_lo:[0,1] neg_hi:[0,1]
	v_mov_b32_e32 v33, v38
	v_sub_f32_e32 v35, v36, v40
	v_pk_add_f32 v[32:33], v[32:33], v[40:41] neg_lo:[0,1] neg_hi:[0,1]
	v_sub_f32_e32 v35, v42, v35
	v_add_f32_e32 v32, v32, v35
	v_add_f32_e32 v32, v32, v33
	v_add_f32_e32 v32, v34, v32
	v_cndmask_b32_e64 v32, v222, v32, s[4:5]
	v_cmp_lt_f32_e64 s[4:5], |v11|, s77
	s_nop 1
	v_cndmask_b32_e64 v11, v32, v11, s[4:5]
	v_or_b32_e32 v32, 13, v10
	v_ashrrev_i32_e32 v33, 31, v32
	v_lshlrev_b64 v[32:33], 9, v[32:33]
	v_lshl_add_u64 v[32:33], v[6:7], 0, v[32:33]
	v_add_f32_e32 v31, v31, v11
	v_add_f32_e32 v11, v27, v109
	v_mul_f32_e64 v32, |v11|, s33
	v_fma_f32 v33, |v11|, s33, -v32
	v_rndne_f32_e32 v34, v32
	v_fma_f32 v33, |v11|, s71, v33
	v_sub_f32_e32 v32, v32, v34
	v_add_f32_e32 v32, v32, v33
	v_exp_f32_e32 v32, v32
	v_cvt_i32_f32_e32 v33, v34
	v_cmp_ngt_f32_e64 s[4:5], |v11|, s72
	v_max_f32_e64 v46, -v11, 0
	v_ldexp_f32 v32, v32, v33
	v_cndmask_b32_e64 v32, 0, v32, s[4:5]
	v_cmp_nlt_f32_e64 s[4:5], |v11|, s73
	s_nop 1
	v_cndmask_b32_e64 v11, v222, v32, s[4:5]
	v_add_f32_e32 v34, 1.0, v11
	v_add_f32_e32 v32, -1.0, v34
	v_sub_f32_e32 v33, v32, v34
	v_add_f32_e32 v33, 1.0, v33
	v_sub_f32_e32 v32, v11, v32
	v_add_f32_e32 v35, v32, v33
	v_frexp_mant_f32_e32 v32, v34
	v_cmp_gt_f32_e64 s[4:5], s75, v32
	v_cvt_f64_f32_e32 v[32:33], v34
	v_frexp_exp_i32_f64_e32 v32, v[32:33]
	v_subbrev_co_u32_e64 v40, s[4:5], 0, v32, s[4:5]
	v_sub_u32_e32 v32, 0, v40
	v_ldexp_f32 v33, v34, v32
	v_add_f32_e32 v34, -1.0, v33
	v_add_f32_e32 v36, 1.0, v33
	v_ldexp_f32 v32, v35, v32
	v_add_f32_e32 v35, 1.0, v34
	v_add_f32_e32 v37, -1.0, v36
	v_sub_f32_e32 v35, v33, v35
	v_sub_f32_e32 v33, v33, v37
	v_add_f32_e32 v35, v32, v35
	v_add_f32_e32 v32, v32, v33
	v_add_f32_e32 v41, v36, v32
	v_rcp_f32_e32 v43, v41
	v_sub_f32_e32 v33, v36, v41
	v_add_f32_e32 v42, v32, v33
	v_add_f32_e32 v33, v34, v35
	v_mul_f32_e32 v45, v33, v43
	v_sub_f32_e32 v32, v34, v33
	v_mul_f32_e32 v34, v41, v45
	v_fma_f32 v36, v45, v41, -v34
	v_fmac_f32_e32 v36, v45, v42
	v_add_f32_e32 v44, v35, v32
	v_add_f32_e32 v32, v34, v36
	v_sub_f32_e32 v35, v33, v32
	v_pk_add_f32 v[38:39], v[32:33], v[34:35] neg_lo:[0,1] neg_hi:[0,1]
	v_mov_b32_e32 v37, v32
	v_pk_add_f32 v[32:33], v[38:39], v[36:37] neg_lo:[0,1] neg_hi:[0,1]
	v_cmp_neq_f32_e64 s[4:5], s74, v11
	v_add_f32_e32 v33, v44, v33
	v_add_f32_e32 v32, v32, v33
	v_add_f32_e32 v33, v35, v32
	v_mul_f32_e32 v44, v43, v33
	v_mul_f32_e32 v34, v41, v44
	v_fma_f32 v36, v44, v41, -v34
	v_fmac_f32_e32 v36, v44, v42
	v_sub_f32_e32 v35, v35, v33
	v_add_f32_e32 v41, v32, v35
	v_add_f32_e32 v32, v34, v36
	v_sub_f32_e32 v35, v33, v32
	v_pk_add_f32 v[38:39], v[32:33], v[34:35] neg_lo:[0,1] neg_hi:[0,1]
	v_mov_b32_e32 v37, v32
	v_pk_add_f32 v[32:33], v[38:39], v[36:37] neg_lo:[0,1] neg_hi:[0,1]
	s_nop 0
	v_add_f32_e32 v33, v41, v33
	v_add_f32_e32 v32, v32, v33
	v_add_f32_e32 v33, v45, v44
	v_add_f32_e32 v32, v35, v32
	v_sub_f32_e32 v34, v33, v45
	v_mul_f32_e32 v32, v43, v32
	v_sub_f32_e32 v34, v44, v34
	v_add_f32_e32 v34, v34, v32
	v_add_f32_e32 v36, v33, v34
	v_mul_f32_e32 v37, v36, v36
	v_fmamk_f32 v32, v37, 0x3e9b6dac, v219
	v_fmaak_f32 v167, v37, v32, 0x3f2aaada
	v_cvt_f32_i32_e32 v32, v40
	v_sub_f32_e32 v33, v36, v33
	v_sub_f32_e32 v33, v34, v33
	v_ldexp_f32 v38, v33, 1
	v_mul_f32_e32 v33, v36, v37
	v_ldexp_f32 v35, v36, 1
	v_pk_mul_f32 v[36:37], v[32:33], v[166:167]
	s_nop 0
	v_fma_f32 v34, v32, s76, -v36
	v_fmac_f32_e32 v34, 0xb102e308, v32
	v_pk_add_f32 v[32:33], v[36:37], v[34:35]
	s_nop 0
	v_sub_f32_e32 v35, v33, v35
	v_sub_f32_e32 v35, v37, v35
	v_add_f32_e32 v39, v38, v35
	v_mov_b32_e32 v38, v36
	v_pk_add_f32 v[36:37], v[32:33], v[36:37] neg_lo:[0,1] neg_hi:[0,1]
	v_pk_add_f32 v[40:41], v[32:33], v[38:39]
	v_mov_b32_e32 v35, v32
	v_mov_b32_e32 v37, v41
	v_pk_add_f32 v[42:43], v[34:35], v[36:37] neg_lo:[0,1] neg_hi:[0,1]
	v_pk_add_f32 v[34:35], v[34:35], v[36:37]
	v_mov_b32_e32 v38, v39
	v_pk_add_f32 v[36:37], v[34:35], v[32:33] op_sel:[1,0] op_sel_hi:[0,1] neg_lo:[0,1] neg_hi:[0,1]
	v_pk_add_f32 v[44:45], v[40:41], v[36:37] op_sel_hi:[1,0] neg_lo:[0,1] neg_hi:[0,1]
	v_mov_b32_e32 v40, v41
	v_mov_b32_e32 v41, v35
	v_pk_mov_b32 v[36:37], v[32:33], v[36:37] op_sel:[1,0]
	v_mov_b32_e32 v39, v32
	v_pk_add_f32 v[36:37], v[40:41], v[36:37] neg_lo:[0,1] neg_hi:[0,1]
	v_mov_b32_e32 v44, v42
	v_pk_add_f32 v[32:33], v[38:39], v[36:37] neg_lo:[0,1] neg_hi:[0,1]
	v_mov_b32_e32 v43, v35
	v_pk_add_f32 v[36:37], v[44:45], v[32:33]
	s_nop 0
	v_pk_add_f32 v[38:39], v[36:37], v[36:37] op_sel:[0,1] op_sel_hi:[1,0]
	s_nop 0
	v_pk_add_f32 v[34:35], v[34:35], v[38:39] op_sel:[1,0] op_sel_hi:[0,1]
	v_mov_b32_e32 v37, v34
	v_pk_add_f32 v[40:41], v[36:37], v[42:43] neg_lo:[0,1] neg_hi:[0,1]
	v_mov_b32_e32 v33, v38
	v_sub_f32_e32 v35, v36, v40
	v_pk_add_f32 v[32:33], v[32:33], v[40:41] neg_lo:[0,1] neg_hi:[0,1]
	v_sub_f32_e32 v35, v42, v35
	v_add_f32_e32 v32, v32, v35
	v_add_f32_e32 v32, v32, v33
	v_add_f32_e32 v32, v34, v32
	v_or_b32_e32 v34, 14, v10
	v_ashrrev_i32_e32 v35, 31, v34
	v_cndmask_b32_e64 v32, v222, v32, s[4:5]
	v_cmp_lt_f32_e64 s[4:5], |v11|, s77
	v_lshlrev_b64 v[34:35], 9, v[34:35]
	v_lshl_add_u64 v[34:35], v[6:7], 0, v[34:35]
	v_cndmask_b32_e64 v11, v32, v11, s[4:5]
	v_add_f32_e32 v32, v46, v11
	v_add_f32_e32 v11, v27, v110
	v_mul_f32_e64 v34, |v11|, s33
	v_fma_f32 v35, |v11|, s33, -v34
	v_rndne_f32_e32 v36, v34
	v_fma_f32 v35, |v11|, s71, v35
; __device__ __forceinline__ void phase_small(const Params& P, int l) {
;     ...
;         for (int i = 0; i < 32; ++i) { const int s = lane * 32 + i; const float xx = misc[(size_t)(b * 2048 + s) * 128 + 64 + h] + bias;
;             const float ls = -(fmaxf(-xx, 0.f) + log1pf(expf(-fabsf(xx)))); run += ls; loc[i] = run; }
	v_sub_f32_e32 v34, v34, v36
	v_add_f32_e32 v34, v34, v35
	v_exp_f32_e32 v34, v34
	v_cvt_i32_f32_e32 v35, v36
	v_cmp_ngt_f32_e64 s[4:5], |v11|, s72
	v_max_f32_e64 v33, -v11, 0
	v_ldexp_f32 v34, v34, v35
	v_cndmask_b32_e64 v34, 0, v34, s[4:5]
	v_cmp_nlt_f32_e64 s[4:5], |v11|, s73
	s_nop 1
	v_cndmask_b32_e64 v11, v222, v34, s[4:5]
	v_add_f32_e32 v36, 1.0, v11
	v_add_f32_e32 v34, -1.0, v36
	v_sub_f32_e32 v35, v34, v36
	v_add_f32_e32 v35, 1.0, v35
	v_sub_f32_e32 v34, v11, v34
	v_add_f32_e32 v37, v34, v35
	v_frexp_mant_f32_e32 v34, v36
	v_cmp_gt_f32_e64 s[4:5], s75, v34
	v_cvt_f64_f32_e32 v[34:35], v36
	v_frexp_exp_i32_f64_e32 v34, v[34:35]
	v_subbrev_co_u32_e64 v42, s[4:5], 0, v34, s[4:5]
	v_sub_u32_e32 v34, 0, v42
	v_ldexp_f32 v35, v36, v34
	v_add_f32_e32 v36, -1.0, v35
	v_add_f32_e32 v38, 1.0, v35
	v_ldexp_f32 v34, v37, v34
	v_add_f32_e32 v37, 1.0, v36
	v_add_f32_e32 v39, -1.0, v38
	v_sub_f32_e32 v37, v35, v37
	v_sub_f32_e32 v35, v35, v39
	v_add_f32_e32 v37, v34, v37
	v_add_f32_e32 v34, v34, v35
	v_add_f32_e32 v43, v38, v34
	v_rcp_f32_e32 v45, v43
	v_sub_f32_e32 v35, v38, v43
	v_add_f32_e32 v44, v34, v35
	v_add_f32_e32 v35, v36, v37
	v_mul_f32_e32 v47, v35, v45
	v_sub_f32_e32 v34, v36, v35
	v_mul_f32_e32 v36, v43, v47
	v_fma_f32 v38, v47, v43, -v36
	v_fmac_f32_e32 v38, v47, v44
	v_add_f32_e32 v46, v37, v34
	v_add_f32_e32 v34, v36, v38
	v_sub_f32_e32 v37, v35, v34
	v_pk_add_f32 v[40:41], v[34:35], v[36:37] neg_lo:[0,1] neg_hi:[0,1]
	v_mov_b32_e32 v39, v34
	v_pk_add_f32 v[34:35], v[40:41], v[38:39] neg_lo:[0,1] neg_hi:[0,1]
	v_cmp_neq_f32_e64 s[4:5], s74, v11
	v_add_f32_e32 v35, v46, v35
	v_add_f32_e32 v34, v34, v35
	v_add_f32_e32 v35, v37, v34
	v_mul_f32_e32 v46, v45, v35
	v_mul_f32_e32 v36, v43, v46
	v_fma_f32 v38, v46, v43, -v36
	v_fmac_f32_e32 v38, v46, v44
	v_sub_f32_e32 v37, v37, v35
	v_add_f32_e32 v43, v34, v37
	v_add_f32_e32 v34, v36, v38
	v_sub_f32_e32 v37, v35, v34
	v_pk_add_f32 v[40:41], v[34:35], v[36:37] neg_lo:[0,1] neg_hi:[0,1]
	v_mov_b32_e32 v39, v34
	v_pk_add_f32 v[34:35], v[40:41], v[38:39] neg_lo:[0,1] neg_hi:[0,1]
	s_nop 0
	v_add_f32_e32 v35, v43, v35
	v_add_f32_e32 v34, v34, v35
	v_add_f32_e32 v35, v47, v46
	v_add_f32_e32 v34, v37, v34
	v_sub_f32_e32 v36, v35, v47
	v_mul_f32_e32 v34, v45, v34
	v_sub_f32_e32 v36, v46, v36
	v_add_f32_e32 v36, v36, v34
	v_add_f32_e32 v38, v35, v36
	v_mul_f32_e32 v39, v38, v38
	v_fmamk_f32 v34, v39, 0x3e9b6dac, v219
	v_fmaak_f32 v167, v39, v34, 0x3f2aaada
	v_cvt_f32_i32_e32 v34, v42
	v_sub_f32_e32 v35, v38, v35
	v_sub_f32_e32 v35, v36, v35
	v_ldexp_f32 v40, v35, 1
	v_mul_f32_e32 v35, v38, v39
	v_ldexp_f32 v37, v38, 1
	v_pk_mul_f32 v[38:39], v[34:35], v[166:167]
	s_nop 0
	v_fma_f32 v36, v34, s76, -v38
	v_fmac_f32_e32 v36, 0xb102e308, v34
	v_pk_add_f32 v[34:35], v[38:39], v[36:37]
	s_nop 0
	v_sub_f32_e32 v37, v35, v37
	v_sub_f32_e32 v37, v39, v37
	v_add_f32_e32 v41, v40, v37
	v_mov_b32_e32 v40, v38
	v_pk_add_f32 v[38:39], v[34:35], v[38:39] neg_lo:[0,1] neg_hi:[0,1]
	v_pk_add_f32 v[42:43], v[34:35], v[40:41]
	v_mov_b32_e32 v37, v34
	v_mov_b32_e32 v39, v43
	v_pk_add_f32 v[44:45], v[36:37], v[38:39] neg_lo:[0,1] neg_hi:[0,1]
	v_pk_add_f32 v[36:37], v[36:37], v[38:39]
	v_mov_b32_e32 v40, v41
	v_pk_add_f32 v[38:39], v[36:37], v[34:35] op_sel:[1,0] op_sel_hi:[0,1] neg_lo:[0,1] neg_hi:[0,1]
	v_pk_add_f32 v[46:47], v[42:43], v[38:39] op_sel_hi:[1,0] neg_lo:[0,1] neg_hi:[0,1]
	v_mov_b32_e32 v42, v43
	v_mov_b32_e32 v43, v37
	v_pk_mov_b32 v[38:39], v[34:35], v[38:39] op_sel:[1,0]
	v_mov_b32_e32 v41, v34
	v_pk_add_f32 v[38:39], v[42:43], v[38:39] neg_lo:[0,1] neg_hi:[0,1]
	v_mov_b32_e32 v46, v44
	v_pk_add_f32 v[34:35], v[40:41], v[38:39] neg_lo:[0,1] neg_hi:[0,1]
	v_mov_b32_e32 v45, v37
	v_pk_add_f32 v[38:39], v[46:47], v[34:35]
	s_nop 0
	v_pk_add_f32 v[40:41], v[38:39], v[38:39] op_sel:[0,1] op_sel_hi:[1,0]
	s_nop 0
	v_pk_add_f32 v[36:37], v[36:37], v[40:41] op_sel:[1,0] op_sel_hi:[0,1]
	v_mov_b32_e32 v39, v36
	v_pk_add_f32 v[42:43], v[38:39], v[44:45] neg_lo:[0,1] neg_hi:[0,1]
	v_mov_b32_e32 v35, v40
	v_sub_f32_e32 v37, v38, v42
	v_pk_add_f32 v[34:35], v[34:35], v[42:43] neg_lo:[0,1] neg_hi:[0,1]
	v_sub_f32_e32 v37, v44, v37
	v_add_f32_e32 v34, v34, v37
	v_add_f32_e32 v34, v34, v35
	v_add_f32_e32 v34, v36, v34
	v_cndmask_b32_e64 v34, v222, v34, s[4:5]
	v_cmp_lt_f32_e64 s[4:5], |v11|, s77
	s_nop 1
	v_cndmask_b32_e64 v11, v34, v11, s[4:5]
	v_or_b32_e32 v34, 15, v10
	v_ashrrev_i32_e32 v35, 31, v34
	v_lshlrev_b64 v[34:35], 9, v[34:35]
	v_lshl_add_u64 v[34:35], v[6:7], 0, v[34:35]
	v_add_f32_e32 v33, v33, v11
	v_add_f32_e32 v11, v27, v111
	v_mul_f32_e64 v34, |v11|, s33
	v_fma_f32 v35, |v11|, s33, -v34
	v_rndne_f32_e32 v36, v34
	v_fma_f32 v35, |v11|, s71, v35
	v_sub_f32_e32 v34, v34, v36
	v_add_f32_e32 v34, v34, v35
	v_exp_f32_e32 v34, v34
	v_cvt_i32_f32_e32 v35, v36
	v_cmp_ngt_f32_e64 s[4:5], |v11|, s72
	v_max_f32_e64 v48, -v11, 0
	v_ldexp_f32 v34, v34, v35
	v_cndmask_b32_e64 v34, 0, v34, s[4:5]
	v_cmp_nlt_f32_e64 s[4:5], |v11|, s73
	s_nop 1
	v_cndmask_b32_e64 v11, v222, v34, s[4:5]
	v_add_f32_e32 v36, 1.0, v11
	v_add_f32_e32 v34, -1.0, v36
	v_sub_f32_e32 v35, v34, v36
	v_add_f32_e32 v35, 1.0, v35
	v_sub_f32_e32 v34, v11, v34
	v_add_f32_e32 v37, v34, v35
	v_frexp_mant_f32_e32 v34, v36
	v_cmp_gt_f32_e64 s[4:5], s75, v34
	v_cvt_f64_f32_e32 v[34:35], v36
	v_frexp_exp_i32_f64_e32 v34, v[34:35]
	v_subbrev_co_u32_e64 v42, s[4:5], 0, v34, s[4:5]
	v_sub_u32_e32 v34, 0, v42
	v_ldexp_f32 v35, v36, v34
	v_add_f32_e32 v36, -1.0, v35
	v_add_f32_e32 v38, 1.0, v35
	v_ldexp_f32 v34, v37, v34
	v_add_f32_e32 v37, 1.0, v36
	v_add_f32_e32 v39, -1.0, v38
	v_sub_f32_e32 v37, v35, v37
	v_sub_f32_e32 v35, v35, v39
; __device__ __forceinline__ void phase_small(const Params& P, int l) {
;     ...
;         for (int i = 0; i < 32; ++i) { const int s = lane * 32 + i; const float xx = misc[(size_t)(b * 2048 + s) * 128 + 64 + h] + bias;
;             const float ls = -(fmaxf(-xx, 0.f) + log1pf(expf(-fabsf(xx)))); run += ls; loc[i] = run; }
	v_add_f32_e32 v37, v34, v37
	v_add_f32_e32 v34, v34, v35
	v_add_f32_e32 v43, v38, v34
	v_rcp_f32_e32 v45, v43
	v_sub_f32_e32 v35, v38, v43
	v_add_f32_e32 v44, v34, v35
	v_add_f32_e32 v35, v36, v37
	v_mul_f32_e32 v47, v35, v45
	v_sub_f32_e32 v34, v36, v35
	v_mul_f32_e32 v36, v43, v47
	v_fma_f32 v38, v47, v43, -v36
	v_fmac_f32_e32 v38, v47, v44
	v_add_f32_e32 v46, v37, v34
	v_add_f32_e32 v34, v36, v38
	v_sub_f32_e32 v37, v35, v34
	v_pk_add_f32 v[40:41], v[34:35], v[36:37] neg_lo:[0,1] neg_hi:[0,1]
	v_mov_b32_e32 v39, v34
	v_pk_add_f32 v[34:35], v[40:41], v[38:39] neg_lo:[0,1] neg_hi:[0,1]
	v_cmp_neq_f32_e64 s[4:5], s74, v11
	v_add_f32_e32 v35, v46, v35
	v_add_f32_e32 v34, v34, v35
	v_add_f32_e32 v35, v37, v34
	v_mul_f32_e32 v46, v45, v35
	v_mul_f32_e32 v36, v43, v46
	v_fma_f32 v38, v46, v43, -v36
	v_fmac_f32_e32 v38, v46, v44
	v_sub_f32_e32 v37, v37, v35
	v_add_f32_e32 v43, v34, v37
	v_add_f32_e32 v34, v36, v38
	v_sub_f32_e32 v37, v35, v34
	v_pk_add_f32 v[40:41], v[34:35], v[36:37] neg_lo:[0,1] neg_hi:[0,1]
	v_mov_b32_e32 v39, v34
	v_pk_add_f32 v[34:35], v[40:41], v[38:39] neg_lo:[0,1] neg_hi:[0,1]
	s_nop 0
	v_add_f32_e32 v35, v43, v35
	v_add_f32_e32 v34, v34, v35
	v_add_f32_e32 v35, v47, v46
	v_add_f32_e32 v34, v37, v34
	v_sub_f32_e32 v36, v35, v47
	v_mul_f32_e32 v34, v45, v34
	v_sub_f32_e32 v36, v46, v36
	v_add_f32_e32 v36, v36, v34
	v_add_f32_e32 v38, v35, v36
	v_mul_f32_e32 v39, v38, v38
	v_fmamk_f32 v34, v39, 0x3e9b6dac, v219
	v_fmaak_f32 v167, v39, v34, 0x3f2aaada
	v_cvt_f32_i32_e32 v34, v42
	v_sub_f32_e32 v35, v38, v35
	v_sub_f32_e32 v35, v36, v35
	v_ldexp_f32 v40, v35, 1
	v_mul_f32_e32 v35, v38, v39
	v_ldexp_f32 v37, v38, 1
	v_pk_mul_f32 v[38:39], v[34:35], v[166:167]
	s_nop 0
	v_fma_f32 v36, v34, s76, -v38
	v_fmac_f32_e32 v36, 0xb102e308, v34
	v_pk_add_f32 v[34:35], v[38:39], v[36:37]
	s_nop 0
	v_sub_f32_e32 v37, v35, v37
	v_sub_f32_e32 v37, v39, v37
	v_add_f32_e32 v41, v40, v37
	v_mov_b32_e32 v40, v38
	v_pk_add_f32 v[38:39], v[34:35], v[38:39] neg_lo:[0,1] neg_hi:[0,1]
	v_pk_add_f32 v[42:43], v[34:35], v[40:41]
	v_mov_b32_e32 v37, v34
	v_mov_b32_e32 v39, v43
	v_pk_add_f32 v[44:45], v[36:37], v[38:39] neg_lo:[0,1] neg_hi:[0,1]
	v_pk_add_f32 v[36:37], v[36:37], v[38:39]
	v_mov_b32_e32 v40, v41
	v_pk_add_f32 v[38:39], v[36:37], v[34:35] op_sel:[1,0] op_sel_hi:[0,1] neg_lo:[0,1] neg_hi:[0,1]
	v_pk_add_f32 v[46:47], v[42:43], v[38:39] op_sel_hi:[1,0] neg_lo:[0,1] neg_hi:[0,1]
	v_mov_b32_e32 v42, v43
	v_mov_b32_e32 v43, v37
	v_pk_mov_b32 v[38:39], v[34:35], v[38:39] op_sel:[1,0]
	v_mov_b32_e32 v41, v34
	v_pk_add_f32 v[38:39], v[42:43], v[38:39] neg_lo:[0,1] neg_hi:[0,1]
	v_mov_b32_e32 v46, v44
	v_pk_add_f32 v[34:35], v[40:41], v[38:39] neg_lo:[0,1] neg_hi:[0,1]
	v_mov_b32_e32 v45, v37
	v_pk_add_f32 v[38:39], v[46:47], v[34:35]
	s_nop 0
	v_pk_add_f32 v[40:41], v[38:39], v[38:39] op_sel:[0,1] op_sel_hi:[1,0]
	s_nop 0
	v_pk_add_f32 v[36:37], v[36:37], v[40:41] op_sel:[1,0] op_sel_hi:[0,1]
	v_mov_b32_e32 v39, v36
	v_pk_add_f32 v[42:43], v[38:39], v[44:45] neg_lo:[0,1] neg_hi:[0,1]
	v_mov_b32_e32 v35, v40
	v_sub_f32_e32 v37, v38, v42
	v_pk_add_f32 v[34:35], v[34:35], v[42:43] neg_lo:[0,1] neg_hi:[0,1]
	v_sub_f32_e32 v37, v44, v37
	v_add_f32_e32 v34, v34, v37
	v_add_f32_e32 v34, v34, v35
	v_add_f32_e32 v34, v36, v34
	v_or_b32_e32 v36, 16, v10
	v_ashrrev_i32_e32 v37, 31, v36
	v_cndmask_b32_e64 v34, v222, v34, s[4:5]
	v_cmp_lt_f32_e64 s[4:5], |v11|, s77
	v_lshlrev_b64 v[36:37], 9, v[36:37]
	v_lshl_add_u64 v[36:37], v[6:7], 0, v[36:37]
	v_cndmask_b32_e64 v11, v34, v11, s[4:5]
	v_add_f32_e32 v34, v48, v11
	v_add_f32_e32 v11, v27, v112
	v_mul_f32_e64 v36, |v11|, s33
	v_fma_f32 v37, |v11|, s33, -v36
	v_rndne_f32_e32 v38, v36
	v_fma_f32 v37, |v11|, s71, v37
	v_sub_f32_e32 v36, v36, v38
	v_add_f32_e32 v36, v36, v37
	v_exp_f32_e32 v36, v36
	v_cvt_i32_f32_e32 v37, v38
	v_cmp_ngt_f32_e64 s[4:5], |v11|, s72
	v_max_f32_e64 v35, -v11, 0
	v_ldexp_f32 v36, v36, v37
	v_cndmask_b32_e64 v36, 0, v36, s[4:5]
	v_cmp_nlt_f32_e64 s[4:5], |v11|, s73
	s_nop 1
	v_cndmask_b32_e64 v11, v222, v36, s[4:5]
	v_add_f32_e32 v38, 1.0, v11
	v_add_f32_e32 v36, -1.0, v38
	v_sub_f32_e32 v37, v36, v38
	v_add_f32_e32 v37, 1.0, v37
	v_sub_f32_e32 v36, v11, v36
	v_add_f32_e32 v39, v36, v37
	v_frexp_mant_f32_e32 v36, v38
	v_cmp_gt_f32_e64 s[4:5], s75, v36
	v_cvt_f64_f32_e32 v[36:37], v38
	v_frexp_exp_i32_f64_e32 v36, v[36:37]
	v_subbrev_co_u32_e64 v44, s[4:5], 0, v36, s[4:5]
	v_sub_u32_e32 v36, 0, v44
	v_ldexp_f32 v37, v38, v36
	v_add_f32_e32 v38, -1.0, v37
	v_add_f32_e32 v40, 1.0, v37
	v_ldexp_f32 v36, v39, v36
	v_add_f32_e32 v39, 1.0, v38
	v_add_f32_e32 v41, -1.0, v40
	v_sub_f32_e32 v39, v37, v39
	v_sub_f32_e32 v37, v37, v41
	v_add_f32_e32 v39, v36, v39
	v_add_f32_e32 v36, v36, v37
	v_add_f32_e32 v45, v40, v36
	v_rcp_f32_e32 v47, v45
	v_sub_f32_e32 v37, v40, v45
	v_add_f32_e32 v46, v36, v37
	v_add_f32_e32 v37, v38, v39
	v_mul_f32_e32 v49, v37, v47
	v_sub_f32_e32 v36, v38, v37
	v_mul_f32_e32 v38, v45, v49
	v_fma_f32 v40, v49, v45, -v38
	v_fmac_f32_e32 v40, v49, v46
	v_add_f32_e32 v48, v39, v36
	v_add_f32_e32 v36, v38, v40
	v_sub_f32_e32 v39, v37, v36
	v_pk_add_f32 v[42:43], v[36:37], v[38:39] neg_lo:[0,1] neg_hi:[0,1]
	v_mov_b32_e32 v41, v36
	v_pk_add_f32 v[36:37], v[42:43], v[40:41] neg_lo:[0,1] neg_hi:[0,1]
	v_cmp_neq_f32_e64 s[4:5], s74, v11
	v_add_f32_e32 v37, v48, v37
	v_add_f32_e32 v36, v36, v37
	v_add_f32_e32 v37, v39, v36
	v_mul_f32_e32 v48, v47, v37
	v_mul_f32_e32 v38, v45, v48
	v_fma_f32 v40, v48, v45, -v38
	v_fmac_f32_e32 v40, v48, v46
	v_sub_f32_e32 v39, v39, v37
	v_add_f32_e32 v45, v36, v39
	v_add_f32_e32 v36, v38, v40
	v_sub_f32_e32 v39, v37, v36
; __device__ __forceinline__ void phase_small(const Params& P, int l) {
;     ...
;         for (int i = 0; i < 32; ++i) { const int s = lane * 32 + i; const float xx = misc[(size_t)(b * 2048 + s) * 128 + 64 + h] + bias;
;             const float ls = -(fmaxf(-xx, 0.f) + log1pf(expf(-fabsf(xx)))); run += ls; loc[i] = run; }
	v_pk_add_f32 v[42:43], v[36:37], v[38:39] neg_lo:[0,1] neg_hi:[0,1]
	v_mov_b32_e32 v41, v36
	v_pk_add_f32 v[36:37], v[42:43], v[40:41] neg_lo:[0,1] neg_hi:[0,1]
	s_nop 0
	v_add_f32_e32 v37, v45, v37
	v_add_f32_e32 v36, v36, v37
	v_add_f32_e32 v37, v49, v48
	v_add_f32_e32 v36, v39, v36
	v_sub_f32_e32 v38, v37, v49
	v_mul_f32_e32 v36, v47, v36
	v_sub_f32_e32 v38, v48, v38
	v_add_f32_e32 v38, v38, v36
	v_add_f32_e32 v40, v37, v38
	v_mul_f32_e32 v41, v40, v40
	v_fmamk_f32 v36, v41, 0x3e9b6dac, v219
	v_fmaak_f32 v167, v41, v36, 0x3f2aaada
	v_cvt_f32_i32_e32 v36, v44
	v_sub_f32_e32 v37, v40, v37
	v_sub_f32_e32 v37, v38, v37
	v_ldexp_f32 v42, v37, 1
	v_mul_f32_e32 v37, v40, v41
	v_ldexp_f32 v39, v40, 1
	v_pk_mul_f32 v[40:41], v[36:37], v[166:167]
	s_nop 0
	v_fma_f32 v38, v36, s76, -v40
	v_fmac_f32_e32 v38, 0xb102e308, v36
	v_pk_add_f32 v[36:37], v[40:41], v[38:39]
	s_nop 0
	v_sub_f32_e32 v39, v37, v39
	v_sub_f32_e32 v39, v41, v39
	v_add_f32_e32 v43, v42, v39
	v_mov_b32_e32 v42, v40
	v_pk_add_f32 v[40:41], v[36:37], v[40:41] neg_lo:[0,1] neg_hi:[0,1]
	v_pk_add_f32 v[44:45], v[36:37], v[42:43]
	v_mov_b32_e32 v39, v36
	v_mov_b32_e32 v41, v45
	v_pk_add_f32 v[46:47], v[38:39], v[40:41] neg_lo:[0,1] neg_hi:[0,1]
	v_pk_add_f32 v[38:39], v[38:39], v[40:41]
	v_mov_b32_e32 v42, v43
	v_pk_add_f32 v[40:41], v[38:39], v[36:37] op_sel:[1,0] op_sel_hi:[0,1] neg_lo:[0,1] neg_hi:[0,1]
	v_pk_add_f32 v[48:49], v[44:45], v[40:41] op_sel_hi:[1,0] neg_lo:[0,1] neg_hi:[0,1]
	v_mov_b32_e32 v44, v45
	v_mov_b32_e32 v45, v39
	v_pk_mov_b32 v[40:41], v[36:37], v[40:41] op_sel:[1,0]
	v_mov_b32_e32 v43, v36
	v_pk_add_f32 v[40:41], v[44:45], v[40:41] neg_lo:[0,1] neg_hi:[0,1]
	v_mov_b32_e32 v48, v46
	v_pk_add_f32 v[36:37], v[42:43], v[40:41] neg_lo:[0,1] neg_hi:[0,1]
	v_mov_b32_e32 v47, v39
	v_pk_add_f32 v[40:41], v[48:49], v[36:37]
	s_nop 0
	v_pk_add_f32 v[42:43], v[40:41], v[40:41] op_sel:[0,1] op_sel_hi:[1,0]
	s_nop 0
	v_pk_add_f32 v[38:39], v[38:39], v[42:43] op_sel:[1,0] op_sel_hi:[0,1]
	v_mov_b32_e32 v41, v38
	v_pk_add_f32 v[44:45], v[40:41], v[46:47] neg_lo:[0,1] neg_hi:[0,1]
	v_mov_b32_e32 v37, v42
	v_sub_f32_e32 v39, v40, v44
	v_pk_add_f32 v[36:37], v[36:37], v[44:45] neg_lo:[0,1] neg_hi:[0,1]
	v_sub_f32_e32 v39, v46, v39
	v_add_f32_e32 v36, v36, v39
	v_add_f32_e32 v36, v36, v37
	v_add_f32_e32 v36, v38, v36
	v_cndmask_b32_e64 v36, v222, v36, s[4:5]
	v_cmp_lt_f32_e64 s[4:5], |v11|, s77
	s_nop 1
	v_cndmask_b32_e64 v11, v36, v11, s[4:5]
	v_or_b32_e32 v36, 17, v10
	v_ashrrev_i32_e32 v37, 31, v36
	v_lshlrev_b64 v[36:37], 9, v[36:37]
	v_lshl_add_u64 v[36:37], v[6:7], 0, v[36:37]
	v_add_f32_e32 v35, v35, v11
	v_add_f32_e32 v11, v27, v113
	v_mul_f32_e64 v36, |v11|, s33
	v_fma_f32 v37, |v11|, s33, -v36
	v_rndne_f32_e32 v38, v36
	v_fma_f32 v37, |v11|, s71, v37
	v_sub_f32_e32 v36, v36, v38
	v_add_f32_e32 v36, v36, v37
	v_exp_f32_e32 v36, v36
	v_cvt_i32_f32_e32 v37, v38
	v_cmp_ngt_f32_e64 s[4:5], |v11|, s72
	v_max_f32_e64 v50, -v11, 0
	v_ldexp_f32 v36, v36, v37
	v_cndmask_b32_e64 v36, 0, v36, s[4:5]
	v_cmp_nlt_f32_e64 s[4:5], |v11|, s73
	s_nop 1
	v_cndmask_b32_e64 v11, v222, v36, s[4:5]
	v_add_f32_e32 v38, 1.0, v11
	v_add_f32_e32 v36, -1.0, v38
	v_sub_f32_e32 v37, v36, v38
	v_add_f32_e32 v37, 1.0, v37
	v_sub_f32_e32 v36, v11, v36
	v_add_f32_e32 v39, v36, v37
	v_frexp_mant_f32_e32 v36, v38
	v_cmp_gt_f32_e64 s[4:5], s75, v36
	v_cvt_f64_f32_e32 v[36:37], v38
	v_frexp_exp_i32_f64_e32 v36, v[36:37]
	v_subbrev_co_u32_e64 v44, s[4:5], 0, v36, s[4:5]
	v_sub_u32_e32 v36, 0, v44
	v_ldexp_f32 v37, v38, v36
	v_add_f32_e32 v38, -1.0, v37
	v_add_f32_e32 v40, 1.0, v37
	v_ldexp_f32 v36, v39, v36
	v_add_f32_e32 v39, 1.0, v38
	v_add_f32_e32 v41, -1.0, v40
	v_sub_f32_e32 v39, v37, v39
	v_sub_f32_e32 v37, v37, v41
	v_add_f32_e32 v39, v36, v39
	v_add_f32_e32 v36, v36, v37
	v_add_f32_e32 v45, v40, v36
	v_rcp_f32_e32 v47, v45
	v_sub_f32_e32 v37, v40, v45
	v_add_f32_e32 v46, v36, v37
	v_add_f32_e32 v37, v38, v39
	v_mul_f32_e32 v49, v37, v47
	v_sub_f32_e32 v36, v38, v37
	v_mul_f32_e32 v38, v45, v49
	v_fma_f32 v40, v49, v45, -v38
	v_fmac_f32_e32 v40, v49, v46
	v_add_f32_e32 v48, v39, v36
	v_add_f32_e32 v36, v38, v40
	v_sub_f32_e32 v39, v37, v36
	v_pk_add_f32 v[42:43], v[36:37], v[38:39] neg_lo:[0,1] neg_hi:[0,1]
	v_mov_b32_e32 v41, v36
	v_pk_add_f32 v[36:37], v[42:43], v[40:41] neg_lo:[0,1] neg_hi:[0,1]
	v_cmp_neq_f32_e64 s[4:5], s74, v11
	v_add_f32_e32 v37, v48, v37
	v_add_f32_e32 v36, v36, v37
	v_add_f32_e32 v37, v39, v36
	v_mul_f32_e32 v48, v47, v37
	v_mul_f32_e32 v38, v45, v48
	v_fma_f32 v40, v48, v45, -v38
	v_fmac_f32_e32 v40, v48, v46
	v_sub_f32_e32 v39, v39, v37
	v_add_f32_e32 v45, v36, v39
	v_add_f32_e32 v36, v38, v40
	v_sub_f32_e32 v39, v37, v36
	v_pk_add_f32 v[42:43], v[36:37], v[38:39] neg_lo:[0,1] neg_hi:[0,1]
	v_mov_b32_e32 v41, v36
	v_pk_add_f32 v[36:37], v[42:43], v[40:41] neg_lo:[0,1] neg_hi:[0,1]
	s_nop 0
	v_add_f32_e32 v37, v45, v37
	v_add_f32_e32 v36, v36, v37
	v_add_f32_e32 v37, v49, v48
	v_add_f32_e32 v36, v39, v36
	v_sub_f32_e32 v38, v37, v49
	v_mul_f32_e32 v36, v47, v36
	v_sub_f32_e32 v38, v48, v38
	v_add_f32_e32 v38, v38, v36
	v_add_f32_e32 v40, v37, v38
	v_mul_f32_e32 v41, v40, v40
	v_fmamk_f32 v36, v41, 0x3e9b6dac, v219
	v_fmaak_f32 v167, v41, v36, 0x3f2aaada
	v_cvt_f32_i32_e32 v36, v44
	v_sub_f32_e32 v37, v40, v37
	v_sub_f32_e32 v37, v38, v37
	v_ldexp_f32 v42, v37, 1
	v_mul_f32_e32 v37, v40, v41
	v_ldexp_f32 v39, v40, 1
	v_pk_mul_f32 v[40:41], v[36:37], v[166:167]
	s_nop 0
	v_fma_f32 v38, v36, s76, -v40
	v_fmac_f32_e32 v38, 0xb102e308, v36
	v_pk_add_f32 v[36:37], v[40:41], v[38:39]
	s_nop 0
	v_sub_f32_e32 v39, v37, v39
	v_sub_f32_e32 v39, v41, v39
	v_add_f32_e32 v43, v42, v39
; __device__ __forceinline__ void phase_small(const Params& P, int l) {
;     ...
;         for (int i = 0; i < 32; ++i) { const int s = lane * 32 + i; const float xx = misc[(size_t)(b * 2048 + s) * 128 + 64 + h] + bias;
;             const float ls = -(fmaxf(-xx, 0.f) + log1pf(expf(-fabsf(xx)))); run += ls; loc[i] = run; }
	v_mov_b32_e32 v42, v40
	v_pk_add_f32 v[40:41], v[36:37], v[40:41] neg_lo:[0,1] neg_hi:[0,1]
	v_pk_add_f32 v[44:45], v[36:37], v[42:43]
	v_mov_b32_e32 v39, v36
	v_mov_b32_e32 v41, v45
	v_pk_add_f32 v[46:47], v[38:39], v[40:41] neg_lo:[0,1] neg_hi:[0,1]
	v_pk_add_f32 v[38:39], v[38:39], v[40:41]
	v_mov_b32_e32 v42, v43
	v_pk_add_f32 v[40:41], v[38:39], v[36:37] op_sel:[1,0] op_sel_hi:[0,1] neg_lo:[0,1] neg_hi:[0,1]
	v_pk_add_f32 v[48:49], v[44:45], v[40:41] op_sel_hi:[1,0] neg_lo:[0,1] neg_hi:[0,1]
	v_mov_b32_e32 v44, v45
	v_mov_b32_e32 v45, v39
	v_pk_mov_b32 v[40:41], v[36:37], v[40:41] op_sel:[1,0]
	v_mov_b32_e32 v43, v36
	v_pk_add_f32 v[40:41], v[44:45], v[40:41] neg_lo:[0,1] neg_hi:[0,1]
	v_mov_b32_e32 v48, v46
	v_pk_add_f32 v[36:37], v[42:43], v[40:41] neg_lo:[0,1] neg_hi:[0,1]
	v_mov_b32_e32 v47, v39
	v_pk_add_f32 v[40:41], v[48:49], v[36:37]
	s_nop 0
	v_pk_add_f32 v[42:43], v[40:41], v[40:41] op_sel:[0,1] op_sel_hi:[1,0]
	s_nop 0
	v_pk_add_f32 v[38:39], v[38:39], v[42:43] op_sel:[1,0] op_sel_hi:[0,1]
	v_mov_b32_e32 v41, v38
	v_pk_add_f32 v[44:45], v[40:41], v[46:47] neg_lo:[0,1] neg_hi:[0,1]
	v_mov_b32_e32 v37, v42
	v_sub_f32_e32 v39, v40, v44
	v_pk_add_f32 v[36:37], v[36:37], v[44:45] neg_lo:[0,1] neg_hi:[0,1]
	v_sub_f32_e32 v39, v46, v39
	v_add_f32_e32 v36, v36, v39
	v_add_f32_e32 v36, v36, v37
	v_add_f32_e32 v36, v38, v36
	v_or_b32_e32 v38, 18, v10
	v_ashrrev_i32_e32 v39, 31, v38
	v_cndmask_b32_e64 v36, v222, v36, s[4:5]
	v_cmp_lt_f32_e64 s[4:5], |v11|, s77
	v_lshlrev_b64 v[38:39], 9, v[38:39]
	v_lshl_add_u64 v[38:39], v[6:7], 0, v[38:39]
	v_cndmask_b32_e64 v11, v36, v11, s[4:5]
	v_add_f32_e32 v36, v50, v11
	v_add_f32_e32 v11, v27, v114
	v_mul_f32_e64 v38, |v11|, s33
	v_fma_f32 v39, |v11|, s33, -v38
	v_rndne_f32_e32 v40, v38
	v_fma_f32 v39, |v11|, s71, v39
	v_sub_f32_e32 v38, v38, v40
	v_add_f32_e32 v38, v38, v39
	v_exp_f32_e32 v38, v38
	v_cvt_i32_f32_e32 v39, v40
	v_cmp_ngt_f32_e64 s[4:5], |v11|, s72
	v_max_f32_e64 v37, -v11, 0
	v_ldexp_f32 v38, v38, v39
	v_cndmask_b32_e64 v38, 0, v38, s[4:5]
	v_cmp_nlt_f32_e64 s[4:5], |v11|, s73
	s_nop 1
	v_cndmask_b32_e64 v11, v222, v38, s[4:5]
	v_add_f32_e32 v40, 1.0, v11
	v_add_f32_e32 v38, -1.0, v40
	v_sub_f32_e32 v39, v38, v40
	v_add_f32_e32 v39, 1.0, v39
	v_sub_f32_e32 v38, v11, v38
	v_add_f32_e32 v41, v38, v39
	v_frexp_mant_f32_e32 v38, v40
	v_cmp_gt_f32_e64 s[4:5], s75, v38
	v_cvt_f64_f32_e32 v[38:39], v40
	v_frexp_exp_i32_f64_e32 v38, v[38:39]
	v_subbrev_co_u32_e64 v46, s[4:5], 0, v38, s[4:5]
	v_sub_u32_e32 v38, 0, v46
	v_ldexp_f32 v39, v40, v38
	v_add_f32_e32 v40, -1.0, v39
	v_add_f32_e32 v42, 1.0, v39
	v_ldexp_f32 v38, v41, v38
	v_add_f32_e32 v41, 1.0, v40
	v_add_f32_e32 v43, -1.0, v42
	v_sub_f32_e32 v41, v39, v41
	v_sub_f32_e32 v39, v39, v43
	v_add_f32_e32 v41, v38, v41
	v_add_f32_e32 v38, v38, v39
	v_add_f32_e32 v47, v42, v38
	v_rcp_f32_e32 v49, v47
	v_sub_f32_e32 v39, v42, v47
	v_add_f32_e32 v48, v38, v39
	v_add_f32_e32 v39, v40, v41
	v_mul_f32_e32 v51, v39, v49
	v_sub_f32_e32 v38, v40, v39
	v_mul_f32_e32 v40, v47, v51
	v_fma_f32 v42, v51, v47, -v40
	v_fmac_f32_e32 v42, v51, v48
	v_add_f32_e32 v50, v41, v38
	v_add_f32_e32 v38, v40, v42
	v_sub_f32_e32 v41, v39, v38
	v_pk_add_f32 v[44:45], v[38:39], v[40:41] neg_lo:[0,1] neg_hi:[0,1]
	v_mov_b32_e32 v43, v38
	v_pk_add_f32 v[38:39], v[44:45], v[42:43] neg_lo:[0,1] neg_hi:[0,1]
	v_cmp_neq_f32_e64 s[4:5], s74, v11
	v_add_f32_e32 v39, v50, v39
	v_add_f32_e32 v38, v38, v39
	v_add_f32_e32 v39, v41, v38
	v_mul_f32_e32 v50, v49, v39
	v_mul_f32_e32 v40, v47, v50
	v_fma_f32 v42, v50, v47, -v40
	v_fmac_f32_e32 v42, v50, v48
	v_sub_f32_e32 v41, v41, v39
	v_add_f32_e32 v47, v38, v41
	v_add_f32_e32 v38, v40, v42
	v_sub_f32_e32 v41, v39, v38
	v_pk_add_f32 v[44:45], v[38:39], v[40:41] neg_lo:[0,1] neg_hi:[0,1]
	v_mov_b32_e32 v43, v38
	v_pk_add_f32 v[38:39], v[44:45], v[42:43] neg_lo:[0,1] neg_hi:[0,1]
	s_nop 0
	v_add_f32_e32 v39, v47, v39
	v_add_f32_e32 v38, v38, v39
	v_add_f32_e32 v39, v51, v50
	v_add_f32_e32 v38, v41, v38
	v_sub_f32_e32 v40, v39, v51
	v_mul_f32_e32 v38, v49, v38
	v_sub_f32_e32 v40, v50, v40
	v_add_f32_e32 v40, v40, v38
	v_add_f32_e32 v42, v39, v40
	v_mul_f32_e32 v43, v42, v42
	v_fmamk_f32 v38, v43, 0x3e9b6dac, v219
	v_fmaak_f32 v167, v43, v38, 0x3f2aaada
	v_cvt_f32_i32_e32 v38, v46
	v_sub_f32_e32 v39, v42, v39
	v_sub_f32_e32 v39, v40, v39
	v_ldexp_f32 v44, v39, 1
	v_mul_f32_e32 v39, v42, v43
	v_ldexp_f32 v41, v42, 1
	v_pk_mul_f32 v[42:43], v[38:39], v[166:167]
	s_nop 0
	v_fma_f32 v40, v38, s76, -v42
	v_fmac_f32_e32 v40, 0xb102e308, v38
	v_pk_add_f32 v[38:39], v[42:43], v[40:41]
	s_nop 0
	v_sub_f32_e32 v41, v39, v41
	v_sub_f32_e32 v41, v43, v41
	v_add_f32_e32 v45, v44, v41
	v_mov_b32_e32 v44, v42
	v_pk_add_f32 v[42:43], v[38:39], v[42:43] neg_lo:[0,1] neg_hi:[0,1]
	v_pk_add_f32 v[46:47], v[38:39], v[44:45]
	v_mov_b32_e32 v41, v38
	v_mov_b32_e32 v43, v47
	v_pk_add_f32 v[48:49], v[40:41], v[42:43] neg_lo:[0,1] neg_hi:[0,1]
	v_pk_add_f32 v[40:41], v[40:41], v[42:43]
	v_mov_b32_e32 v44, v45
	v_pk_add_f32 v[42:43], v[40:41], v[38:39] op_sel:[1,0] op_sel_hi:[0,1] neg_lo:[0,1] neg_hi:[0,1]
	v_pk_add_f32 v[50:51], v[46:47], v[42:43] op_sel_hi:[1,0] neg_lo:[0,1] neg_hi:[0,1]
	v_mov_b32_e32 v46, v47
	v_mov_b32_e32 v47, v41
	v_pk_mov_b32 v[42:43], v[38:39], v[42:43] op_sel:[1,0]
	v_mov_b32_e32 v45, v38
	v_pk_add_f32 v[42:43], v[46:47], v[42:43] neg_lo:[0,1] neg_hi:[0,1]
	v_mov_b32_e32 v50, v48
	v_pk_add_f32 v[38:39], v[44:45], v[42:43] neg_lo:[0,1] neg_hi:[0,1]
	v_mov_b32_e32 v49, v41
	v_pk_add_f32 v[42:43], v[50:51], v[38:39]
	s_nop 0
	v_pk_add_f32 v[44:45], v[42:43], v[42:43] op_sel:[0,1] op_sel_hi:[1,0]
	s_nop 0
; __device__ __forceinline__ void phase_small(const Params& P, int l) {
;     ...
;         for (int i = 0; i < 32; ++i) { const int s = lane * 32 + i; const float xx = misc[(size_t)(b * 2048 + s) * 128 + 64 + h] + bias;
;             const float ls = -(fmaxf(-xx, 0.f) + log1pf(expf(-fabsf(xx)))); run += ls; loc[i] = run; }
	v_pk_add_f32 v[40:41], v[40:41], v[44:45] op_sel:[1,0] op_sel_hi:[0,1]
	v_mov_b32_e32 v43, v40
	v_pk_add_f32 v[46:47], v[42:43], v[48:49] neg_lo:[0,1] neg_hi:[0,1]
	v_mov_b32_e32 v39, v44
	v_sub_f32_e32 v41, v42, v46
	v_pk_add_f32 v[38:39], v[38:39], v[46:47] neg_lo:[0,1] neg_hi:[0,1]
	v_sub_f32_e32 v41, v48, v41
	v_add_f32_e32 v38, v38, v41
	v_add_f32_e32 v38, v38, v39
	v_add_f32_e32 v38, v40, v38
	v_cndmask_b32_e64 v38, v222, v38, s[4:5]
	v_cmp_lt_f32_e64 s[4:5], |v11|, s77
	s_nop 1
	v_cndmask_b32_e64 v11, v38, v11, s[4:5]
	v_or_b32_e32 v38, 19, v10
	v_ashrrev_i32_e32 v39, 31, v38
	v_lshlrev_b64 v[38:39], 9, v[38:39]
	v_lshl_add_u64 v[38:39], v[6:7], 0, v[38:39]
	v_add_f32_e32 v37, v37, v11
	v_add_f32_e32 v11, v27, v115
	v_mul_f32_e64 v38, |v11|, s33
	v_fma_f32 v39, |v11|, s33, -v38
	v_rndne_f32_e32 v40, v38
	v_fma_f32 v39, |v11|, s71, v39
	v_sub_f32_e32 v38, v38, v40
	v_add_f32_e32 v38, v38, v39
	v_exp_f32_e32 v38, v38
	v_cvt_i32_f32_e32 v39, v40
	v_cmp_ngt_f32_e64 s[4:5], |v11|, s72
	v_max_f32_e64 v52, -v11, 0
	v_ldexp_f32 v38, v38, v39
	v_cndmask_b32_e64 v38, 0, v38, s[4:5]
	v_cmp_nlt_f32_e64 s[4:5], |v11|, s73
	s_nop 1
	v_cndmask_b32_e64 v11, v222, v38, s[4:5]
	v_add_f32_e32 v40, 1.0, v11
	v_add_f32_e32 v38, -1.0, v40
	v_sub_f32_e32 v39, v38, v40
	v_add_f32_e32 v39, 1.0, v39
	v_sub_f32_e32 v38, v11, v38
	v_add_f32_e32 v41, v38, v39
	v_frexp_mant_f32_e32 v38, v40
	v_cmp_gt_f32_e64 s[4:5], s75, v38
	v_cvt_f64_f32_e32 v[38:39], v40
	v_frexp_exp_i32_f64_e32 v38, v[38:39]
	v_subbrev_co_u32_e64 v46, s[4:5], 0, v38, s[4:5]
	v_sub_u32_e32 v38, 0, v46
	v_ldexp_f32 v39, v40, v38
	v_add_f32_e32 v40, -1.0, v39
	v_add_f32_e32 v42, 1.0, v39
	v_ldexp_f32 v38, v41, v38
	v_add_f32_e32 v41, 1.0, v40
	v_add_f32_e32 v43, -1.0, v42
	v_sub_f32_e32 v41, v39, v41
	v_sub_f32_e32 v39, v39, v43
	v_add_f32_e32 v41, v38, v41
	v_add_f32_e32 v38, v38, v39
	v_add_f32_e32 v47, v42, v38
	v_rcp_f32_e32 v49, v47
	v_sub_f32_e32 v39, v42, v47
	v_add_f32_e32 v48, v38, v39
	v_add_f32_e32 v39, v40, v41
	v_mul_f32_e32 v51, v39, v49
	v_sub_f32_e32 v38, v40, v39
	v_mul_f32_e32 v40, v47, v51
	v_fma_f32 v42, v51, v47, -v40
	v_fmac_f32_e32 v42, v51, v48
	v_add_f32_e32 v50, v41, v38
	v_add_f32_e32 v38, v40, v42
	v_sub_f32_e32 v41, v39, v38
	v_pk_add_f32 v[44:45], v[38:39], v[40:41] neg_lo:[0,1] neg_hi:[0,1]
	v_mov_b32_e32 v43, v38
	v_pk_add_f32 v[38:39], v[44:45], v[42:43] neg_lo:[0,1] neg_hi:[0,1]
	v_cmp_neq_f32_e64 s[4:5], s74, v11
	v_add_f32_e32 v39, v50, v39
	v_add_f32_e32 v38, v38, v39
	v_add_f32_e32 v39, v41, v38
	v_mul_f32_e32 v50, v49, v39
	v_mul_f32_e32 v40, v47, v50
	v_fma_f32 v42, v50, v47, -v40
	v_fmac_f32_e32 v42, v50, v48
	v_sub_f32_e32 v41, v41, v39
	v_add_f32_e32 v47, v38, v41
	v_add_f32_e32 v38, v40, v42
	v_sub_f32_e32 v41, v39, v38
	v_pk_add_f32 v[44:45], v[38:39], v[40:41] neg_lo:[0,1] neg_hi:[0,1]
	v_mov_b32_e32 v43, v38
	v_pk_add_f32 v[38:39], v[44:45], v[42:43] neg_lo:[0,1] neg_hi:[0,1]
	s_nop 0
	v_add_f32_e32 v39, v47, v39
	v_add_f32_e32 v38, v38, v39
	v_add_f32_e32 v39, v51, v50
	v_add_f32_e32 v38, v41, v38
	v_sub_f32_e32 v40, v39, v51
	v_mul_f32_e32 v38, v49, v38
	v_sub_f32_e32 v40, v50, v40
	v_add_f32_e32 v40, v40, v38
	v_add_f32_e32 v42, v39, v40
	v_mul_f32_e32 v43, v42, v42
	v_fmamk_f32 v38, v43, 0x3e9b6dac, v219
	v_fmaak_f32 v167, v43, v38, 0x3f2aaada
	v_cvt_f32_i32_e32 v38, v46
	v_sub_f32_e32 v39, v42, v39
	v_sub_f32_e32 v39, v40, v39
	v_ldexp_f32 v44, v39, 1
	v_mul_f32_e32 v39, v42, v43
	v_ldexp_f32 v41, v42, 1
	v_pk_mul_f32 v[42:43], v[38:39], v[166:167]
	s_nop 0
	v_fma_f32 v40, v38, s76, -v42
	v_fmac_f32_e32 v40, 0xb102e308, v38
	v_pk_add_f32 v[38:39], v[42:43], v[40:41]
	s_nop 0
	v_sub_f32_e32 v41, v39, v41
	v_sub_f32_e32 v41, v43, v41
	v_add_f32_e32 v45, v44, v41
	v_mov_b32_e32 v44, v42
	v_pk_add_f32 v[42:43], v[38:39], v[42:43] neg_lo:[0,1] neg_hi:[0,1]
	v_pk_add_f32 v[46:47], v[38:39], v[44:45]
	v_mov_b32_e32 v41, v38
	v_mov_b32_e32 v43, v47
	v_pk_add_f32 v[48:49], v[40:41], v[42:43] neg_lo:[0,1] neg_hi:[0,1]
	v_pk_add_f32 v[40:41], v[40:41], v[42:43]
	v_mov_b32_e32 v44, v45
	v_pk_add_f32 v[42:43], v[40:41], v[38:39] op_sel:[1,0] op_sel_hi:[0,1] neg_lo:[0,1] neg_hi:[0,1]
	v_pk_add_f32 v[50:51], v[46:47], v[42:43] op_sel_hi:[1,0] neg_lo:[0,1] neg_hi:[0,1]
	v_mov_b32_e32 v46, v47
	v_mov_b32_e32 v47, v41
	v_pk_mov_b32 v[42:43], v[38:39], v[42:43] op_sel:[1,0]
	v_mov_b32_e32 v45, v38
	v_pk_add_f32 v[42:43], v[46:47], v[42:43] neg_lo:[0,1] neg_hi:[0,1]
	v_mov_b32_e32 v50, v48
	v_pk_add_f32 v[38:39], v[44:45], v[42:43] neg_lo:[0,1] neg_hi:[0,1]
	v_mov_b32_e32 v49, v41
	v_pk_add_f32 v[42:43], v[50:51], v[38:39]
	s_nop 0
	v_pk_add_f32 v[44:45], v[42:43], v[42:43] op_sel:[0,1] op_sel_hi:[1,0]
	s_nop 0
	v_pk_add_f32 v[40:41], v[40:41], v[44:45] op_sel:[1,0] op_sel_hi:[0,1]
	v_mov_b32_e32 v43, v40
	v_pk_add_f32 v[46:47], v[42:43], v[48:49] neg_lo:[0,1] neg_hi:[0,1]
	v_mov_b32_e32 v39, v44
	v_sub_f32_e32 v41, v42, v46
	v_pk_add_f32 v[38:39], v[38:39], v[46:47] neg_lo:[0,1] neg_hi:[0,1]
	v_sub_f32_e32 v41, v48, v41
	v_add_f32_e32 v38, v38, v41
	v_add_f32_e32 v38, v38, v39
	v_add_f32_e32 v38, v40, v38
	v_or_b32_e32 v40, 20, v10
	v_ashrrev_i32_e32 v41, 31, v40
	v_cndmask_b32_e64 v38, v222, v38, s[4:5]
	v_cmp_lt_f32_e64 s[4:5], |v11|, s77
	v_lshlrev_b64 v[40:41], 9, v[40:41]
	v_lshl_add_u64 v[40:41], v[6:7], 0, v[40:41]
	v_cndmask_b32_e64 v11, v38, v11, s[4:5]
	v_add_f32_e32 v38, v52, v11
	v_add_f32_e32 v11, v27, v116
	v_mul_f32_e64 v40, |v11|, s33
	v_fma_f32 v41, |v11|, s33, -v40
	v_rndne_f32_e32 v42, v40
	v_fma_f32 v41, |v11|, s71, v41
	v_sub_f32_e32 v40, v40, v42
	v_add_f32_e32 v40, v40, v41
	v_exp_f32_e32 v40, v40
	v_cvt_i32_f32_e32 v41, v42
; __device__ __forceinline__ void phase_small(const Params& P, int l) {
;     ...
;         for (int i = 0; i < 32; ++i) { const int s = lane * 32 + i; const float xx = misc[(size_t)(b * 2048 + s) * 128 + 64 + h] + bias;
;             const float ls = -(fmaxf(-xx, 0.f) + log1pf(expf(-fabsf(xx)))); run += ls; loc[i] = run; }
	v_cmp_ngt_f32_e64 s[4:5], |v11|, s72
	v_max_f32_e64 v39, -v11, 0
	v_ldexp_f32 v40, v40, v41
	v_cndmask_b32_e64 v40, 0, v40, s[4:5]
	v_cmp_nlt_f32_e64 s[4:5], |v11|, s73
	s_nop 1
	v_cndmask_b32_e64 v11, v222, v40, s[4:5]
	v_add_f32_e32 v42, 1.0, v11
	v_add_f32_e32 v40, -1.0, v42
	v_sub_f32_e32 v41, v40, v42
	v_add_f32_e32 v41, 1.0, v41
	v_sub_f32_e32 v40, v11, v40
	v_add_f32_e32 v43, v40, v41
	v_frexp_mant_f32_e32 v40, v42
	v_cmp_gt_f32_e64 s[4:5], s75, v40
	v_cvt_f64_f32_e32 v[40:41], v42
	v_frexp_exp_i32_f64_e32 v40, v[40:41]
	v_subbrev_co_u32_e64 v48, s[4:5], 0, v40, s[4:5]
	v_sub_u32_e32 v40, 0, v48
	v_ldexp_f32 v41, v42, v40
	v_add_f32_e32 v42, -1.0, v41
	v_add_f32_e32 v44, 1.0, v41
	v_ldexp_f32 v40, v43, v40
	v_add_f32_e32 v43, 1.0, v42
	v_add_f32_e32 v45, -1.0, v44
	v_sub_f32_e32 v43, v41, v43
	v_sub_f32_e32 v41, v41, v45
	v_add_f32_e32 v43, v40, v43
	v_add_f32_e32 v40, v40, v41
	v_add_f32_e32 v49, v44, v40
	v_rcp_f32_e32 v51, v49
	v_sub_f32_e32 v41, v44, v49
	v_add_f32_e32 v50, v40, v41
	v_add_f32_e32 v41, v42, v43
	v_mul_f32_e32 v53, v41, v51
	v_sub_f32_e32 v40, v42, v41
	v_mul_f32_e32 v42, v49, v53
	v_fma_f32 v44, v53, v49, -v42
	v_fmac_f32_e32 v44, v53, v50
	v_add_f32_e32 v52, v43, v40
	v_add_f32_e32 v40, v42, v44
	v_sub_f32_e32 v43, v41, v40
	v_pk_add_f32 v[46:47], v[40:41], v[42:43] neg_lo:[0,1] neg_hi:[0,1]
	v_mov_b32_e32 v45, v40
	v_pk_add_f32 v[40:41], v[46:47], v[44:45] neg_lo:[0,1] neg_hi:[0,1]
	v_cmp_neq_f32_e64 s[4:5], s74, v11
	v_add_f32_e32 v41, v52, v41
	v_add_f32_e32 v40, v40, v41
	v_add_f32_e32 v41, v43, v40
	v_mul_f32_e32 v52, v51, v41
	v_mul_f32_e32 v42, v49, v52
	v_fma_f32 v44, v52, v49, -v42
	v_fmac_f32_e32 v44, v52, v50
	v_sub_f32_e32 v43, v43, v41
	v_add_f32_e32 v49, v40, v43
	v_add_f32_e32 v40, v42, v44
	v_sub_f32_e32 v43, v41, v40
	v_pk_add_f32 v[46:47], v[40:41], v[42:43] neg_lo:[0,1] neg_hi:[0,1]
	v_mov_b32_e32 v45, v40
	v_pk_add_f32 v[40:41], v[46:47], v[44:45] neg_lo:[0,1] neg_hi:[0,1]
	s_nop 0
	v_add_f32_e32 v41, v49, v41
	v_add_f32_e32 v40, v40, v41
	v_add_f32_e32 v41, v53, v52
	v_add_f32_e32 v40, v43, v40
	v_sub_f32_e32 v42, v41, v53
	v_mul_f32_e32 v40, v51, v40
	v_sub_f32_e32 v42, v52, v42
	v_add_f32_e32 v42, v42, v40
	v_add_f32_e32 v44, v41, v42
	v_mul_f32_e32 v45, v44, v44
	v_fmamk_f32 v40, v45, 0x3e9b6dac, v219
	v_fmaak_f32 v167, v45, v40, 0x3f2aaada
	v_cvt_f32_i32_e32 v40, v48
	v_sub_f32_e32 v41, v44, v41
	v_sub_f32_e32 v41, v42, v41
	v_ldexp_f32 v46, v41, 1
	v_mul_f32_e32 v41, v44, v45
	v_ldexp_f32 v43, v44, 1
	v_pk_mul_f32 v[44:45], v[40:41], v[166:167]
	s_nop 0
	v_fma_f32 v42, v40, s76, -v44
	v_fmac_f32_e32 v42, 0xb102e308, v40
	v_pk_add_f32 v[40:41], v[44:45], v[42:43]
	s_nop 0
	v_sub_f32_e32 v43, v41, v43
	v_sub_f32_e32 v43, v45, v43
	v_add_f32_e32 v47, v46, v43
	v_mov_b32_e32 v46, v44
	v_pk_add_f32 v[44:45], v[40:41], v[44:45] neg_lo:[0,1] neg_hi:[0,1]
	v_pk_add_f32 v[48:49], v[40:41], v[46:47]
	v_mov_b32_e32 v43, v40
	v_mov_b32_e32 v45, v49
	v_pk_add_f32 v[50:51], v[42:43], v[44:45] neg_lo:[0,1] neg_hi:[0,1]
	v_pk_add_f32 v[42:43], v[42:43], v[44:45]
	v_mov_b32_e32 v46, v47
	v_pk_add_f32 v[44:45], v[42:43], v[40:41] op_sel:[1,0] op_sel_hi:[0,1] neg_lo:[0,1] neg_hi:[0,1]
	v_pk_add_f32 v[52:53], v[48:49], v[44:45] op_sel_hi:[1,0] neg_lo:[0,1] neg_hi:[0,1]
	v_mov_b32_e32 v48, v49
	v_mov_b32_e32 v49, v43
	v_pk_mov_b32 v[44:45], v[40:41], v[44:45] op_sel:[1,0]
	v_mov_b32_e32 v47, v40
	v_pk_add_f32 v[44:45], v[48:49], v[44:45] neg_lo:[0,1] neg_hi:[0,1]
	v_mov_b32_e32 v52, v50
	v_pk_add_f32 v[40:41], v[46:47], v[44:45] neg_lo:[0,1] neg_hi:[0,1]
	v_mov_b32_e32 v51, v43
	v_pk_add_f32 v[44:45], v[52:53], v[40:41]
	s_nop 0
	v_pk_add_f32 v[46:47], v[44:45], v[44:45] op_sel:[0,1] op_sel_hi:[1,0]
	s_nop 0
	v_pk_add_f32 v[42:43], v[42:43], v[46:47] op_sel:[1,0] op_sel_hi:[0,1]
	v_mov_b32_e32 v45, v42
	v_pk_add_f32 v[48:49], v[44:45], v[50:51] neg_lo:[0,1] neg_hi:[0,1]
	v_mov_b32_e32 v41, v46
	v_sub_f32_e32 v43, v44, v48
	v_pk_add_f32 v[40:41], v[40:41], v[48:49] neg_lo:[0,1] neg_hi:[0,1]
	v_sub_f32_e32 v43, v50, v43
	v_add_f32_e32 v40, v40, v43
	v_add_f32_e32 v40, v40, v41
	v_add_f32_e32 v40, v42, v40
	v_cndmask_b32_e64 v40, v222, v40, s[4:5]
	v_cmp_lt_f32_e64 s[4:5], |v11|, s77
	s_nop 1
	v_cndmask_b32_e64 v11, v40, v11, s[4:5]
	v_or_b32_e32 v40, 21, v10
	v_ashrrev_i32_e32 v41, 31, v40
	v_lshlrev_b64 v[40:41], 9, v[40:41]
	v_lshl_add_u64 v[40:41], v[6:7], 0, v[40:41]
	v_add_f32_e32 v39, v39, v11
	v_add_f32_e32 v11, v27, v117
	v_mul_f32_e64 v40, |v11|, s33
	v_fma_f32 v41, |v11|, s33, -v40
	v_rndne_f32_e32 v42, v40
	v_fma_f32 v41, |v11|, s71, v41
	v_sub_f32_e32 v40, v40, v42
	v_add_f32_e32 v40, v40, v41
	v_exp_f32_e32 v40, v40
	v_cvt_i32_f32_e32 v41, v42
	v_cmp_ngt_f32_e64 s[4:5], |v11|, s72
	v_max_f32_e64 v54, -v11, 0
	v_ldexp_f32 v40, v40, v41
	v_cndmask_b32_e64 v40, 0, v40, s[4:5]
	v_cmp_nlt_f32_e64 s[4:5], |v11|, s73
	s_nop 1
	v_cndmask_b32_e64 v11, v222, v40, s[4:5]
	v_add_f32_e32 v42, 1.0, v11
	v_add_f32_e32 v40, -1.0, v42
	v_sub_f32_e32 v41, v40, v42
	v_add_f32_e32 v41, 1.0, v41
	v_sub_f32_e32 v40, v11, v40
	v_add_f32_e32 v43, v40, v41
	v_frexp_mant_f32_e32 v40, v42
	v_cmp_gt_f32_e64 s[4:5], s75, v40
	v_cvt_f64_f32_e32 v[40:41], v42
	v_frexp_exp_i32_f64_e32 v40, v[40:41]
	v_subbrev_co_u32_e64 v48, s[4:5], 0, v40, s[4:5]
	v_sub_u32_e32 v40, 0, v48
	v_ldexp_f32 v41, v42, v40
	v_add_f32_e32 v42, -1.0, v41
	v_add_f32_e32 v44, 1.0, v41
	v_ldexp_f32 v40, v43, v40
	v_add_f32_e32 v43, 1.0, v42
	v_add_f32_e32 v45, -1.0, v44
	v_sub_f32_e32 v43, v41, v43
	v_sub_f32_e32 v41, v41, v45
	v_add_f32_e32 v43, v40, v43
	v_add_f32_e32 v40, v40, v41
	v_add_f32_e32 v49, v44, v40
	v_rcp_f32_e32 v51, v49
; __device__ __forceinline__ void phase_small(const Params& P, int l) {
;     ...
;         for (int i = 0; i < 32; ++i) { const int s = lane * 32 + i; const float xx = misc[(size_t)(b * 2048 + s) * 128 + 64 + h] + bias;
;             const float ls = -(fmaxf(-xx, 0.f) + log1pf(expf(-fabsf(xx)))); run += ls; loc[i] = run; }
	v_sub_f32_e32 v41, v44, v49
	v_add_f32_e32 v50, v40, v41
	v_add_f32_e32 v41, v42, v43
	v_mul_f32_e32 v53, v41, v51
	v_sub_f32_e32 v40, v42, v41
	v_mul_f32_e32 v42, v49, v53
	v_fma_f32 v44, v53, v49, -v42
	v_fmac_f32_e32 v44, v53, v50
	v_add_f32_e32 v52, v43, v40
	v_add_f32_e32 v40, v42, v44
	v_sub_f32_e32 v43, v41, v40
	v_pk_add_f32 v[46:47], v[40:41], v[42:43] neg_lo:[0,1] neg_hi:[0,1]
	v_mov_b32_e32 v45, v40
	v_pk_add_f32 v[40:41], v[46:47], v[44:45] neg_lo:[0,1] neg_hi:[0,1]
	v_cmp_neq_f32_e64 s[4:5], s74, v11
	v_add_f32_e32 v41, v52, v41
	v_add_f32_e32 v40, v40, v41
	v_add_f32_e32 v41, v43, v40
	v_mul_f32_e32 v52, v51, v41
	v_mul_f32_e32 v42, v49, v52
	v_fma_f32 v44, v52, v49, -v42
	v_fmac_f32_e32 v44, v52, v50
	v_sub_f32_e32 v43, v43, v41
	v_add_f32_e32 v49, v40, v43
	v_add_f32_e32 v40, v42, v44
	v_sub_f32_e32 v43, v41, v40
	v_pk_add_f32 v[46:47], v[40:41], v[42:43] neg_lo:[0,1] neg_hi:[0,1]
	v_mov_b32_e32 v45, v40
	v_pk_add_f32 v[40:41], v[46:47], v[44:45] neg_lo:[0,1] neg_hi:[0,1]
	s_nop 0
	v_add_f32_e32 v41, v49, v41
	v_add_f32_e32 v40, v40, v41
	v_add_f32_e32 v41, v53, v52
	v_add_f32_e32 v40, v43, v40
	v_sub_f32_e32 v42, v41, v53
	v_mul_f32_e32 v40, v51, v40
	v_sub_f32_e32 v42, v52, v42
	v_add_f32_e32 v42, v42, v40
	v_add_f32_e32 v44, v41, v42
	v_mul_f32_e32 v45, v44, v44
	v_fmamk_f32 v40, v45, 0x3e9b6dac, v219
	v_fmaak_f32 v167, v45, v40, 0x3f2aaada
	v_cvt_f32_i32_e32 v40, v48
	v_sub_f32_e32 v41, v44, v41
	v_sub_f32_e32 v41, v42, v41
	v_ldexp_f32 v46, v41, 1
	v_mul_f32_e32 v41, v44, v45
	v_ldexp_f32 v43, v44, 1
	v_pk_mul_f32 v[44:45], v[40:41], v[166:167]
	s_nop 0
	v_fma_f32 v42, v40, s76, -v44
	v_fmac_f32_e32 v42, 0xb102e308, v40
	v_pk_add_f32 v[40:41], v[44:45], v[42:43]
	s_nop 0
	v_sub_f32_e32 v43, v41, v43
	v_sub_f32_e32 v43, v45, v43
	v_add_f32_e32 v47, v46, v43
	v_mov_b32_e32 v46, v44
	v_pk_add_f32 v[44:45], v[40:41], v[44:45] neg_lo:[0,1] neg_hi:[0,1]
	v_pk_add_f32 v[48:49], v[40:41], v[46:47]
	v_mov_b32_e32 v43, v40
	v_mov_b32_e32 v45, v49
	v_pk_add_f32 v[50:51], v[42:43], v[44:45] neg_lo:[0,1] neg_hi:[0,1]
	v_pk_add_f32 v[42:43], v[42:43], v[44:45]
	v_mov_b32_e32 v46, v47
	v_pk_add_f32 v[44:45], v[42:43], v[40:41] op_sel:[1,0] op_sel_hi:[0,1] neg_lo:[0,1] neg_hi:[0,1]
	v_pk_add_f32 v[52:53], v[48:49], v[44:45] op_sel_hi:[1,0] neg_lo:[0,1] neg_hi:[0,1]
	v_mov_b32_e32 v48, v49
	v_mov_b32_e32 v49, v43
	v_pk_mov_b32 v[44:45], v[40:41], v[44:45] op_sel:[1,0]
	v_mov_b32_e32 v47, v40
	v_pk_add_f32 v[44:45], v[48:49], v[44:45] neg_lo:[0,1] neg_hi:[0,1]
	v_mov_b32_e32 v52, v50
	v_pk_add_f32 v[40:41], v[46:47], v[44:45] neg_lo:[0,1] neg_hi:[0,1]
	v_mov_b32_e32 v51, v43
	v_pk_add_f32 v[44:45], v[52:53], v[40:41]
	s_nop 0
	v_pk_add_f32 v[46:47], v[44:45], v[44:45] op_sel:[0,1] op_sel_hi:[1,0]
	s_nop 0
	v_pk_add_f32 v[42:43], v[42:43], v[46:47] op_sel:[1,0] op_sel_hi:[0,1]
	v_mov_b32_e32 v45, v42
	v_pk_add_f32 v[48:49], v[44:45], v[50:51] neg_lo:[0,1] neg_hi:[0,1]
	v_mov_b32_e32 v41, v46
	v_sub_f32_e32 v43, v44, v48
	v_pk_add_f32 v[40:41], v[40:41], v[48:49] neg_lo:[0,1] neg_hi:[0,1]
	v_sub_f32_e32 v43, v50, v43
	v_add_f32_e32 v40, v40, v43
	v_add_f32_e32 v40, v40, v41
	v_add_f32_e32 v40, v42, v40
	v_or_b32_e32 v42, 22, v10
	v_ashrrev_i32_e32 v43, 31, v42
	v_cndmask_b32_e64 v40, v222, v40, s[4:5]
	v_cmp_lt_f32_e64 s[4:5], |v11|, s77
	v_lshlrev_b64 v[42:43], 9, v[42:43]
	v_lshl_add_u64 v[42:43], v[6:7], 0, v[42:43]
	v_cndmask_b32_e64 v11, v40, v11, s[4:5]
	v_add_f32_e32 v40, v54, v11
	v_add_f32_e32 v11, v27, v118
	v_mul_f32_e64 v42, |v11|, s33
	v_fma_f32 v43, |v11|, s33, -v42
	v_rndne_f32_e32 v44, v42
	v_fma_f32 v43, |v11|, s71, v43
	v_sub_f32_e32 v42, v42, v44
	v_add_f32_e32 v42, v42, v43
	v_exp_f32_e32 v42, v42
	v_cvt_i32_f32_e32 v43, v44
	v_cmp_ngt_f32_e64 s[4:5], |v11|, s72
	v_max_f32_e64 v41, -v11, 0
	v_ldexp_f32 v42, v42, v43
	v_cndmask_b32_e64 v42, 0, v42, s[4:5]
	v_cmp_nlt_f32_e64 s[4:5], |v11|, s73
	s_nop 1
	v_cndmask_b32_e64 v11, v222, v42, s[4:5]
	v_add_f32_e32 v44, 1.0, v11
	v_add_f32_e32 v42, -1.0, v44
	v_sub_f32_e32 v43, v42, v44
	v_add_f32_e32 v43, 1.0, v43
	v_sub_f32_e32 v42, v11, v42
	v_add_f32_e32 v45, v42, v43
	v_frexp_mant_f32_e32 v42, v44
	v_cmp_gt_f32_e64 s[4:5], s75, v42
	v_cvt_f64_f32_e32 v[42:43], v44
	v_frexp_exp_i32_f64_e32 v42, v[42:43]
	v_subbrev_co_u32_e64 v50, s[4:5], 0, v42, s[4:5]
	v_sub_u32_e32 v42, 0, v50
	v_ldexp_f32 v43, v44, v42
	v_add_f32_e32 v44, -1.0, v43
	v_add_f32_e32 v46, 1.0, v43
	v_ldexp_f32 v42, v45, v42
	v_add_f32_e32 v45, 1.0, v44
	v_add_f32_e32 v47, -1.0, v46
	v_sub_f32_e32 v45, v43, v45
	v_sub_f32_e32 v43, v43, v47
	v_add_f32_e32 v45, v42, v45
	v_add_f32_e32 v42, v42, v43
	v_add_f32_e32 v51, v46, v42
	v_rcp_f32_e32 v53, v51
	v_sub_f32_e32 v43, v46, v51
	v_add_f32_e32 v52, v42, v43
	v_add_f32_e32 v43, v44, v45
	v_mul_f32_e32 v55, v43, v53
	v_sub_f32_e32 v42, v44, v43
	v_mul_f32_e32 v44, v51, v55
	v_fma_f32 v46, v55, v51, -v44
	v_fmac_f32_e32 v46, v55, v52
	v_add_f32_e32 v54, v45, v42
	v_add_f32_e32 v42, v44, v46
	v_sub_f32_e32 v45, v43, v42
	v_pk_add_f32 v[48:49], v[42:43], v[44:45] neg_lo:[0,1] neg_hi:[0,1]
	v_mov_b32_e32 v47, v42
	v_pk_add_f32 v[42:43], v[48:49], v[46:47] neg_lo:[0,1] neg_hi:[0,1]
	v_cmp_neq_f32_e64 s[4:5], s74, v11
	v_add_f32_e32 v43, v54, v43
	v_add_f32_e32 v42, v42, v43
	v_add_f32_e32 v43, v45, v42
	v_mul_f32_e32 v54, v53, v43
	v_mul_f32_e32 v44, v51, v54
	v_fma_f32 v46, v54, v51, -v44
	v_fmac_f32_e32 v46, v54, v52
	v_sub_f32_e32 v45, v45, v43
	v_add_f32_e32 v51, v42, v45
	v_add_f32_e32 v42, v44, v46
	v_sub_f32_e32 v45, v43, v42
	v_pk_add_f32 v[48:49], v[42:43], v[44:45] neg_lo:[0,1] neg_hi:[0,1]
	v_mov_b32_e32 v47, v42
	v_pk_add_f32 v[42:43], v[48:49], v[46:47] neg_lo:[0,1] neg_hi:[0,1]
; __device__ __forceinline__ void phase_small(const Params& P, int l) {
;     ...
;         for (int i = 0; i < 32; ++i) { const int s = lane * 32 + i; const float xx = misc[(size_t)(b * 2048 + s) * 128 + 64 + h] + bias;
;             const float ls = -(fmaxf(-xx, 0.f) + log1pf(expf(-fabsf(xx)))); run += ls; loc[i] = run; }
	s_nop 0
	v_add_f32_e32 v43, v51, v43
	v_add_f32_e32 v42, v42, v43
	v_add_f32_e32 v43, v55, v54
	v_add_f32_e32 v42, v45, v42
	v_sub_f32_e32 v44, v43, v55
	v_mul_f32_e32 v42, v53, v42
	v_sub_f32_e32 v44, v54, v44
	v_add_f32_e32 v44, v44, v42
	v_add_f32_e32 v46, v43, v44
	v_mul_f32_e32 v47, v46, v46
	v_fmamk_f32 v42, v47, 0x3e9b6dac, v219
	v_fmaak_f32 v167, v47, v42, 0x3f2aaada
	v_cvt_f32_i32_e32 v42, v50
	v_sub_f32_e32 v43, v46, v43
	v_sub_f32_e32 v43, v44, v43
	v_ldexp_f32 v48, v43, 1
	v_mul_f32_e32 v43, v46, v47
	v_ldexp_f32 v45, v46, 1
	v_pk_mul_f32 v[46:47], v[42:43], v[166:167]
	s_nop 0
	v_fma_f32 v44, v42, s76, -v46
	v_fmac_f32_e32 v44, 0xb102e308, v42
	v_pk_add_f32 v[42:43], v[46:47], v[44:45]
	s_nop 0
	v_sub_f32_e32 v45, v43, v45
	v_sub_f32_e32 v45, v47, v45
	v_add_f32_e32 v49, v48, v45
	v_mov_b32_e32 v48, v46
	v_pk_add_f32 v[46:47], v[42:43], v[46:47] neg_lo:[0,1] neg_hi:[0,1]
	v_pk_add_f32 v[50:51], v[42:43], v[48:49]
	v_mov_b32_e32 v45, v42
	v_mov_b32_e32 v47, v51
	v_pk_add_f32 v[52:53], v[44:45], v[46:47] neg_lo:[0,1] neg_hi:[0,1]
	v_pk_add_f32 v[44:45], v[44:45], v[46:47]
	v_mov_b32_e32 v48, v49
	v_pk_add_f32 v[46:47], v[44:45], v[42:43] op_sel:[1,0] op_sel_hi:[0,1] neg_lo:[0,1] neg_hi:[0,1]
	v_pk_add_f32 v[54:55], v[50:51], v[46:47] op_sel_hi:[1,0] neg_lo:[0,1] neg_hi:[0,1]
	v_mov_b32_e32 v50, v51
	v_mov_b32_e32 v51, v45
	v_pk_mov_b32 v[46:47], v[42:43], v[46:47] op_sel:[1,0]
	v_mov_b32_e32 v49, v42
	v_pk_add_f32 v[46:47], v[50:51], v[46:47] neg_lo:[0,1] neg_hi:[0,1]
	v_mov_b32_e32 v54, v52
	v_pk_add_f32 v[42:43], v[48:49], v[46:47] neg_lo:[0,1] neg_hi:[0,1]
	v_mov_b32_e32 v53, v45
	v_pk_add_f32 v[46:47], v[54:55], v[42:43]
	s_nop 0
	v_pk_add_f32 v[48:49], v[46:47], v[46:47] op_sel:[0,1] op_sel_hi:[1,0]
	s_nop 0
	v_pk_add_f32 v[44:45], v[44:45], v[48:49] op_sel:[1,0] op_sel_hi:[0,1]
	v_mov_b32_e32 v47, v44
	v_pk_add_f32 v[50:51], v[46:47], v[52:53] neg_lo:[0,1] neg_hi:[0,1]
	v_mov_b32_e32 v43, v48
	v_sub_f32_e32 v45, v46, v50
	v_pk_add_f32 v[42:43], v[42:43], v[50:51] neg_lo:[0,1] neg_hi:[0,1]
	v_sub_f32_e32 v45, v52, v45
	v_add_f32_e32 v42, v42, v45
	v_add_f32_e32 v42, v42, v43
	v_add_f32_e32 v42, v44, v42
	v_cndmask_b32_e64 v42, v222, v42, s[4:5]
	v_cmp_lt_f32_e64 s[4:5], |v11|, s77
	s_nop 1
	v_cndmask_b32_e64 v11, v42, v11, s[4:5]
	v_or_b32_e32 v42, 23, v10
	v_ashrrev_i32_e32 v43, 31, v42
	v_lshlrev_b64 v[42:43], 9, v[42:43]
	v_lshl_add_u64 v[42:43], v[6:7], 0, v[42:43]
	v_add_f32_e32 v41, v41, v11
	v_add_f32_e32 v11, v27, v119
	v_mul_f32_e64 v42, |v11|, s33
	v_fma_f32 v43, |v11|, s33, -v42
	v_rndne_f32_e32 v44, v42
	v_fma_f32 v43, |v11|, s71, v43
	v_sub_f32_e32 v42, v42, v44
	v_add_f32_e32 v42, v42, v43
	v_exp_f32_e32 v42, v42
	v_cvt_i32_f32_e32 v43, v44
	v_cmp_ngt_f32_e64 s[4:5], |v11|, s72
	v_max_f32_e64 v56, -v11, 0
	v_ldexp_f32 v42, v42, v43
	v_cndmask_b32_e64 v42, 0, v42, s[4:5]
	v_cmp_nlt_f32_e64 s[4:5], |v11|, s73
	s_nop 1
	v_cndmask_b32_e64 v11, v222, v42, s[4:5]
	v_add_f32_e32 v44, 1.0, v11
	v_add_f32_e32 v42, -1.0, v44
	v_sub_f32_e32 v43, v42, v44
	v_add_f32_e32 v43, 1.0, v43
	v_sub_f32_e32 v42, v11, v42
	v_add_f32_e32 v45, v42, v43
	v_frexp_mant_f32_e32 v42, v44
	v_cmp_gt_f32_e64 s[4:5], s75, v42
	v_cvt_f64_f32_e32 v[42:43], v44
	v_frexp_exp_i32_f64_e32 v42, v[42:43]
	v_subbrev_co_u32_e64 v50, s[4:5], 0, v42, s[4:5]
	v_sub_u32_e32 v42, 0, v50
	v_ldexp_f32 v43, v44, v42
	v_add_f32_e32 v44, -1.0, v43
	v_add_f32_e32 v46, 1.0, v43
	v_ldexp_f32 v42, v45, v42
	v_add_f32_e32 v45, 1.0, v44
	v_add_f32_e32 v47, -1.0, v46
	v_sub_f32_e32 v45, v43, v45
	v_sub_f32_e32 v43, v43, v47
	v_add_f32_e32 v45, v42, v45
	v_add_f32_e32 v42, v42, v43
	v_add_f32_e32 v51, v46, v42
	v_rcp_f32_e32 v53, v51
	v_sub_f32_e32 v43, v46, v51
	v_add_f32_e32 v52, v42, v43
	v_add_f32_e32 v43, v44, v45
	v_mul_f32_e32 v55, v43, v53
	v_sub_f32_e32 v42, v44, v43
	v_mul_f32_e32 v44, v51, v55
	v_fma_f32 v46, v55, v51, -v44
	v_fmac_f32_e32 v46, v55, v52
	v_add_f32_e32 v54, v45, v42
	v_add_f32_e32 v42, v44, v46
	v_sub_f32_e32 v45, v43, v42
	v_pk_add_f32 v[48:49], v[42:43], v[44:45] neg_lo:[0,1] neg_hi:[0,1]
	v_mov_b32_e32 v47, v42
	v_pk_add_f32 v[42:43], v[48:49], v[46:47] neg_lo:[0,1] neg_hi:[0,1]
	v_cmp_neq_f32_e64 s[4:5], s74, v11
	v_add_f32_e32 v43, v54, v43
	v_add_f32_e32 v42, v42, v43
	v_add_f32_e32 v43, v45, v42
	v_mul_f32_e32 v54, v53, v43
	v_mul_f32_e32 v44, v51, v54
	v_fma_f32 v46, v54, v51, -v44
	v_fmac_f32_e32 v46, v54, v52
	v_sub_f32_e32 v45, v45, v43
	v_add_f32_e32 v51, v42, v45
	v_add_f32_e32 v42, v44, v46
	v_sub_f32_e32 v45, v43, v42
	v_pk_add_f32 v[48:49], v[42:43], v[44:45] neg_lo:[0,1] neg_hi:[0,1]
	v_mov_b32_e32 v47, v42
	v_pk_add_f32 v[42:43], v[48:49], v[46:47] neg_lo:[0,1] neg_hi:[0,1]
	s_nop 0
	v_add_f32_e32 v43, v51, v43
	v_add_f32_e32 v42, v42, v43
	v_add_f32_e32 v43, v55, v54
	v_add_f32_e32 v42, v45, v42
	v_sub_f32_e32 v44, v43, v55
	v_mul_f32_e32 v42, v53, v42
	v_sub_f32_e32 v44, v54, v44
	v_add_f32_e32 v44, v44, v42
	v_add_f32_e32 v46, v43, v44
	v_mul_f32_e32 v47, v46, v46
	v_fmamk_f32 v42, v47, 0x3e9b6dac, v219
	v_fmaak_f32 v167, v47, v42, 0x3f2aaada
	v_cvt_f32_i32_e32 v42, v50
	v_sub_f32_e32 v43, v46, v43
	v_sub_f32_e32 v43, v44, v43
	v_ldexp_f32 v48, v43, 1
	v_mul_f32_e32 v43, v46, v47
	v_ldexp_f32 v45, v46, 1
	v_pk_mul_f32 v[46:47], v[42:43], v[166:167]
	s_nop 0
	v_fma_f32 v44, v42, s76, -v46
	v_fmac_f32_e32 v44, 0xb102e308, v42
	v_pk_add_f32 v[42:43], v[46:47], v[44:45]
	s_nop 0
	v_sub_f32_e32 v45, v43, v45
	v_sub_f32_e32 v45, v47, v45
	v_add_f32_e32 v49, v48, v45
	v_mov_b32_e32 v48, v46
	v_pk_add_f32 v[46:47], v[42:43], v[46:47] neg_lo:[0,1] neg_hi:[0,1]
	v_pk_add_f32 v[50:51], v[42:43], v[48:49]
	v_mov_b32_e32 v45, v42
; __device__ __forceinline__ void phase_small(const Params& P, int l) {
;     ...
;         for (int i = 0; i < 32; ++i) { const int s = lane * 32 + i; const float xx = misc[(size_t)(b * 2048 + s) * 128 + 64 + h] + bias;
;             const float ls = -(fmaxf(-xx, 0.f) + log1pf(expf(-fabsf(xx)))); run += ls; loc[i] = run; }
	v_mov_b32_e32 v47, v51
	v_pk_add_f32 v[52:53], v[44:45], v[46:47] neg_lo:[0,1] neg_hi:[0,1]
	v_pk_add_f32 v[44:45], v[44:45], v[46:47]
	v_mov_b32_e32 v48, v49
	v_pk_add_f32 v[46:47], v[44:45], v[42:43] op_sel:[1,0] op_sel_hi:[0,1] neg_lo:[0,1] neg_hi:[0,1]
	v_pk_add_f32 v[54:55], v[50:51], v[46:47] op_sel_hi:[1,0] neg_lo:[0,1] neg_hi:[0,1]
	v_mov_b32_e32 v50, v51
	v_mov_b32_e32 v51, v45
	v_pk_mov_b32 v[46:47], v[42:43], v[46:47] op_sel:[1,0]
	v_mov_b32_e32 v49, v42
	v_pk_add_f32 v[46:47], v[50:51], v[46:47] neg_lo:[0,1] neg_hi:[0,1]
	v_mov_b32_e32 v54, v52
	v_pk_add_f32 v[42:43], v[48:49], v[46:47] neg_lo:[0,1] neg_hi:[0,1]
	v_mov_b32_e32 v53, v45
	v_pk_add_f32 v[46:47], v[54:55], v[42:43]
	s_nop 0
	v_pk_add_f32 v[48:49], v[46:47], v[46:47] op_sel:[0,1] op_sel_hi:[1,0]
	s_nop 0
	v_pk_add_f32 v[44:45], v[44:45], v[48:49] op_sel:[1,0] op_sel_hi:[0,1]
	v_mov_b32_e32 v47, v44
	v_pk_add_f32 v[50:51], v[46:47], v[52:53] neg_lo:[0,1] neg_hi:[0,1]
	v_mov_b32_e32 v43, v48
	v_sub_f32_e32 v45, v46, v50
	v_pk_add_f32 v[42:43], v[42:43], v[50:51] neg_lo:[0,1] neg_hi:[0,1]
	v_sub_f32_e32 v45, v52, v45
	v_add_f32_e32 v42, v42, v45
	v_add_f32_e32 v42, v42, v43
	v_add_f32_e32 v42, v44, v42
	v_or_b32_e32 v44, 24, v10
	v_ashrrev_i32_e32 v45, 31, v44
	v_cndmask_b32_e64 v42, v222, v42, s[4:5]
	v_cmp_lt_f32_e64 s[4:5], |v11|, s77
	v_lshlrev_b64 v[44:45], 9, v[44:45]
	v_lshl_add_u64 v[44:45], v[6:7], 0, v[44:45]
	v_cndmask_b32_e64 v11, v42, v11, s[4:5]
	v_add_f32_e32 v42, v56, v11
	v_add_f32_e32 v11, v27, v120
	v_mul_f32_e64 v44, |v11|, s33
	v_fma_f32 v45, |v11|, s33, -v44
	v_rndne_f32_e32 v46, v44
	v_fma_f32 v45, |v11|, s71, v45
	v_sub_f32_e32 v44, v44, v46
	v_add_f32_e32 v44, v44, v45
	v_exp_f32_e32 v44, v44
	v_cvt_i32_f32_e32 v45, v46
	v_cmp_ngt_f32_e64 s[4:5], |v11|, s72
	v_max_f32_e64 v43, -v11, 0
	v_ldexp_f32 v44, v44, v45
	v_cndmask_b32_e64 v44, 0, v44, s[4:5]
	v_cmp_nlt_f32_e64 s[4:5], |v11|, s73
	s_nop 1
	v_cndmask_b32_e64 v11, v222, v44, s[4:5]
	v_add_f32_e32 v46, 1.0, v11
	v_add_f32_e32 v44, -1.0, v46
	v_sub_f32_e32 v45, v44, v46
	v_add_f32_e32 v45, 1.0, v45
	v_sub_f32_e32 v44, v11, v44
	v_add_f32_e32 v47, v44, v45
	v_frexp_mant_f32_e32 v44, v46
	v_cmp_gt_f32_e64 s[4:5], s75, v44
	v_cvt_f64_f32_e32 v[44:45], v46
	v_frexp_exp_i32_f64_e32 v44, v[44:45]
	v_subbrev_co_u32_e64 v52, s[4:5], 0, v44, s[4:5]
	v_sub_u32_e32 v44, 0, v52
	v_ldexp_f32 v45, v46, v44
	v_add_f32_e32 v46, -1.0, v45
	v_add_f32_e32 v48, 1.0, v45
	v_ldexp_f32 v44, v47, v44
	v_add_f32_e32 v47, 1.0, v46
	v_add_f32_e32 v49, -1.0, v48
	v_sub_f32_e32 v47, v45, v47
	v_sub_f32_e32 v45, v45, v49
	v_add_f32_e32 v47, v44, v47
	v_add_f32_e32 v44, v44, v45
	v_add_f32_e32 v53, v48, v44
	v_rcp_f32_e32 v55, v53
	v_sub_f32_e32 v45, v48, v53
	v_add_f32_e32 v54, v44, v45
	v_add_f32_e32 v45, v46, v47
	v_mul_f32_e32 v57, v45, v55
	v_sub_f32_e32 v44, v46, v45
	v_mul_f32_e32 v46, v53, v57
	v_fma_f32 v48, v57, v53, -v46
	v_fmac_f32_e32 v48, v57, v54
	v_add_f32_e32 v56, v47, v44
	v_add_f32_e32 v44, v46, v48
	v_sub_f32_e32 v47, v45, v44
	v_pk_add_f32 v[50:51], v[44:45], v[46:47] neg_lo:[0,1] neg_hi:[0,1]
	v_mov_b32_e32 v49, v44
	v_pk_add_f32 v[44:45], v[50:51], v[48:49] neg_lo:[0,1] neg_hi:[0,1]
	v_cmp_neq_f32_e64 s[4:5], s74, v11
	v_add_f32_e32 v45, v56, v45
	v_add_f32_e32 v44, v44, v45
	v_add_f32_e32 v45, v47, v44
	v_mul_f32_e32 v56, v55, v45
	v_mul_f32_e32 v46, v53, v56
	v_fma_f32 v48, v56, v53, -v46
	v_fmac_f32_e32 v48, v56, v54
	v_sub_f32_e32 v47, v47, v45
	v_add_f32_e32 v53, v44, v47
	v_add_f32_e32 v44, v46, v48
	v_sub_f32_e32 v47, v45, v44
	v_pk_add_f32 v[50:51], v[44:45], v[46:47] neg_lo:[0,1] neg_hi:[0,1]
	v_mov_b32_e32 v49, v44
	v_pk_add_f32 v[44:45], v[50:51], v[48:49] neg_lo:[0,1] neg_hi:[0,1]
	s_nop 0
	v_add_f32_e32 v45, v53, v45
	v_add_f32_e32 v44, v44, v45
	v_add_f32_e32 v45, v57, v56
	v_add_f32_e32 v44, v47, v44
	v_sub_f32_e32 v46, v45, v57
	v_mul_f32_e32 v44, v55, v44
	v_sub_f32_e32 v46, v56, v46
	v_add_f32_e32 v46, v46, v44
	v_add_f32_e32 v48, v45, v46
	v_mul_f32_e32 v49, v48, v48
	v_fmamk_f32 v44, v49, 0x3e9b6dac, v219
	v_fmaak_f32 v167, v49, v44, 0x3f2aaada
	v_cvt_f32_i32_e32 v44, v52
	v_sub_f32_e32 v45, v48, v45
	v_sub_f32_e32 v45, v46, v45
	v_ldexp_f32 v50, v45, 1
	v_mul_f32_e32 v45, v48, v49
	v_ldexp_f32 v47, v48, 1
	v_pk_mul_f32 v[48:49], v[44:45], v[166:167]
	s_nop 0
	v_fma_f32 v46, v44, s76, -v48
	v_fmac_f32_e32 v46, 0xb102e308, v44
	v_pk_add_f32 v[44:45], v[48:49], v[46:47]
	s_nop 0
	v_sub_f32_e32 v47, v45, v47
	v_sub_f32_e32 v47, v49, v47
	v_add_f32_e32 v51, v50, v47
	v_mov_b32_e32 v50, v48
	v_pk_add_f32 v[48:49], v[44:45], v[48:49] neg_lo:[0,1] neg_hi:[0,1]
	v_pk_add_f32 v[52:53], v[44:45], v[50:51]
	v_mov_b32_e32 v47, v44
	v_mov_b32_e32 v49, v53
	v_pk_add_f32 v[54:55], v[46:47], v[48:49] neg_lo:[0,1] neg_hi:[0,1]
	v_pk_add_f32 v[46:47], v[46:47], v[48:49]
	v_mov_b32_e32 v50, v51
	v_pk_add_f32 v[48:49], v[46:47], v[44:45] op_sel:[1,0] op_sel_hi:[0,1] neg_lo:[0,1] neg_hi:[0,1]
	v_pk_add_f32 v[56:57], v[52:53], v[48:49] op_sel_hi:[1,0] neg_lo:[0,1] neg_hi:[0,1]
	v_mov_b32_e32 v52, v53
	v_mov_b32_e32 v53, v47
	v_pk_mov_b32 v[48:49], v[44:45], v[48:49] op_sel:[1,0]
	v_mov_b32_e32 v51, v44
	v_pk_add_f32 v[48:49], v[52:53], v[48:49] neg_lo:[0,1] neg_hi:[0,1]
	v_mov_b32_e32 v56, v54
	v_pk_add_f32 v[44:45], v[50:51], v[48:49] neg_lo:[0,1] neg_hi:[0,1]
	v_mov_b32_e32 v55, v47
	v_pk_add_f32 v[48:49], v[56:57], v[44:45]
	s_nop 0
	v_pk_add_f32 v[50:51], v[48:49], v[48:49] op_sel:[0,1] op_sel_hi:[1,0]
	s_nop 0
	v_pk_add_f32 v[46:47], v[46:47], v[50:51] op_sel:[1,0] op_sel_hi:[0,1]
	v_mov_b32_e32 v49, v46
	v_pk_add_f32 v[52:53], v[48:49], v[54:55] neg_lo:[0,1] neg_hi:[0,1]
	v_mov_b32_e32 v45, v50
; __device__ __forceinline__ void phase_small(const Params& P, int l) {
;     ...
;         for (int i = 0; i < 32; ++i) { const int s = lane * 32 + i; const float xx = misc[(size_t)(b * 2048 + s) * 128 + 64 + h] + bias;
;             const float ls = -(fmaxf(-xx, 0.f) + log1pf(expf(-fabsf(xx)))); run += ls; loc[i] = run; }
	v_sub_f32_e32 v47, v48, v52
	v_pk_add_f32 v[44:45], v[44:45], v[52:53] neg_lo:[0,1] neg_hi:[0,1]
	v_sub_f32_e32 v47, v54, v47
	v_add_f32_e32 v44, v44, v47
	v_add_f32_e32 v44, v44, v45
	v_add_f32_e32 v44, v46, v44
	v_cndmask_b32_e64 v44, v222, v44, s[4:5]
	v_cmp_lt_f32_e64 s[4:5], |v11|, s77
	s_nop 1
	v_cndmask_b32_e64 v11, v44, v11, s[4:5]
	v_or_b32_e32 v44, 25, v10
	v_ashrrev_i32_e32 v45, 31, v44
	v_lshlrev_b64 v[44:45], 9, v[44:45]
	v_lshl_add_u64 v[44:45], v[6:7], 0, v[44:45]
	v_add_f32_e32 v43, v43, v11
	v_add_f32_e32 v11, v27, v121
	v_mul_f32_e64 v44, |v11|, s33
	v_fma_f32 v45, |v11|, s33, -v44
	v_rndne_f32_e32 v46, v44
	v_fma_f32 v45, |v11|, s71, v45
	v_sub_f32_e32 v44, v44, v46
	v_add_f32_e32 v44, v44, v45
	v_exp_f32_e32 v44, v44
	v_cvt_i32_f32_e32 v45, v46
	v_cmp_ngt_f32_e64 s[4:5], |v11|, s72
	v_max_f32_e64 v58, -v11, 0
	v_ldexp_f32 v44, v44, v45
	v_cndmask_b32_e64 v44, 0, v44, s[4:5]
	v_cmp_nlt_f32_e64 s[4:5], |v11|, s73
	s_nop 1
	v_cndmask_b32_e64 v11, v222, v44, s[4:5]
	v_add_f32_e32 v46, 1.0, v11
	v_add_f32_e32 v44, -1.0, v46
	v_sub_f32_e32 v45, v44, v46
	v_add_f32_e32 v45, 1.0, v45
	v_sub_f32_e32 v44, v11, v44
	v_add_f32_e32 v47, v44, v45
	v_frexp_mant_f32_e32 v44, v46
	v_cmp_gt_f32_e64 s[4:5], s75, v44
	v_cvt_f64_f32_e32 v[44:45], v46
	v_frexp_exp_i32_f64_e32 v44, v[44:45]
	v_subbrev_co_u32_e64 v52, s[4:5], 0, v44, s[4:5]
	v_sub_u32_e32 v44, 0, v52
	v_ldexp_f32 v45, v46, v44
	v_add_f32_e32 v46, -1.0, v45
	v_add_f32_e32 v48, 1.0, v45
	v_ldexp_f32 v44, v47, v44
	v_add_f32_e32 v47, 1.0, v46
	v_add_f32_e32 v49, -1.0, v48
	v_sub_f32_e32 v47, v45, v47
	v_sub_f32_e32 v45, v45, v49
	v_add_f32_e32 v47, v44, v47
	v_add_f32_e32 v44, v44, v45
	v_add_f32_e32 v53, v48, v44
	v_rcp_f32_e32 v55, v53
	v_sub_f32_e32 v45, v48, v53
	v_add_f32_e32 v54, v44, v45
	v_add_f32_e32 v45, v46, v47
	v_mul_f32_e32 v57, v45, v55
	v_sub_f32_e32 v44, v46, v45
	v_mul_f32_e32 v46, v53, v57
	v_fma_f32 v48, v57, v53, -v46
	v_fmac_f32_e32 v48, v57, v54
	v_add_f32_e32 v56, v47, v44
	v_add_f32_e32 v44, v46, v48
	v_sub_f32_e32 v47, v45, v44
	v_pk_add_f32 v[50:51], v[44:45], v[46:47] neg_lo:[0,1] neg_hi:[0,1]
	v_mov_b32_e32 v49, v44
	v_pk_add_f32 v[44:45], v[50:51], v[48:49] neg_lo:[0,1] neg_hi:[0,1]
	v_cmp_neq_f32_e64 s[4:5], s74, v11
	v_add_f32_e32 v45, v56, v45
	v_add_f32_e32 v44, v44, v45
	v_add_f32_e32 v45, v47, v44
	v_mul_f32_e32 v56, v55, v45
	v_mul_f32_e32 v46, v53, v56
	v_fma_f32 v48, v56, v53, -v46
	v_fmac_f32_e32 v48, v56, v54
	v_sub_f32_e32 v47, v47, v45
	v_add_f32_e32 v53, v44, v47
	v_add_f32_e32 v44, v46, v48
	v_sub_f32_e32 v47, v45, v44
	v_pk_add_f32 v[50:51], v[44:45], v[46:47] neg_lo:[0,1] neg_hi:[0,1]
	v_mov_b32_e32 v49, v44
	v_pk_add_f32 v[44:45], v[50:51], v[48:49] neg_lo:[0,1] neg_hi:[0,1]
	s_nop 0
	v_add_f32_e32 v45, v53, v45
	v_add_f32_e32 v44, v44, v45
	v_add_f32_e32 v45, v57, v56
	v_add_f32_e32 v44, v47, v44
	v_sub_f32_e32 v46, v45, v57
	v_mul_f32_e32 v44, v55, v44
	v_sub_f32_e32 v46, v56, v46
	v_add_f32_e32 v46, v46, v44
	v_add_f32_e32 v48, v45, v46
	v_mul_f32_e32 v49, v48, v48
	v_fmamk_f32 v44, v49, 0x3e9b6dac, v219
	v_fmaak_f32 v167, v49, v44, 0x3f2aaada
	v_cvt_f32_i32_e32 v44, v52
	v_sub_f32_e32 v45, v48, v45
	v_sub_f32_e32 v45, v46, v45
	v_ldexp_f32 v50, v45, 1
	v_mul_f32_e32 v45, v48, v49
	v_ldexp_f32 v47, v48, 1
	v_pk_mul_f32 v[48:49], v[44:45], v[166:167]
	s_nop 0
	v_fma_f32 v46, v44, s76, -v48
	v_fmac_f32_e32 v46, 0xb102e308, v44
	v_pk_add_f32 v[44:45], v[48:49], v[46:47]
	s_nop 0
	v_sub_f32_e32 v47, v45, v47
	v_sub_f32_e32 v47, v49, v47
	v_add_f32_e32 v51, v50, v47
	v_mov_b32_e32 v50, v48
	v_pk_add_f32 v[48:49], v[44:45], v[48:49] neg_lo:[0,1] neg_hi:[0,1]
	v_pk_add_f32 v[52:53], v[44:45], v[50:51]
	v_mov_b32_e32 v47, v44
	v_mov_b32_e32 v49, v53
	v_pk_add_f32 v[54:55], v[46:47], v[48:49] neg_lo:[0,1] neg_hi:[0,1]
	v_pk_add_f32 v[46:47], v[46:47], v[48:49]
	v_mov_b32_e32 v50, v51
	v_pk_add_f32 v[48:49], v[46:47], v[44:45] op_sel:[1,0] op_sel_hi:[0,1] neg_lo:[0,1] neg_hi:[0,1]
	v_pk_add_f32 v[56:57], v[52:53], v[48:49] op_sel_hi:[1,0] neg_lo:[0,1] neg_hi:[0,1]
	v_mov_b32_e32 v52, v53
	v_mov_b32_e32 v53, v47
	v_pk_mov_b32 v[48:49], v[44:45], v[48:49] op_sel:[1,0]
	v_mov_b32_e32 v51, v44
	v_pk_add_f32 v[48:49], v[52:53], v[48:49] neg_lo:[0,1] neg_hi:[0,1]
	v_mov_b32_e32 v56, v54
	v_pk_add_f32 v[44:45], v[50:51], v[48:49] neg_lo:[0,1] neg_hi:[0,1]
	v_mov_b32_e32 v55, v47
	v_pk_add_f32 v[48:49], v[56:57], v[44:45]
	s_nop 0
	v_pk_add_f32 v[50:51], v[48:49], v[48:49] op_sel:[0,1] op_sel_hi:[1,0]
	s_nop 0
	v_pk_add_f32 v[46:47], v[46:47], v[50:51] op_sel:[1,0] op_sel_hi:[0,1]
	v_mov_b32_e32 v49, v46
	v_pk_add_f32 v[52:53], v[48:49], v[54:55] neg_lo:[0,1] neg_hi:[0,1]
	v_mov_b32_e32 v45, v50
	v_sub_f32_e32 v47, v48, v52
	v_pk_add_f32 v[44:45], v[44:45], v[52:53] neg_lo:[0,1] neg_hi:[0,1]
	v_sub_f32_e32 v47, v54, v47
	v_add_f32_e32 v44, v44, v47
	v_add_f32_e32 v44, v44, v45
	v_add_f32_e32 v44, v46, v44
	v_or_b32_e32 v46, 26, v10
	v_ashrrev_i32_e32 v47, 31, v46
	v_cndmask_b32_e64 v44, v222, v44, s[4:5]
	v_cmp_lt_f32_e64 s[4:5], |v11|, s77
	v_lshlrev_b64 v[46:47], 9, v[46:47]
	v_lshl_add_u64 v[46:47], v[6:7], 0, v[46:47]
	v_cndmask_b32_e64 v11, v44, v11, s[4:5]
	v_add_f32_e32 v44, v58, v11
	v_add_f32_e32 v11, v27, v122
	v_mul_f32_e64 v46, |v11|, s33
	v_fma_f32 v47, |v11|, s33, -v46
	v_rndne_f32_e32 v48, v46
	v_fma_f32 v47, |v11|, s71, v47
	v_sub_f32_e32 v46, v46, v48
	v_add_f32_e32 v46, v46, v47
	v_exp_f32_e32 v46, v46
	v_cvt_i32_f32_e32 v47, v48
	v_cmp_ngt_f32_e64 s[4:5], |v11|, s72
	v_max_f32_e64 v45, -v11, 0
	v_ldexp_f32 v46, v46, v47
	v_cndmask_b32_e64 v46, 0, v46, s[4:5]
	v_cmp_nlt_f32_e64 s[4:5], |v11|, s73
	s_nop 1
; __device__ __forceinline__ void phase_small(const Params& P, int l) {
;     ...
;         for (int i = 0; i < 32; ++i) { const int s = lane * 32 + i; const float xx = misc[(size_t)(b * 2048 + s) * 128 + 64 + h] + bias;
;             const float ls = -(fmaxf(-xx, 0.f) + log1pf(expf(-fabsf(xx)))); run += ls; loc[i] = run; }
	v_cndmask_b32_e64 v11, v222, v46, s[4:5]
	v_add_f32_e32 v48, 1.0, v11
	v_add_f32_e32 v46, -1.0, v48
	v_sub_f32_e32 v47, v46, v48
	v_add_f32_e32 v47, 1.0, v47
	v_sub_f32_e32 v46, v11, v46
	v_add_f32_e32 v49, v46, v47
	v_frexp_mant_f32_e32 v46, v48
	v_cmp_gt_f32_e64 s[4:5], s75, v46
	v_cvt_f64_f32_e32 v[46:47], v48
	v_frexp_exp_i32_f64_e32 v46, v[46:47]
	v_subbrev_co_u32_e64 v54, s[4:5], 0, v46, s[4:5]
	v_sub_u32_e32 v46, 0, v54
	v_ldexp_f32 v47, v48, v46
	v_add_f32_e32 v48, -1.0, v47
	v_add_f32_e32 v50, 1.0, v47
	v_ldexp_f32 v46, v49, v46
	v_add_f32_e32 v49, 1.0, v48
	v_add_f32_e32 v51, -1.0, v50
	v_sub_f32_e32 v49, v47, v49
	v_sub_f32_e32 v47, v47, v51
	v_add_f32_e32 v49, v46, v49
	v_add_f32_e32 v46, v46, v47
	v_add_f32_e32 v55, v50, v46
	v_rcp_f32_e32 v57, v55
	v_sub_f32_e32 v47, v50, v55
	v_add_f32_e32 v56, v46, v47
	v_add_f32_e32 v47, v48, v49
	v_mul_f32_e32 v59, v47, v57
	v_sub_f32_e32 v46, v48, v47
	v_mul_f32_e32 v48, v55, v59
	v_fma_f32 v50, v59, v55, -v48
	v_fmac_f32_e32 v50, v59, v56
	v_add_f32_e32 v58, v49, v46
	v_add_f32_e32 v46, v48, v50
	v_sub_f32_e32 v49, v47, v46
	v_pk_add_f32 v[52:53], v[46:47], v[48:49] neg_lo:[0,1] neg_hi:[0,1]
	v_mov_b32_e32 v51, v46
	v_pk_add_f32 v[46:47], v[52:53], v[50:51] neg_lo:[0,1] neg_hi:[0,1]
	v_cmp_neq_f32_e64 s[4:5], s74, v11
	v_add_f32_e32 v47, v58, v47
	v_add_f32_e32 v46, v46, v47
	v_add_f32_e32 v47, v49, v46
	v_mul_f32_e32 v58, v57, v47
	v_mul_f32_e32 v48, v55, v58
	v_fma_f32 v50, v58, v55, -v48
	v_fmac_f32_e32 v50, v58, v56
	v_sub_f32_e32 v49, v49, v47
	v_add_f32_e32 v55, v46, v49
	v_add_f32_e32 v46, v48, v50
	v_sub_f32_e32 v49, v47, v46
	v_pk_add_f32 v[52:53], v[46:47], v[48:49] neg_lo:[0,1] neg_hi:[0,1]
	v_mov_b32_e32 v51, v46
	v_pk_add_f32 v[46:47], v[52:53], v[50:51] neg_lo:[0,1] neg_hi:[0,1]
	s_nop 0
	v_add_f32_e32 v47, v55, v47
	v_add_f32_e32 v46, v46, v47
	v_add_f32_e32 v47, v59, v58
	v_add_f32_e32 v46, v49, v46
	v_sub_f32_e32 v48, v47, v59
	v_mul_f32_e32 v46, v57, v46
	v_sub_f32_e32 v48, v58, v48
	v_add_f32_e32 v48, v48, v46
	v_add_f32_e32 v50, v47, v48
	v_mul_f32_e32 v51, v50, v50
	v_fmamk_f32 v46, v51, 0x3e9b6dac, v219
	v_fmaak_f32 v167, v51, v46, 0x3f2aaada
	v_cvt_f32_i32_e32 v46, v54
	v_sub_f32_e32 v47, v50, v47
	v_sub_f32_e32 v47, v48, v47
	v_ldexp_f32 v52, v47, 1
	v_mul_f32_e32 v47, v50, v51
	v_ldexp_f32 v49, v50, 1
	v_pk_mul_f32 v[50:51], v[46:47], v[166:167]
	s_nop 0
	v_fma_f32 v48, v46, s76, -v50
	v_fmac_f32_e32 v48, 0xb102e308, v46
	v_pk_add_f32 v[46:47], v[50:51], v[48:49]
	s_nop 0
	v_sub_f32_e32 v49, v47, v49
	v_sub_f32_e32 v49, v51, v49
	v_add_f32_e32 v53, v52, v49
	v_mov_b32_e32 v52, v50
	v_pk_add_f32 v[50:51], v[46:47], v[50:51] neg_lo:[0,1] neg_hi:[0,1]
	v_pk_add_f32 v[54:55], v[46:47], v[52:53]
	v_mov_b32_e32 v49, v46
	v_mov_b32_e32 v51, v55
	v_pk_add_f32 v[56:57], v[48:49], v[50:51] neg_lo:[0,1] neg_hi:[0,1]
	v_pk_add_f32 v[48:49], v[48:49], v[50:51]
	v_mov_b32_e32 v52, v53
	v_pk_add_f32 v[50:51], v[48:49], v[46:47] op_sel:[1,0] op_sel_hi:[0,1] neg_lo:[0,1] neg_hi:[0,1]
	v_pk_add_f32 v[58:59], v[54:55], v[50:51] op_sel_hi:[1,0] neg_lo:[0,1] neg_hi:[0,1]
	v_mov_b32_e32 v54, v55
	v_mov_b32_e32 v55, v49
	v_pk_mov_b32 v[50:51], v[46:47], v[50:51] op_sel:[1,0]
	v_mov_b32_e32 v53, v46
	v_pk_add_f32 v[50:51], v[54:55], v[50:51] neg_lo:[0,1] neg_hi:[0,1]
	v_mov_b32_e32 v58, v56
	v_pk_add_f32 v[46:47], v[52:53], v[50:51] neg_lo:[0,1] neg_hi:[0,1]
	v_mov_b32_e32 v57, v49
	v_pk_add_f32 v[50:51], v[58:59], v[46:47]
	s_nop 0
	v_pk_add_f32 v[52:53], v[50:51], v[50:51] op_sel:[0,1] op_sel_hi:[1,0]
	s_nop 0
	v_pk_add_f32 v[48:49], v[48:49], v[52:53] op_sel:[1,0] op_sel_hi:[0,1]
	v_mov_b32_e32 v51, v48
	v_pk_add_f32 v[54:55], v[50:51], v[56:57] neg_lo:[0,1] neg_hi:[0,1]
	v_mov_b32_e32 v47, v52
	v_sub_f32_e32 v49, v50, v54
	v_pk_add_f32 v[46:47], v[46:47], v[54:55] neg_lo:[0,1] neg_hi:[0,1]
	v_sub_f32_e32 v49, v56, v49
	v_add_f32_e32 v46, v46, v49
	v_add_f32_e32 v46, v46, v47
	v_add_f32_e32 v46, v48, v46
	v_cndmask_b32_e64 v46, v222, v46, s[4:5]
	v_cmp_lt_f32_e64 s[4:5], |v11|, s77
	s_nop 1
	v_cndmask_b32_e64 v11, v46, v11, s[4:5]
	v_or_b32_e32 v46, 27, v10
	v_ashrrev_i32_e32 v47, 31, v46
	v_lshlrev_b64 v[46:47], 9, v[46:47]
	v_lshl_add_u64 v[46:47], v[6:7], 0, v[46:47]
	v_add_f32_e32 v45, v45, v11
	v_add_f32_e32 v11, v27, v123
	v_mul_f32_e64 v46, |v11|, s33
	v_fma_f32 v47, |v11|, s33, -v46
	v_rndne_f32_e32 v48, v46
	v_fma_f32 v47, |v11|, s71, v47
	v_sub_f32_e32 v46, v46, v48
	v_add_f32_e32 v46, v46, v47
	v_exp_f32_e32 v46, v46
	v_cvt_i32_f32_e32 v47, v48
	v_cmp_ngt_f32_e64 s[4:5], |v11|, s72
	v_max_f32_e64 v60, -v11, 0
	v_ldexp_f32 v46, v46, v47
	v_cndmask_b32_e64 v46, 0, v46, s[4:5]
	v_cmp_nlt_f32_e64 s[4:5], |v11|, s73
	s_nop 1
	v_cndmask_b32_e64 v11, v222, v46, s[4:5]
	v_add_f32_e32 v48, 1.0, v11
	v_add_f32_e32 v46, -1.0, v48
	v_sub_f32_e32 v47, v46, v48
	v_add_f32_e32 v47, 1.0, v47
	v_sub_f32_e32 v46, v11, v46
	v_add_f32_e32 v49, v46, v47
	v_frexp_mant_f32_e32 v46, v48
	v_cmp_gt_f32_e64 s[4:5], s75, v46
	v_cvt_f64_f32_e32 v[46:47], v48
	v_frexp_exp_i32_f64_e32 v46, v[46:47]
	v_subbrev_co_u32_e64 v54, s[4:5], 0, v46, s[4:5]
	v_sub_u32_e32 v46, 0, v54
	v_ldexp_f32 v47, v48, v46
	v_add_f32_e32 v48, -1.0, v47
	v_add_f32_e32 v50, 1.0, v47
	v_ldexp_f32 v46, v49, v46
	v_add_f32_e32 v49, 1.0, v48
	v_add_f32_e32 v51, -1.0, v50
	v_sub_f32_e32 v49, v47, v49
	v_sub_f32_e32 v47, v47, v51
	v_add_f32_e32 v49, v46, v49
	v_add_f32_e32 v46, v46, v47
	v_add_f32_e32 v55, v50, v46
	v_rcp_f32_e32 v57, v55
	v_sub_f32_e32 v47, v50, v55
	v_add_f32_e32 v56, v46, v47
	v_add_f32_e32 v47, v48, v49
	v_mul_f32_e32 v59, v47, v57
	v_sub_f32_e32 v46, v48, v47
	v_mul_f32_e32 v48, v55, v59
	v_fma_f32 v50, v59, v55, -v48
; __device__ __forceinline__ void phase_small(const Params& P, int l) {
;     ...
;         for (int i = 0; i < 32; ++i) { const int s = lane * 32 + i; const float xx = misc[(size_t)(b * 2048 + s) * 128 + 64 + h] + bias;
;             const float ls = -(fmaxf(-xx, 0.f) + log1pf(expf(-fabsf(xx)))); run += ls; loc[i] = run; }
	v_fmac_f32_e32 v50, v59, v56
	v_add_f32_e32 v58, v49, v46
	v_add_f32_e32 v46, v48, v50
	v_sub_f32_e32 v49, v47, v46
	v_pk_add_f32 v[52:53], v[46:47], v[48:49] neg_lo:[0,1] neg_hi:[0,1]
	v_mov_b32_e32 v51, v46
	v_pk_add_f32 v[46:47], v[52:53], v[50:51] neg_lo:[0,1] neg_hi:[0,1]
	v_cmp_neq_f32_e64 s[4:5], s74, v11
	v_add_f32_e32 v47, v58, v47
	v_add_f32_e32 v46, v46, v47
	v_add_f32_e32 v47, v49, v46
	v_mul_f32_e32 v58, v57, v47
	v_mul_f32_e32 v48, v55, v58
	v_fma_f32 v50, v58, v55, -v48
	v_fmac_f32_e32 v50, v58, v56
	v_sub_f32_e32 v49, v49, v47
	v_add_f32_e32 v55, v46, v49
	v_add_f32_e32 v46, v48, v50
	v_sub_f32_e32 v49, v47, v46
	v_pk_add_f32 v[52:53], v[46:47], v[48:49] neg_lo:[0,1] neg_hi:[0,1]
	v_mov_b32_e32 v51, v46
	v_pk_add_f32 v[46:47], v[52:53], v[50:51] neg_lo:[0,1] neg_hi:[0,1]
	s_nop 0
	v_add_f32_e32 v47, v55, v47
	v_add_f32_e32 v46, v46, v47
	v_add_f32_e32 v47, v59, v58
	v_add_f32_e32 v46, v49, v46
	v_sub_f32_e32 v48, v47, v59
	v_mul_f32_e32 v46, v57, v46
	v_sub_f32_e32 v48, v58, v48
	v_add_f32_e32 v48, v48, v46
	v_add_f32_e32 v50, v47, v48
	v_mul_f32_e32 v51, v50, v50
	v_fmamk_f32 v46, v51, 0x3e9b6dac, v219
	v_fmaak_f32 v167, v51, v46, 0x3f2aaada
	v_cvt_f32_i32_e32 v46, v54
	v_sub_f32_e32 v47, v50, v47
	v_sub_f32_e32 v47, v48, v47
	v_ldexp_f32 v52, v47, 1
	v_mul_f32_e32 v47, v50, v51
	v_ldexp_f32 v49, v50, 1
	v_pk_mul_f32 v[50:51], v[46:47], v[166:167]
	s_nop 0
	v_fma_f32 v48, v46, s76, -v50
	v_fmac_f32_e32 v48, 0xb102e308, v46
	v_pk_add_f32 v[46:47], v[50:51], v[48:49]
	s_nop 0
	v_sub_f32_e32 v49, v47, v49
	v_sub_f32_e32 v49, v51, v49
	v_add_f32_e32 v53, v52, v49
	v_mov_b32_e32 v52, v50
	v_pk_add_f32 v[50:51], v[46:47], v[50:51] neg_lo:[0,1] neg_hi:[0,1]
	v_pk_add_f32 v[54:55], v[46:47], v[52:53]
	v_mov_b32_e32 v49, v46
	v_mov_b32_e32 v51, v55
	v_pk_add_f32 v[56:57], v[48:49], v[50:51] neg_lo:[0,1] neg_hi:[0,1]
	v_pk_add_f32 v[48:49], v[48:49], v[50:51]
	v_mov_b32_e32 v52, v53
	v_pk_add_f32 v[50:51], v[48:49], v[46:47] op_sel:[1,0] op_sel_hi:[0,1] neg_lo:[0,1] neg_hi:[0,1]
	v_pk_add_f32 v[58:59], v[54:55], v[50:51] op_sel_hi:[1,0] neg_lo:[0,1] neg_hi:[0,1]
	v_mov_b32_e32 v54, v55
	v_mov_b32_e32 v55, v49
	v_pk_mov_b32 v[50:51], v[46:47], v[50:51] op_sel:[1,0]
	v_mov_b32_e32 v53, v46
	v_pk_add_f32 v[50:51], v[54:55], v[50:51] neg_lo:[0,1] neg_hi:[0,1]
	v_mov_b32_e32 v58, v56
	v_pk_add_f32 v[46:47], v[52:53], v[50:51] neg_lo:[0,1] neg_hi:[0,1]
	v_mov_b32_e32 v57, v49
	v_pk_add_f32 v[50:51], v[58:59], v[46:47]
	s_nop 0
	v_pk_add_f32 v[52:53], v[50:51], v[50:51] op_sel:[0,1] op_sel_hi:[1,0]
	s_nop 0
	v_pk_add_f32 v[48:49], v[48:49], v[52:53] op_sel:[1,0] op_sel_hi:[0,1]
	v_mov_b32_e32 v51, v48
	v_pk_add_f32 v[54:55], v[50:51], v[56:57] neg_lo:[0,1] neg_hi:[0,1]
	v_mov_b32_e32 v47, v52
	v_sub_f32_e32 v49, v50, v54
	v_pk_add_f32 v[46:47], v[46:47], v[54:55] neg_lo:[0,1] neg_hi:[0,1]
	v_sub_f32_e32 v49, v56, v49
	v_add_f32_e32 v46, v46, v49
	v_add_f32_e32 v46, v46, v47
	v_add_f32_e32 v46, v48, v46
	v_or_b32_e32 v48, 28, v10
	v_ashrrev_i32_e32 v49, 31, v48
	v_cndmask_b32_e64 v46, v222, v46, s[4:5]
	v_cmp_lt_f32_e64 s[4:5], |v11|, s77
	v_lshlrev_b64 v[48:49], 9, v[48:49]
	v_lshl_add_u64 v[48:49], v[6:7], 0, v[48:49]
	v_cndmask_b32_e64 v11, v46, v11, s[4:5]
	v_add_f32_e32 v46, v60, v11
	v_add_f32_e32 v11, v27, v124
	v_mul_f32_e64 v48, |v11|, s33
	v_fma_f32 v49, |v11|, s33, -v48
	v_rndne_f32_e32 v50, v48
	v_fma_f32 v49, |v11|, s71, v49
	v_sub_f32_e32 v48, v48, v50
	v_add_f32_e32 v48, v48, v49
	v_exp_f32_e32 v48, v48
	v_cvt_i32_f32_e32 v49, v50
	v_cmp_ngt_f32_e64 s[4:5], |v11|, s72
	v_max_f32_e64 v47, -v11, 0
	v_ldexp_f32 v48, v48, v49
	v_cndmask_b32_e64 v48, 0, v48, s[4:5]
	v_cmp_nlt_f32_e64 s[4:5], |v11|, s73
	s_nop 1
	v_cndmask_b32_e64 v11, v222, v48, s[4:5]
	v_add_f32_e32 v50, 1.0, v11
	v_add_f32_e32 v48, -1.0, v50
	v_sub_f32_e32 v49, v48, v50
	v_add_f32_e32 v49, 1.0, v49
	v_sub_f32_e32 v48, v11, v48
	v_add_f32_e32 v51, v48, v49
	v_frexp_mant_f32_e32 v48, v50
	v_cmp_gt_f32_e64 s[4:5], s75, v48
	v_cvt_f64_f32_e32 v[48:49], v50
	v_frexp_exp_i32_f64_e32 v48, v[48:49]
	v_subbrev_co_u32_e64 v56, s[4:5], 0, v48, s[4:5]
	v_sub_u32_e32 v48, 0, v56
	v_ldexp_f32 v49, v50, v48
	v_add_f32_e32 v50, -1.0, v49
	v_add_f32_e32 v52, 1.0, v49
	v_ldexp_f32 v48, v51, v48
	v_add_f32_e32 v51, 1.0, v50
	v_add_f32_e32 v53, -1.0, v52
	v_sub_f32_e32 v51, v49, v51
	v_sub_f32_e32 v49, v49, v53
	v_add_f32_e32 v51, v48, v51
	v_add_f32_e32 v48, v48, v49
	v_add_f32_e32 v57, v52, v48
	v_rcp_f32_e32 v59, v57
	v_sub_f32_e32 v49, v52, v57
	v_add_f32_e32 v58, v48, v49
	v_add_f32_e32 v49, v50, v51
	v_mul_f32_e32 v61, v49, v59
	v_sub_f32_e32 v48, v50, v49
	v_mul_f32_e32 v50, v57, v61
	v_fma_f32 v52, v61, v57, -v50
	v_fmac_f32_e32 v52, v61, v58
	v_add_f32_e32 v60, v51, v48
	v_add_f32_e32 v48, v50, v52
	v_sub_f32_e32 v51, v49, v48
	v_pk_add_f32 v[54:55], v[48:49], v[50:51] neg_lo:[0,1] neg_hi:[0,1]
	v_mov_b32_e32 v53, v48
	v_pk_add_f32 v[48:49], v[54:55], v[52:53] neg_lo:[0,1] neg_hi:[0,1]
	v_cmp_neq_f32_e64 s[4:5], s74, v11
	v_add_f32_e32 v49, v60, v49
	v_add_f32_e32 v48, v48, v49
	v_add_f32_e32 v49, v51, v48
	v_mul_f32_e32 v60, v59, v49
	v_mul_f32_e32 v50, v57, v60
	v_fma_f32 v52, v60, v57, -v50
	v_fmac_f32_e32 v52, v60, v58
	v_sub_f32_e32 v51, v51, v49
	v_add_f32_e32 v57, v48, v51
	v_add_f32_e32 v48, v50, v52
	v_sub_f32_e32 v51, v49, v48
	v_pk_add_f32 v[54:55], v[48:49], v[50:51] neg_lo:[0,1] neg_hi:[0,1]
	v_mov_b32_e32 v53, v48
	v_pk_add_f32 v[48:49], v[54:55], v[52:53] neg_lo:[0,1] neg_hi:[0,1]
	s_nop 0
	v_add_f32_e32 v49, v57, v49
	v_add_f32_e32 v48, v48, v49
	v_add_f32_e32 v49, v61, v60
	v_add_f32_e32 v48, v51, v48
	v_sub_f32_e32 v50, v49, v61
	v_mul_f32_e32 v48, v59, v48
; __device__ __forceinline__ void phase_small(const Params& P, int l) {
;     ...
;         for (int i = 0; i < 32; ++i) { const int s = lane * 32 + i; const float xx = misc[(size_t)(b * 2048 + s) * 128 + 64 + h] + bias;
;             const float ls = -(fmaxf(-xx, 0.f) + log1pf(expf(-fabsf(xx)))); run += ls; loc[i] = run; }
	v_sub_f32_e32 v50, v60, v50
	v_add_f32_e32 v50, v50, v48
	v_add_f32_e32 v52, v49, v50
	v_mul_f32_e32 v53, v52, v52
	v_fmamk_f32 v48, v53, 0x3e9b6dac, v219
	v_fmaak_f32 v167, v53, v48, 0x3f2aaada
	v_cvt_f32_i32_e32 v48, v56
	v_sub_f32_e32 v49, v52, v49
	v_sub_f32_e32 v49, v50, v49
	v_ldexp_f32 v54, v49, 1
	v_mul_f32_e32 v49, v52, v53
	v_ldexp_f32 v51, v52, 1
	v_pk_mul_f32 v[52:53], v[48:49], v[166:167]
	s_nop 0
	v_fma_f32 v50, v48, s76, -v52
	v_fmac_f32_e32 v50, 0xb102e308, v48
	v_pk_add_f32 v[48:49], v[52:53], v[50:51]
	s_nop 0
	v_sub_f32_e32 v51, v49, v51
	v_sub_f32_e32 v51, v53, v51
	v_add_f32_e32 v55, v54, v51
	v_mov_b32_e32 v54, v52
	v_pk_add_f32 v[52:53], v[48:49], v[52:53] neg_lo:[0,1] neg_hi:[0,1]
	v_pk_add_f32 v[56:57], v[48:49], v[54:55]
	v_mov_b32_e32 v51, v48
	v_mov_b32_e32 v53, v57
	v_pk_add_f32 v[58:59], v[50:51], v[52:53] neg_lo:[0,1] neg_hi:[0,1]
	v_pk_add_f32 v[50:51], v[50:51], v[52:53]
	v_mov_b32_e32 v54, v55
	v_pk_add_f32 v[52:53], v[50:51], v[48:49] op_sel:[1,0] op_sel_hi:[0,1] neg_lo:[0,1] neg_hi:[0,1]
	v_pk_add_f32 v[60:61], v[56:57], v[52:53] op_sel_hi:[1,0] neg_lo:[0,1] neg_hi:[0,1]
	v_mov_b32_e32 v56, v57
	v_mov_b32_e32 v57, v51
	v_pk_mov_b32 v[52:53], v[48:49], v[52:53] op_sel:[1,0]
	v_mov_b32_e32 v55, v48
	v_pk_add_f32 v[52:53], v[56:57], v[52:53] neg_lo:[0,1] neg_hi:[0,1]
	v_mov_b32_e32 v60, v58
	v_pk_add_f32 v[48:49], v[54:55], v[52:53] neg_lo:[0,1] neg_hi:[0,1]
	v_mov_b32_e32 v59, v51
	v_pk_add_f32 v[52:53], v[60:61], v[48:49]
	s_nop 0
	v_pk_add_f32 v[54:55], v[52:53], v[52:53] op_sel:[0,1] op_sel_hi:[1,0]
	s_nop 0
	v_pk_add_f32 v[50:51], v[50:51], v[54:55] op_sel:[1,0] op_sel_hi:[0,1]
	v_mov_b32_e32 v53, v50
	v_pk_add_f32 v[56:57], v[52:53], v[58:59] neg_lo:[0,1] neg_hi:[0,1]
	v_mov_b32_e32 v49, v54
	v_sub_f32_e32 v51, v52, v56
	v_pk_add_f32 v[48:49], v[48:49], v[56:57] neg_lo:[0,1] neg_hi:[0,1]
	v_sub_f32_e32 v51, v58, v51
	v_add_f32_e32 v48, v48, v51
	v_add_f32_e32 v48, v48, v49
	v_add_f32_e32 v48, v50, v48
	v_cndmask_b32_e64 v48, v222, v48, s[4:5]
	v_cmp_lt_f32_e64 s[4:5], |v11|, s77
	s_nop 1
	v_cndmask_b32_e64 v11, v48, v11, s[4:5]
	v_or_b32_e32 v48, 29, v10
	v_ashrrev_i32_e32 v49, 31, v48
	v_lshlrev_b64 v[48:49], 9, v[48:49]
	v_lshl_add_u64 v[48:49], v[6:7], 0, v[48:49]
	v_add_f32_e32 v47, v47, v11
	v_add_f32_e32 v11, v27, v125
	v_mul_f32_e64 v48, |v11|, s33
	v_fma_f32 v49, |v11|, s33, -v48
	v_rndne_f32_e32 v50, v48
	v_fma_f32 v49, |v11|, s71, v49
	v_sub_f32_e32 v48, v48, v50
	v_add_f32_e32 v48, v48, v49
	v_exp_f32_e32 v48, v48
	v_cvt_i32_f32_e32 v49, v50
	v_cmp_ngt_f32_e64 s[4:5], |v11|, s72
	v_max_f32_e64 v62, -v11, 0
	v_ldexp_f32 v48, v48, v49
	v_cndmask_b32_e64 v48, 0, v48, s[4:5]
	v_cmp_nlt_f32_e64 s[4:5], |v11|, s73
	s_nop 1
	v_cndmask_b32_e64 v11, v222, v48, s[4:5]
	v_add_f32_e32 v50, 1.0, v11
	v_add_f32_e32 v48, -1.0, v50
	v_sub_f32_e32 v49, v48, v50
	v_add_f32_e32 v49, 1.0, v49
	v_sub_f32_e32 v48, v11, v48
	v_add_f32_e32 v51, v48, v49
	v_frexp_mant_f32_e32 v48, v50
	v_cmp_gt_f32_e64 s[4:5], s75, v48
	v_cvt_f64_f32_e32 v[48:49], v50
	v_frexp_exp_i32_f64_e32 v48, v[48:49]
	v_subbrev_co_u32_e64 v56, s[4:5], 0, v48, s[4:5]
	v_sub_u32_e32 v48, 0, v56
	v_ldexp_f32 v49, v50, v48
	v_add_f32_e32 v50, -1.0, v49
	v_add_f32_e32 v52, 1.0, v49
	v_ldexp_f32 v48, v51, v48
	v_add_f32_e32 v51, 1.0, v50
	v_add_f32_e32 v53, -1.0, v52
	v_sub_f32_e32 v51, v49, v51
	v_sub_f32_e32 v49, v49, v53
	v_add_f32_e32 v51, v48, v51
	v_add_f32_e32 v48, v48, v49
	v_add_f32_e32 v57, v52, v48
	v_rcp_f32_e32 v59, v57
	v_sub_f32_e32 v49, v52, v57
	v_add_f32_e32 v58, v48, v49
	v_add_f32_e32 v49, v50, v51
	v_mul_f32_e32 v61, v49, v59
	v_sub_f32_e32 v48, v50, v49
	v_mul_f32_e32 v50, v57, v61
	v_fma_f32 v52, v61, v57, -v50
	v_fmac_f32_e32 v52, v61, v58
	v_add_f32_e32 v60, v51, v48
	v_add_f32_e32 v48, v50, v52
	v_sub_f32_e32 v51, v49, v48
	v_pk_add_f32 v[54:55], v[48:49], v[50:51] neg_lo:[0,1] neg_hi:[0,1]
	v_mov_b32_e32 v53, v48
	v_pk_add_f32 v[48:49], v[54:55], v[52:53] neg_lo:[0,1] neg_hi:[0,1]
	v_cmp_neq_f32_e64 s[4:5], s74, v11
	v_add_f32_e32 v49, v60, v49
	v_add_f32_e32 v48, v48, v49
	v_add_f32_e32 v49, v51, v48
	v_mul_f32_e32 v60, v59, v49
	v_mul_f32_e32 v50, v57, v60
	v_fma_f32 v52, v60, v57, -v50
	v_fmac_f32_e32 v52, v60, v58
	v_sub_f32_e32 v51, v51, v49
	v_add_f32_e32 v57, v48, v51
	v_add_f32_e32 v48, v50, v52
	v_sub_f32_e32 v51, v49, v48
	v_pk_add_f32 v[54:55], v[48:49], v[50:51] neg_lo:[0,1] neg_hi:[0,1]
	v_mov_b32_e32 v53, v48
	v_pk_add_f32 v[48:49], v[54:55], v[52:53] neg_lo:[0,1] neg_hi:[0,1]
	s_nop 0
	v_add_f32_e32 v49, v57, v49
	v_add_f32_e32 v48, v48, v49
	v_add_f32_e32 v49, v61, v60
	v_add_f32_e32 v48, v51, v48
	v_sub_f32_e32 v50, v49, v61
	v_mul_f32_e32 v48, v59, v48
	v_sub_f32_e32 v50, v60, v50
	v_add_f32_e32 v50, v50, v48
	v_add_f32_e32 v52, v49, v50
	v_mul_f32_e32 v53, v52, v52
	v_fmamk_f32 v48, v53, 0x3e9b6dac, v219
	v_fmaak_f32 v167, v53, v48, 0x3f2aaada
	v_cvt_f32_i32_e32 v48, v56
	v_sub_f32_e32 v49, v52, v49
	v_sub_f32_e32 v49, v50, v49
	v_ldexp_f32 v54, v49, 1
	v_mul_f32_e32 v49, v52, v53
	v_ldexp_f32 v51, v52, 1
	v_pk_mul_f32 v[52:53], v[48:49], v[166:167]
	s_nop 0
	v_fma_f32 v50, v48, s76, -v52
	v_fmac_f32_e32 v50, 0xb102e308, v48
	v_pk_add_f32 v[48:49], v[52:53], v[50:51]
	s_nop 0
	v_sub_f32_e32 v51, v49, v51
	v_sub_f32_e32 v51, v53, v51
	v_add_f32_e32 v55, v54, v51
	v_mov_b32_e32 v54, v52
	v_pk_add_f32 v[52:53], v[48:49], v[52:53] neg_lo:[0,1] neg_hi:[0,1]
	v_pk_add_f32 v[56:57], v[48:49], v[54:55]
	v_mov_b32_e32 v51, v48
	v_mov_b32_e32 v53, v57
	v_pk_add_f32 v[58:59], v[50:51], v[52:53] neg_lo:[0,1] neg_hi:[0,1]
	v_pk_add_f32 v[50:51], v[50:51], v[52:53]
	v_mov_b32_e32 v54, v55
; __device__ __forceinline__ void phase_small(const Params& P, int l) {
;     ...
;         for (int i = 0; i < 32; ++i) { const int s = lane * 32 + i; const float xx = misc[(size_t)(b * 2048 + s) * 128 + 64 + h] + bias;
;             const float ls = -(fmaxf(-xx, 0.f) + log1pf(expf(-fabsf(xx)))); run += ls; loc[i] = run; }
	v_pk_add_f32 v[52:53], v[50:51], v[48:49] op_sel:[1,0] op_sel_hi:[0,1] neg_lo:[0,1] neg_hi:[0,1]
	v_pk_add_f32 v[60:61], v[56:57], v[52:53] op_sel_hi:[1,0] neg_lo:[0,1] neg_hi:[0,1]
	v_mov_b32_e32 v56, v57
	v_mov_b32_e32 v57, v51
	v_pk_mov_b32 v[52:53], v[48:49], v[52:53] op_sel:[1,0]
	v_mov_b32_e32 v55, v48
	v_pk_add_f32 v[52:53], v[56:57], v[52:53] neg_lo:[0,1] neg_hi:[0,1]
	v_mov_b32_e32 v60, v58
	v_pk_add_f32 v[48:49], v[54:55], v[52:53] neg_lo:[0,1] neg_hi:[0,1]
	v_mov_b32_e32 v59, v51
	v_pk_add_f32 v[52:53], v[60:61], v[48:49]
	s_nop 0
	v_pk_add_f32 v[54:55], v[52:53], v[52:53] op_sel:[0,1] op_sel_hi:[1,0]
	s_nop 0
	v_pk_add_f32 v[50:51], v[50:51], v[54:55] op_sel:[1,0] op_sel_hi:[0,1]
	v_mov_b32_e32 v53, v50
	v_pk_add_f32 v[56:57], v[52:53], v[58:59] neg_lo:[0,1] neg_hi:[0,1]
	v_mov_b32_e32 v49, v54
	v_sub_f32_e32 v51, v52, v56
	v_pk_add_f32 v[48:49], v[48:49], v[56:57] neg_lo:[0,1] neg_hi:[0,1]
	v_sub_f32_e32 v51, v58, v51
	v_add_f32_e32 v48, v48, v51
	v_add_f32_e32 v48, v48, v49
	v_add_f32_e32 v48, v50, v48
	v_or_b32_e32 v50, 30, v10
	v_ashrrev_i32_e32 v51, 31, v50
	v_cndmask_b32_e64 v48, v222, v48, s[4:5]
	v_cmp_lt_f32_e64 s[4:5], |v11|, s77
	v_lshlrev_b64 v[50:51], 9, v[50:51]
	v_lshl_add_u64 v[50:51], v[6:7], 0, v[50:51]
	v_cndmask_b32_e64 v11, v48, v11, s[4:5]
	v_add_f32_e32 v48, v62, v11
	v_or_b32_e32 v10, 31, v10
	v_add_f32_e32 v11, v27, v126
	v_mul_f32_e64 v50, |v11|, s33
	v_fma_f32 v51, |v11|, s33, -v50
	v_rndne_f32_e32 v52, v50
	v_fma_f32 v51, |v11|, s71, v51
	v_sub_f32_e32 v50, v50, v52
	v_add_f32_e32 v50, v50, v51
	v_exp_f32_e32 v50, v50
	v_cvt_i32_f32_e32 v51, v52
	v_cmp_ngt_f32_e64 s[4:5], |v11|, s72
	v_max_f32_e64 v49, -v11, 0
	v_ldexp_f32 v50, v50, v51
	v_cndmask_b32_e64 v50, 0, v50, s[4:5]
	v_cmp_nlt_f32_e64 s[4:5], |v11|, s73
	s_nop 1
	v_cndmask_b32_e64 v11, v222, v50, s[4:5]
	v_add_f32_e32 v52, 1.0, v11
	v_add_f32_e32 v50, -1.0, v52
	v_sub_f32_e32 v51, v50, v52
	v_add_f32_e32 v51, 1.0, v51
	v_sub_f32_e32 v50, v11, v50
	v_add_f32_e32 v53, v50, v51
	v_frexp_mant_f32_e32 v50, v52
	v_cmp_gt_f32_e64 s[4:5], s75, v50
	v_cvt_f64_f32_e32 v[50:51], v52
	v_frexp_exp_i32_f64_e32 v50, v[50:51]
	v_subbrev_co_u32_e64 v58, s[4:5], 0, v50, s[4:5]
	v_sub_u32_e32 v50, 0, v58
	v_ldexp_f32 v51, v52, v50
	v_add_f32_e32 v52, -1.0, v51
	v_add_f32_e32 v54, 1.0, v51
	v_ldexp_f32 v50, v53, v50
	v_add_f32_e32 v53, 1.0, v52
	v_add_f32_e32 v55, -1.0, v54
	v_sub_f32_e32 v53, v51, v53
	v_sub_f32_e32 v51, v51, v55
	v_add_f32_e32 v53, v50, v53
	v_add_f32_e32 v50, v50, v51
	v_add_f32_e32 v59, v54, v50
	v_rcp_f32_e32 v61, v59
	v_sub_f32_e32 v51, v54, v59
	v_add_f32_e32 v60, v50, v51
	v_add_f32_e32 v51, v52, v53
	v_mul_f32_e32 v63, v51, v61
	v_sub_f32_e32 v50, v52, v51
	v_mul_f32_e32 v52, v59, v63
	v_fma_f32 v54, v63, v59, -v52
	v_fmac_f32_e32 v54, v63, v60
	v_add_f32_e32 v62, v53, v50
	v_add_f32_e32 v50, v52, v54
	v_sub_f32_e32 v53, v51, v50
	v_pk_add_f32 v[56:57], v[50:51], v[52:53] neg_lo:[0,1] neg_hi:[0,1]
	v_mov_b32_e32 v55, v50
	v_pk_add_f32 v[50:51], v[56:57], v[54:55] neg_lo:[0,1] neg_hi:[0,1]
	v_cmp_neq_f32_e64 s[4:5], s74, v11
	v_add_f32_e32 v51, v62, v51
	v_add_f32_e32 v50, v50, v51
	v_add_f32_e32 v51, v53, v50
	v_mul_f32_e32 v62, v61, v51
	v_mul_f32_e32 v52, v59, v62
	v_fma_f32 v54, v62, v59, -v52
	v_fmac_f32_e32 v54, v62, v60
	v_sub_f32_e32 v53, v53, v51
	v_add_f32_e32 v59, v50, v53
	v_add_f32_e32 v50, v52, v54
	v_sub_f32_e32 v53, v51, v50
	v_pk_add_f32 v[56:57], v[50:51], v[52:53] neg_lo:[0,1] neg_hi:[0,1]
	v_mov_b32_e32 v55, v50
	v_pk_add_f32 v[50:51], v[56:57], v[54:55] neg_lo:[0,1] neg_hi:[0,1]
	s_nop 0
	v_add_f32_e32 v51, v59, v51
	v_add_f32_e32 v50, v50, v51
	v_add_f32_e32 v51, v63, v62
	v_add_f32_e32 v50, v53, v50
	v_sub_f32_e32 v52, v51, v63
	v_mul_f32_e32 v50, v61, v50
	v_sub_f32_e32 v52, v62, v52
	v_add_f32_e32 v52, v52, v50
	v_add_f32_e32 v54, v51, v52
	v_mul_f32_e32 v55, v54, v54
	v_fmamk_f32 v50, v55, 0x3e9b6dac, v219
	v_fmaak_f32 v167, v55, v50, 0x3f2aaada
	v_cvt_f32_i32_e32 v50, v58
	v_sub_f32_e32 v51, v54, v51
	v_sub_f32_e32 v51, v52, v51
	v_ldexp_f32 v56, v51, 1
	v_mul_f32_e32 v51, v54, v55
	v_ldexp_f32 v53, v54, 1
	v_pk_mul_f32 v[54:55], v[50:51], v[166:167]
	s_nop 0
	v_fma_f32 v52, v50, s76, -v54
	v_fmac_f32_e32 v52, 0xb102e308, v50
	v_pk_add_f32 v[50:51], v[54:55], v[52:53]
	s_nop 0
	v_sub_f32_e32 v53, v51, v53
	v_sub_f32_e32 v53, v55, v53
	v_add_f32_e32 v57, v56, v53
	v_mov_b32_e32 v56, v54
	v_pk_add_f32 v[54:55], v[50:51], v[54:55] neg_lo:[0,1] neg_hi:[0,1]
	v_pk_add_f32 v[58:59], v[50:51], v[56:57]
	v_mov_b32_e32 v53, v50
	v_mov_b32_e32 v55, v59
	v_pk_add_f32 v[60:61], v[52:53], v[54:55] neg_lo:[0,1] neg_hi:[0,1]
	v_pk_add_f32 v[52:53], v[52:53], v[54:55]
	v_mov_b32_e32 v56, v57
	v_pk_add_f32 v[54:55], v[52:53], v[50:51] op_sel:[1,0] op_sel_hi:[0,1] neg_lo:[0,1] neg_hi:[0,1]
	v_pk_add_f32 v[62:63], v[58:59], v[54:55] op_sel_hi:[1,0] neg_lo:[0,1] neg_hi:[0,1]
	v_mov_b32_e32 v58, v59
	v_mov_b32_e32 v59, v53
	v_pk_mov_b32 v[54:55], v[50:51], v[54:55] op_sel:[1,0]
	v_mov_b32_e32 v57, v50
	v_pk_add_f32 v[54:55], v[58:59], v[54:55] neg_lo:[0,1] neg_hi:[0,1]
	v_mov_b32_e32 v62, v60
	v_pk_add_f32 v[50:51], v[56:57], v[54:55] neg_lo:[0,1] neg_hi:[0,1]
	v_mov_b32_e32 v61, v53
	v_pk_add_f32 v[54:55], v[62:63], v[50:51]
	s_nop 0
	v_pk_add_f32 v[56:57], v[54:55], v[54:55] op_sel:[0,1] op_sel_hi:[1,0]
	s_nop 0
	v_pk_add_f32 v[52:53], v[52:53], v[56:57] op_sel:[1,0] op_sel_hi:[0,1]
	v_mov_b32_e32 v55, v52
	v_pk_add_f32 v[58:59], v[54:55], v[60:61] neg_lo:[0,1] neg_hi:[0,1]
	v_mov_b32_e32 v51, v56
	v_sub_f32_e32 v53, v54, v58
	v_pk_add_f32 v[50:51], v[50:51], v[58:59] neg_lo:[0,1] neg_hi:[0,1]
	v_sub_f32_e32 v53, v60, v53
; __device__ __forceinline__ void phase_small(const Params& P, int l) {
;     ...
;         for (int i = 0; i < 32; ++i) { const int s = lane * 32 + i; const float xx = misc[(size_t)(b * 2048 + s) * 128 + 64 + h] + bias;
;             const float ls = -(fmaxf(-xx, 0.f) + log1pf(expf(-fabsf(xx)))); run += ls; loc[i] = run; }
;         float incl = run;
; #pragma unroll
;         for (int o = 1; o < 64; o <<= 1) { const float t = __shfl_up(incl, o); if (lane >= o) incl += t; }
	v_add_f32_e32 v50, v50, v53
	v_add_f32_e32 v50, v50, v51
	v_add_f32_e32 v50, v52, v50
	v_cndmask_b32_e64 v50, v222, v50, s[4:5]
	v_cmp_lt_f32_e64 s[4:5], |v11|, s77
	s_nop 1
	v_cndmask_b32_e64 v11, v50, v11, s[4:5]
	v_add_f32_e32 v49, v49, v11
	v_ashrrev_i32_e32 v11, 31, v10
	v_lshlrev_b64 v[10:11], 9, v[10:11]
	v_lshl_add_u64 v[10:11], v[6:7], 0, v[10:11]
	v_add_f32_e32 v10, v27, v127
	v_mul_f32_e64 v11, |v10|, s33
	v_fma_f32 v50, |v10|, s33, -v11
	v_rndne_f32_e32 v51, v11
	v_fma_f32 v50, |v10|, s71, v50
	v_sub_f32_e32 v11, v11, v51
	v_add_f32_e32 v11, v11, v50
	v_exp_f32_e32 v11, v11
	v_cvt_i32_f32_e32 v50, v51
	v_cmp_ngt_f32_e64 s[4:5], |v10|, s72
	v_max_f32_e64 v27, -v10, 0
	v_ldexp_f32 v11, v11, v50
	v_cndmask_b32_e64 v11, 0, v11, s[4:5]
	v_cmp_nlt_f32_e64 s[4:5], |v10|, s73
	s_nop 1
	v_cndmask_b32_e64 v50, v222, v11, s[4:5]
	v_add_f32_e32 v52, 1.0, v50
	v_add_f32_e32 v10, -1.0, v52
	v_sub_f32_e32 v11, v10, v52
	v_add_f32_e32 v11, 1.0, v11
	v_sub_f32_e32 v10, v50, v10
	v_add_f32_e32 v53, v10, v11
	v_frexp_mant_f32_e32 v10, v52
	v_cmp_gt_f32_e64 s[4:5], s75, v10
	v_cvt_f64_f32_e32 v[10:11], v52
	v_frexp_exp_i32_f64_e32 v10, v[10:11]
	v_subbrev_co_u32_e64 v51, s[4:5], 0, v10, s[4:5]
	v_sub_u32_e32 v10, 0, v51
	v_ldexp_f32 v11, v52, v10
	v_add_f32_e32 v52, -1.0, v11
	v_add_f32_e32 v54, 1.0, v11
	v_ldexp_f32 v10, v53, v10
	v_add_f32_e32 v53, 1.0, v52
	v_add_f32_e32 v55, -1.0, v54
	v_sub_f32_e32 v53, v11, v53
	v_sub_f32_e32 v11, v11, v55
	v_add_f32_e32 v53, v10, v53
	v_add_f32_e32 v10, v10, v11
	v_add_f32_e32 v55, v54, v10
	v_sub_f32_e32 v11, v54, v55
	v_rcp_f32_e32 v54, v55
	v_add_f32_e32 v59, v52, v53
	v_add_f32_e32 v56, v10, v11
	v_sub_f32_e32 v10, v52, v59
	v_mul_f32_e32 v52, v59, v54
	v_add_f32_e32 v53, v53, v10
	v_mul_f32_e32 v10, v55, v52
	v_fma_f32 v60, v52, v55, -v10
	v_fmac_f32_e32 v60, v52, v56
	v_add_f32_e32 v58, v10, v60
	v_sub_f32_e32 v11, v59, v58
	v_pk_add_f32 v[62:63], v[58:59], v[10:11] neg_lo:[0,1] neg_hi:[0,1]
	v_mov_b32_e32 v61, v58
	v_pk_add_f32 v[58:59], v[62:63], v[60:61] neg_lo:[0,1] neg_hi:[0,1]
	v_cmp_neq_f32_e64 s[4:5], s74, v50
	v_add_f32_e32 v10, v53, v59
	v_add_f32_e32 v57, v58, v10
	v_add_f32_e32 v59, v11, v57
	v_mul_f32_e32 v53, v54, v59
	v_mul_f32_e32 v10, v55, v53
	v_fma_f32 v60, v53, v55, -v10
	v_fmac_f32_e32 v60, v53, v56
	v_sub_f32_e32 v11, v11, v59
	v_add_f32_e32 v58, v10, v60
	v_add_f32_e32 v55, v57, v11
	v_sub_f32_e32 v11, v59, v58
	v_pk_add_f32 v[56:57], v[58:59], v[10:11] neg_lo:[0,1] neg_hi:[0,1]
	v_mov_b32_e32 v61, v58
	v_pk_add_f32 v[56:57], v[56:57], v[60:61] neg_lo:[0,1] neg_hi:[0,1]
	s_nop 0
	v_add_f32_e32 v10, v55, v57
	v_add_f32_e32 v10, v56, v10
	v_add_f32_e32 v10, v11, v10
	v_add_f32_e32 v11, v52, v53
	v_sub_f32_e32 v52, v11, v52
	v_mul_f32_e32 v10, v54, v10
	v_sub_f32_e32 v52, v53, v52
	v_add_f32_e32 v52, v52, v10
	v_add_f32_e32 v54, v11, v52
	v_mul_f32_e32 v55, v54, v54
	v_fmamk_f32 v10, v55, 0x3e9b6dac, v219
	v_fmaak_f32 v167, v55, v10, 0x3f2aaada
	v_cvt_f32_i32_e32 v10, v51
	v_sub_f32_e32 v11, v54, v11
	v_sub_f32_e32 v11, v52, v11
	v_ldexp_f32 v51, v11, 1
	v_mul_f32_e32 v11, v54, v55
	v_ldexp_f32 v53, v54, 1
	v_pk_mul_f32 v[54:55], v[10:11], v[166:167]
	s_nop 0
	v_fma_f32 v52, v10, s76, -v54
	v_fmac_f32_e32 v52, 0xb102e308, v10
	v_pk_add_f32 v[10:11], v[54:55], v[52:53]
	v_mov_b32_e32 v56, v54
	v_sub_f32_e32 v53, v11, v53
	v_sub_f32_e32 v53, v55, v53
	v_add_f32_e32 v57, v51, v53
	v_pk_add_f32 v[54:55], v[10:11], v[54:55] neg_lo:[0,1] neg_hi:[0,1]
	v_pk_add_f32 v[58:59], v[10:11], v[56:57]
	v_mov_b32_e32 v53, v10
	v_mov_b32_e32 v55, v59
	v_pk_add_f32 v[60:61], v[52:53], v[54:55] neg_lo:[0,1] neg_hi:[0,1]
	v_pk_add_f32 v[52:53], v[52:53], v[54:55]
	v_mov_b32_e32 v56, v57
	v_pk_add_f32 v[54:55], v[52:53], v[10:11] op_sel:[1,0] op_sel_hi:[0,1] neg_lo:[0,1] neg_hi:[0,1]
	v_pk_add_f32 v[62:63], v[58:59], v[54:55] op_sel_hi:[1,0] neg_lo:[0,1] neg_hi:[0,1]
	v_mov_b32_e32 v58, v59
	v_mov_b32_e32 v59, v53
	v_pk_mov_b32 v[54:55], v[10:11], v[54:55] op_sel:[1,0]
	v_mov_b32_e32 v57, v10
	v_pk_add_f32 v[54:55], v[58:59], v[54:55] neg_lo:[0,1] neg_hi:[0,1]
	v_mov_b32_e32 v62, v60
	v_pk_add_f32 v[10:11], v[56:57], v[54:55] neg_lo:[0,1] neg_hi:[0,1]
	v_mov_b32_e32 v61, v53
	v_pk_add_f32 v[54:55], v[62:63], v[10:11]
	s_nop 0
	v_pk_add_f32 v[56:57], v[54:55], v[54:55] op_sel:[0,1] op_sel_hi:[1,0]
	s_nop 0
	v_pk_add_f32 v[52:53], v[52:53], v[56:57] op_sel:[1,0] op_sel_hi:[0,1]
	v_mov_b32_e32 v55, v52
	v_pk_add_f32 v[58:59], v[54:55], v[60:61] neg_lo:[0,1] neg_hi:[0,1]
	v_mov_b32_e32 v11, v56
	v_sub_f32_e32 v51, v54, v58
	v_pk_add_f32 v[10:11], v[10:11], v[58:59] neg_lo:[0,1] neg_hi:[0,1]
	v_sub_f32_e32 v51, v60, v51
	v_add_f32_e32 v10, v10, v51
	v_add_f32_e32 v10, v10, v11
	v_sub_f32_e64 v11, -v18, v19
	v_sub_f32_e32 v20, v11, v20
	v_sub_f32_e32 v21, v20, v21
	v_sub_f32_e32 v22, v21, v22
	v_sub_f32_e32 v23, v22, v23
	v_add_f32_e32 v10, v52, v10
	v_sub_f32_e32 v24, v23, v24
	v_cndmask_b32_e64 v10, v222, v10, s[4:5]
	v_cmp_lt_f32_e64 s[4:5], |v50|, s77
	v_sub_f32_e32 v25, v24, v25
	v_sub_f32_e32 v26, v25, v26
	v_cndmask_b32_e64 v10, v10, v50, s[4:5]
	v_add_f32_e32 v50, v27, v10
	v_sub_f32_e32 v27, v26, v28
	v_sub_f32_e32 v28, v27, v29
	v_sub_f32_e32 v29, v28, v30
	v_sub_f32_e32 v30, v29, v31
	v_sub_f32_e32 v31, v30, v32
	v_sub_f32_e32 v32, v31, v33
	v_sub_f32_e32 v33, v32, v34
	v_sub_f32_e32 v34, v33, v35
	v_sub_f32_e32 v35, v34, v36
	v_sub_f32_e32 v36, v35, v37
	v_sub_f32_e32 v37, v36, v38
	v_sub_f32_e32 v38, v37, v39
	v_sub_f32_e32 v39, v38, v40
	v_sub_f32_e32 v40, v39, v41
	v_sub_f32_e32 v41, v40, v42
	v_sub_f32_e32 v42, v41, v43
	v_sub_f32_e32 v43, v42, v44
	v_sub_f32_e32 v44, v43, v45
	v_sub_f32_e32 v45, v44, v46
	v_sub_f32_e32 v46, v45, v47
	v_sub_f32_e32 v47, v46, v48
	v_sub_f32_e32 v48, v47, v49
	v_sub_f32_e32 v49, v48, v50
	v_sub_f32_e32 v10, 0, v18
	ds_bpermute_b32 v18, v0, v49
	v_cmp_lt_i32_e64 s[4:5], 31, v2
	s_or_b64 s[48:49], s[4:5], s[48:49]
	s_waitcnt lgkmcnt(0)
; __device__ __forceinline__ void phase_small(const Params& P, int l) {
;     ...
;         for (int o = 1; o < 64; o <<= 1) { const float t = __shfl_up(incl, o); if (lane >= o) incl += t; }
;         const float excl = incl - run; float* fc = (float*)(P.ws + WS_FC) + (size_t)sid * 2048 + lane * 32;
; #pragma unroll
;         for (int i = 0; i < 32; ++i) fc[i] = (loc[i] + excl) * LOG2E; }
	v_add_f32_e32 v18, v49, v18
	v_cndmask_b32_e32 v18, v18, v49, vcc
	ds_bpermute_b32 v19, v13, v18
	s_waitcnt lgkmcnt(0)
	v_add_f32_e32 v19, v18, v19
	v_cndmask_b32_e64 v18, v19, v18, s[38:39]
	ds_bpermute_b32 v19, v14, v18
	s_waitcnt lgkmcnt(0)
	v_add_f32_e32 v19, v18, v19
	v_cndmask_b32_e64 v18, v19, v18, s[40:41]
	ds_bpermute_b32 v19, v15, v18
	s_waitcnt lgkmcnt(0)
	v_add_f32_e32 v19, v18, v19
	v_cndmask_b32_e64 v18, v19, v18, s[42:43]
	ds_bpermute_b32 v19, v16, v18
	s_waitcnt lgkmcnt(0)
	v_add_f32_e32 v19, v18, v19
	v_cndmask_b32_e64 v18, v19, v18, s[44:45]
	ds_bpermute_b32 v19, v17, v18
	s_waitcnt lgkmcnt(0)
	v_add_f32_e32 v19, v18, v19
	v_cndmask_b32_e64 v18, v19, v18, s[46:47]
	v_sub_f32_e32 v50, v18, v49
	v_pk_add_f32 v[10:11], v[10:11], v[50:51] op_sel_hi:[1,0]
	s_nop 0
	v_pk_mul_f32 v[18:19], v[10:11], s[80:81] op_sel_hi:[1,0]
	v_pk_add_f32 v[10:11], v[20:21], v[50:51] op_sel_hi:[1,0]
	s_nop 0
	v_pk_mul_f32 v[20:21], v[10:11], s[80:81] op_sel_hi:[1,0]
	v_pk_add_f32 v[10:11], v[22:23], v[50:51] op_sel_hi:[1,0]
	flat_store_dwordx4 v[8:9], v[18:21]
	s_nop 1
	v_pk_mul_f32 v[18:19], v[10:11], s[80:81] op_sel_hi:[1,0]
	v_pk_add_f32 v[10:11], v[24:25], v[50:51] op_sel_hi:[1,0]
	s_nop 0
	v_pk_mul_f32 v[20:21], v[10:11], s[80:81] op_sel_hi:[1,0]
	v_pk_add_f32 v[10:11], v[26:27], v[50:51] op_sel_hi:[1,0]
	flat_store_dwordx4 v[8:9], v[18:21] offset:16
	s_nop 1
	v_pk_mul_f32 v[18:19], v[10:11], s[80:81] op_sel_hi:[1,0]
	v_pk_add_f32 v[10:11], v[28:29], v[50:51] op_sel_hi:[1,0]
	s_nop 0
	v_pk_mul_f32 v[20:21], v[10:11], s[80:81] op_sel_hi:[1,0]
	v_pk_add_f32 v[10:11], v[30:31], v[50:51] op_sel_hi:[1,0]
	flat_store_dwordx4 v[8:9], v[18:21] offset:32
	s_nop 1
	v_pk_mul_f32 v[18:19], v[10:11], s[80:81] op_sel_hi:[1,0]
	v_pk_add_f32 v[10:11], v[32:33], v[50:51] op_sel_hi:[1,0]
	s_nop 0
	v_pk_mul_f32 v[20:21], v[10:11], s[80:81] op_sel_hi:[1,0]
	v_pk_add_f32 v[10:11], v[34:35], v[50:51] op_sel_hi:[1,0]
	flat_store_dwordx4 v[8:9], v[18:21] offset:48
	s_nop 1
	v_pk_mul_f32 v[18:19], v[10:11], s[80:81] op_sel_hi:[1,0]
	v_pk_add_f32 v[10:11], v[36:37], v[50:51] op_sel_hi:[1,0]
	s_nop 0
	v_pk_mul_f32 v[20:21], v[10:11], s[80:81] op_sel_hi:[1,0]
	v_pk_add_f32 v[10:11], v[38:39], v[50:51] op_sel_hi:[1,0]
	flat_store_dwordx4 v[8:9], v[18:21] offset:64
	s_nop 1
	v_pk_mul_f32 v[18:19], v[10:11], s[80:81] op_sel_hi:[1,0]
	v_pk_add_f32 v[10:11], v[40:41], v[50:51] op_sel_hi:[1,0]
	s_nop 0
	v_pk_mul_f32 v[20:21], v[10:11], s[80:81] op_sel_hi:[1,0]
	v_pk_add_f32 v[10:11], v[42:43], v[50:51] op_sel_hi:[1,0]
	flat_store_dwordx4 v[8:9], v[18:21] offset:80
	s_nop 1
	v_pk_mul_f32 v[18:19], v[10:11], s[80:81] op_sel_hi:[1,0]
	v_pk_add_f32 v[10:11], v[44:45], v[50:51] op_sel_hi:[1,0]
	s_nop 0
	v_pk_mul_f32 v[20:21], v[10:11], s[80:81] op_sel_hi:[1,0]
	v_pk_add_f32 v[10:11], v[46:47], v[50:51] op_sel_hi:[1,0]
	flat_store_dwordx4 v[8:9], v[18:21] offset:96
	s_nop 1
	v_pk_mul_f32 v[18:19], v[10:11], s[80:81] op_sel_hi:[1,0]
	v_pk_add_f32 v[10:11], v[48:49], v[50:51] op_sel_hi:[1,0]
	s_nop 0
	v_pk_mul_f32 v[20:21], v[10:11], s[80:81] op_sel_hi:[1,0]
	flat_store_dwordx4 v[8:9], v[18:21] offset:112
	v_lshl_add_u64 v[8:9], v[8:9], 0, s[10:11]
	s_andn2_b64 exec, exec, s[48:49]
	s_cbranch_execnz .LBB0_900

; #define PG8_STAGE(bufoff, gbase, voff) do { _Pragma("unroll") for (int _i = 0; _i < 2; ++_i) \
;         __builtin_amdgcn_global_load_lds((const unsigned*)((const char*)(gbase) + (voff)[_i]), (PG8_LAS unsigned*)(lds + (bufoff) + ldsw + _i * 8192), 16, 0, 0); } while (0)
; #define PG8_LDA(dst, b, h) do { _Pragma("unroll") for (int m = 0; m < 4; ++m) _Pragma("unroll") for (int k = 0; k < 2; ++k) dst[m][k] = *(const PG8_LAS bf16x8*)(lds + PG8_SA(b, h) + aoff + m * 2048 + k * 1024); } while (0)
; #define PG8_LDB(dst, b, h) do { _Pragma("unroll") for (int n = 0; n < 2; ++n) _Pragma("unroll") for (int k = 0; k < 2; ++k) dst[n][k] = *(const PG8_LAS bf16x8*)(lds + PG8_SB(b, h) + boff + n * 2048 + k * 1024); } while (0)
; #define PG8_MMA(ai, bj, At, Bt) do { __builtin_amdgcn_s_setprio(1); _Pragma("unroll") for (int m = 0; m < 4; ++m) _Pragma("unroll") for (int n = 0; n < 2; ++n) _Pragma("unroll") for (int k = 0; k < 2; ++k) \
;         acc[ai][bj][m][n] = __builtin_amdgcn_mfma_f32_16x16x32_bf16(Bt[n][k], At[m][k], acc[ai][bj][m][n], 0, 0, 0); __builtin_amdgcn_s_setprio(0); } while (0)
; #define PG8_WAIT_V(n) asm volatile("s_waitcnt vmcnt(" #n ")" ::: "memory")
; #define PG8_WAIT_L(n) asm volatile("s_waitcnt lgkmcnt(" #n ")" ::: "memory")
; #define PG8_BAR __builtin_amdgcn_s_barrier()
; #define PG8_SCHED __builtin_amdgcn_sched_barrier(0)
; template <class Epi, class Sched, bool ALIGN_EPI = false, bool SP2 = false>
; __device__ __forceinline__ void gemm_phase(PG8_LAS unsigned char* lds, const Gemm g, const Sched& S, const Epi& E) {
;     ...
;             PG8_LDB(B0, 0, 0); PG8_LDB(B1, 0, 1); PG8_SCHED; PG8_LDA(At, 0, 0); PG8_STAGE(PG8_SA(1, 1), a1 + hstep, voffA);
;             PG8_WAIT_V(8); PG8_WAIT_L(0); PG8_BAR; PG8_MMA(0, 0, At, B0); PG8_MMA(0, 1, At, B1); PG8_BAR; PG8_SCHED;
;             PG8_LDA(At, 0, 1); PG8_STAGE(PG8_SB(0, 0), b2, voffB); PG8_STAGE(PG8_SB(0, 1), b2 + hstep, voffB); PG8_STAGE(PG8_SA(0, 0), a2, voffA);
;             PG8_WAIT_V(8); PG8_WAIT_L(0); PG8_BAR; PG8_MMA(1, 0, At, B0); PG8_MMA(1, 1, At, B1); PG8_BAR; PG8_SCHED;
.LBB0_909:
	s_add_u32 s12, s2, 0xfffe0080
	s_addc_u32 s13, s3, -1
	s_add_i32 s47, 0, 0x10000
	s_cmp_eq_u32 s46, 4
	s_cselect_b32 s15, s9, s13
	s_cselect_b32 s14, s42, s12
	v_add_u32_e32 v158, s47, v167
	s_cselect_b32 s13, s7, s45
	s_cselect_b32 s12, s43, s44
	s_add_i32 s50, 0, 0x14000
	ds_read_b128 v[146:149], v158
	ds_read_b128 v[150:153], v158 offset:1024
	ds_read_b128 v[154:157], v158 offset:2048
	ds_read_b128 v[180:183], v158 offset:3072
	v_add_u32_e32 v158, s50, v167
	ds_read_b128 v[184:187], v158
	ds_read_b128 v[188:191], v158 offset:1024
	ds_read_b128 v[192:195], v158 offset:2048
	ds_read_b128 v[196:199], v158 offset:3072
	v_lshl_add_u64 v[158:159], s[2:3], 0, v[144:145]
	s_add_i32 m0, s28, 0xc000
	ds_read_b128 v[200:203], v178
	ds_read_b128 v[204:207], v178 offset:1024
	ds_read_b128 v[224:227], v178 offset:2048
	ds_read_b128 v[228:231], v178 offset:3072
	ds_read_b128 v[232:235], v178 offset:4096
	ds_read_b128 v[236:239], v178 offset:5120
	ds_read_b128 v[240:243], v178 offset:6144
	ds_read_b128 v[244:247], v178 offset:7168
	global_load_lds_dwordx4 v[158:159], off
	v_lshl_add_u64 v[158:159], s[2:3], 0, v[142:143]
	s_add_i32 m0, s28, 0xe000
	s_nop 0
	global_load_lds_dwordx4 v[158:159], off
	s_waitcnt vmcnt(8)
	s_waitcnt lgkmcnt(0)
	s_barrier
	s_setprio 1
	s_waitcnt lgkmcnt(0)
	v_mfma_f32_16x16x32_bf16 v[126:129], v[146:149], v[200:203], v[126:129]
	v_mfma_f32_16x16x32_bf16 v[122:125], v[154:157], v[200:203], v[122:125]
	v_mfma_f32_16x16x32_bf16 v[110:113], v[146:149], v[224:227], v[110:113]
	v_mfma_f32_16x16x32_bf16 v[106:109], v[154:157], v[224:227], v[106:109]
	v_mfma_f32_16x16x32_bf16 v[94:97], v[146:149], v[232:235], v[94:97]
	v_mfma_f32_16x16x32_bf16 v[90:93], v[154:157], v[232:235], v[90:93]
	v_mfma_f32_16x16x32_bf16 v[78:81], v[146:149], v[240:243], v[78:81]
	v_mfma_f32_16x16x32_bf16 v[74:77], v[154:157], v[240:243], v[74:77]
	v_mfma_f32_16x16x32_bf16 v[126:129], v[150:153], v[204:207], v[126:129]
	v_mfma_f32_16x16x32_bf16 v[122:125], v[180:183], v[204:207], v[122:125]
	v_mfma_f32_16x16x32_bf16 v[110:113], v[150:153], v[228:231], v[110:113]
	v_mfma_f32_16x16x32_bf16 v[106:109], v[180:183], v[228:231], v[106:109]
	v_mfma_f32_16x16x32_bf16 v[94:97], v[150:153], v[236:239], v[94:97]
	v_mfma_f32_16x16x32_bf16 v[90:93], v[180:183], v[236:239], v[90:93]
	v_mfma_f32_16x16x32_bf16 v[78:81], v[150:153], v[244:247], v[78:81]
	v_mfma_f32_16x16x32_bf16 v[74:77], v[180:183], v[244:247], v[74:77]
	s_setprio 0
	s_setprio 1
	v_mfma_f32_16x16x32_bf16 v[118:121], v[184:187], v[200:203], v[118:121]
	v_mfma_f32_16x16x32_bf16 v[114:117], v[192:195], v[200:203], v[114:117]
	v_mfma_f32_16x16x32_bf16 v[102:105], v[184:187], v[224:227], v[102:105]
	v_mfma_f32_16x16x32_bf16 v[98:101], v[192:195], v[224:227], v[98:101]
	v_mfma_f32_16x16x32_bf16 v[86:89], v[184:187], v[232:235], v[86:89]
	v_mfma_f32_16x16x32_bf16 v[82:85], v[192:195], v[232:235], v[82:85]
	v_mfma_f32_16x16x32_bf16 v[70:73], v[184:187], v[240:243], v[70:73]
	v_mfma_f32_16x16x32_bf16 v[66:69], v[192:195], v[240:243], v[66:69]
	v_mfma_f32_16x16x32_bf16 v[118:121], v[188:191], v[204:207], v[118:121]
	v_mfma_f32_16x16x32_bf16 v[114:117], v[196:199], v[204:207], v[114:117]
	v_mfma_f32_16x16x32_bf16 v[102:105], v[188:191], v[228:231], v[102:105]
	v_mfma_f32_16x16x32_bf16 v[98:101], v[196:199], v[228:231], v[98:101]
	v_mfma_f32_16x16x32_bf16 v[86:89], v[188:191], v[236:239], v[86:89]
	v_mfma_f32_16x16x32_bf16 v[82:85], v[196:199], v[236:239], v[82:85]
	v_mfma_f32_16x16x32_bf16 v[70:73], v[188:191], v[244:247], v[70:73]
	v_mfma_f32_16x16x32_bf16 v[66:69], v[196:199], v[244:247], v[66:69]
	s_setprio 0
	s_barrier
	s_add_i32 s47, s47, s26
	v_lshl_add_u64 v[158:159], s[12:13], 0, v[0:1]
	s_mov_b32 m0, s47
	ds_read_b128 v[200:203], v178 offset:16384
	ds_read_b128 v[204:207], v178 offset:17408
	ds_read_b128 v[224:227], v178 offset:18432
	ds_read_b128 v[228:231], v178 offset:19456
	ds_read_b128 v[232:235], v178 offset:20480
	ds_read_b128 v[236:239], v178 offset:21504
	ds_read_b128 v[240:243], v178 offset:22528
	ds_read_b128 v[244:247], v178 offset:23552
	global_load_lds_dwordx4 v[158:159], off
	s_add_i32 m0, s47, 0x2000
	s_add_u32 s48, s12, 0x20000
	v_lshl_add_u64 v[176:177], s[12:13], 0, v[130:131]
	s_addc_u32 s49, s13, 0
	s_add_i32 s47, s50, s26
	global_load_lds_dwordx4 v[176:177], off
	v_lshl_add_u64 v[214:215], s[48:49], 0, v[0:1]
	s_mov_b32 m0, s47
	v_lshl_add_u64 v[248:249], s[14:15], 0, v[132:133]
	global_load_lds_dwordx4 v[214:215], off
	v_lshl_add_u64 v[214:215], s[48:49], 0, v[130:131]
	s_add_i32 m0, s47, 0x2000
	s_nop 0
	global_load_lds_dwordx4 v[214:215], off
	v_lshl_add_u64 v[214:215], s[14:15], 0, v[134:135]
	s_mov_b32 m0, s28
	s_nop 0
	global_load_lds_dwordx4 v[214:215], off
	s_mov_b32 m0, s29
	s_nop 0
	global_load_lds_dwordx4 v[248:249], off
	s_waitcnt vmcnt(8)
	s_waitcnt lgkmcnt(0)
	s_barrier
; #define PG8_STAGE(bufoff, gbase, voff) do { _Pragma("unroll") for (int _i = 0; _i < 2; ++_i) \
;         __builtin_amdgcn_global_load_lds((const unsigned*)((const char*)(gbase) + (voff)[_i]), (PG8_LAS unsigned*)(lds + (bufoff) + ldsw + _i * 8192), 16, 0, 0); } while (0)
; #define PG8_LDA(dst, b, h) do { _Pragma("unroll") for (int m = 0; m < 4; ++m) _Pragma("unroll") for (int k = 0; k < 2; ++k) dst[m][k] = *(const PG8_LAS bf16x8*)(lds + PG8_SA(b, h) + aoff + m * 2048 + k * 1024); } while (0)
; #define PG8_LDB(dst, b, h) do { _Pragma("unroll") for (int n = 0; n < 2; ++n) _Pragma("unroll") for (int k = 0; k < 2; ++k) dst[n][k] = *(const PG8_LAS bf16x8*)(lds + PG8_SB(b, h) + boff + n * 2048 + k * 1024); } while (0)
; #define PG8_MMA(ai, bj, At, Bt) do { __builtin_amdgcn_s_setprio(1); _Pragma("unroll") for (int m = 0; m < 4; ++m) _Pragma("unroll") for (int n = 0; n < 2; ++n) _Pragma("unroll") for (int k = 0; k < 2; ++k) \
;         acc[ai][bj][m][n] = __builtin_amdgcn_mfma_f32_16x16x32_bf16(Bt[n][k], At[m][k], acc[ai][bj][m][n], 0, 0, 0); __builtin_amdgcn_s_setprio(0); } while (0)
; #define PG8_WAIT_V(n) asm volatile("s_waitcnt vmcnt(" #n ")" ::: "memory")
; #define PG8_WAIT_L(n) asm volatile("s_waitcnt lgkmcnt(" #n ")" ::: "memory")
; #define PG8_BAR __builtin_amdgcn_s_barrier()
; #define PG8_SCHED __builtin_amdgcn_sched_barrier(0)
; template <class Epi, class Sched, bool ALIGN_EPI = false, bool SP2 = false>
; __device__ __forceinline__ void gemm_phase(PG8_LAS unsigned char* lds, const Gemm g, const Sched& S, const Epi& E) {
;     ...
;             PG8_WAIT_V(8); PG8_WAIT_L(0); PG8_BAR; PG8_MMA(1, 0, At, B0); PG8_MMA(1, 1, At, B1); PG8_BAR; PG8_SCHED;
;             PG8_LDB(B0, 1, 0); PG8_LDB(B1, 1, 1); PG8_SCHED; PG8_LDA(At, 1, 0); PG8_STAGE(PG8_SA(0, 1), a2 + hstep, voffA);
;             PG8_WAIT_V(8); PG8_WAIT_L(0); PG8_BAR; PG8_MMA(0, 0, At, B0); PG8_MMA(0, 1, At, B1); PG8_BAR; PG8_SCHED;
;             PG8_LDA(At, 1, 1); PG8_STAGE(PG8_SB(1, 0), b3, voffB); PG8_STAGE(PG8_SB(1, 1), b3 + hstep, voffB); PG8_STAGE(PG8_SA(1, 0), a3, voffA);
	s_setprio 1
	s_waitcnt lgkmcnt(0)
	v_mfma_f32_16x16x32_bf16 v[62:65], v[146:149], v[200:203], v[62:65]
	v_mfma_f32_16x16x32_bf16 v[58:61], v[154:157], v[200:203], v[58:61]
	v_mfma_f32_16x16x32_bf16 v[46:49], v[146:149], v[224:227], v[46:49]
	v_mfma_f32_16x16x32_bf16 v[42:45], v[154:157], v[224:227], v[42:45]
	v_mfma_f32_16x16x32_bf16 v[30:33], v[146:149], v[232:235], v[30:33]
	v_mfma_f32_16x16x32_bf16 v[26:29], v[154:157], v[232:235], v[26:29]
	v_mfma_f32_16x16x32_bf16 v[14:17], v[146:149], v[240:243], v[14:17]
	v_mfma_f32_16x16x32_bf16 v[10:13], v[154:157], v[240:243], v[10:13]
	v_mfma_f32_16x16x32_bf16 v[62:65], v[150:153], v[204:207], v[62:65]
	v_mfma_f32_16x16x32_bf16 v[58:61], v[180:183], v[204:207], v[58:61]
	v_mfma_f32_16x16x32_bf16 v[46:49], v[150:153], v[228:231], v[46:49]
	v_mfma_f32_16x16x32_bf16 v[42:45], v[180:183], v[228:231], v[42:45]
	v_mfma_f32_16x16x32_bf16 v[30:33], v[150:153], v[236:239], v[30:33]
	v_mfma_f32_16x16x32_bf16 v[26:29], v[180:183], v[236:239], v[26:29]
	v_mfma_f32_16x16x32_bf16 v[14:17], v[150:153], v[244:247], v[14:17]
	v_mfma_f32_16x16x32_bf16 v[10:13], v[180:183], v[244:247], v[10:13]
	s_setprio 0
	s_setprio 1
	v_mfma_f32_16x16x32_bf16 v[54:57], v[184:187], v[200:203], v[54:57]
	v_mfma_f32_16x16x32_bf16 v[50:53], v[192:195], v[200:203], v[50:53]
	v_mfma_f32_16x16x32_bf16 v[38:41], v[184:187], v[224:227], v[38:41]
	v_mfma_f32_16x16x32_bf16 v[34:37], v[192:195], v[224:227], v[34:37]
	v_mfma_f32_16x16x32_bf16 v[22:25], v[184:187], v[232:235], v[22:25]
	v_mfma_f32_16x16x32_bf16 v[18:21], v[192:195], v[232:235], v[18:21]
	v_mfma_f32_16x16x32_bf16 v[6:9], v[184:187], v[240:243], v[6:9]
	v_mfma_f32_16x16x32_bf16 v[2:5], v[192:195], v[240:243], v[2:5]
	v_mfma_f32_16x16x32_bf16 v[54:57], v[188:191], v[204:207], v[54:57]
	v_mfma_f32_16x16x32_bf16 v[50:53], v[196:199], v[204:207], v[50:53]
	v_mfma_f32_16x16x32_bf16 v[38:41], v[188:191], v[228:231], v[38:41]
	v_mfma_f32_16x16x32_bf16 v[34:37], v[196:199], v[228:231], v[34:37]
	v_mfma_f32_16x16x32_bf16 v[22:25], v[188:191], v[236:239], v[22:25]
	v_mfma_f32_16x16x32_bf16 v[18:21], v[196:199], v[236:239], v[18:21]
	v_mfma_f32_16x16x32_bf16 v[6:9], v[188:191], v[244:247], v[6:9]
	v_mfma_f32_16x16x32_bf16 v[2:5], v[196:199], v[244:247], v[2:5]
	s_setprio 0
	s_barrier
	s_add_i32 s47, 0, 0x18000
	v_add_u32_e32 v160, s47, v167
	s_add_i32 s48, 0, 0x1c000
	ds_read_b128 v[146:149], v160
	ds_read_b128 v[150:153], v160 offset:1024
	ds_read_b128 v[154:157], v160 offset:2048
	ds_read_b128 v[180:183], v160 offset:3072
	v_add_u32_e32 v160, s48, v167
	ds_read_b128 v[184:187], v160
	ds_read_b128 v[188:191], v160 offset:1024
	ds_read_b128 v[192:195], v160 offset:2048
	ds_read_b128 v[196:199], v160 offset:3072
	s_add_u32 s14, s14, 0x20000
	s_addc_u32 s15, s15, 0
	s_mov_b32 m0, s34
	v_lshl_add_u64 v[250:251], s[14:15], 0, v[134:135]
	ds_read_b128 v[200:203], v178 offset:32768
	ds_read_b128 v[204:207], v178 offset:33792
	ds_read_b128 v[224:227], v178 offset:34816
	ds_read_b128 v[228:231], v178 offset:35840
	ds_read_b128 v[232:235], v178 offset:36864
	ds_read_b128 v[236:239], v178 offset:37888
	ds_read_b128 v[240:243], v178 offset:38912
	ds_read_b128 v[244:247], v178 offset:39936
	global_load_lds_dwordx4 v[250:251], off
	v_lshl_add_u64 v[250:251], s[14:15], 0, v[132:133]
	s_mov_b32 m0, s35
	s_nop 0
	global_load_lds_dwordx4 v[250:251], off
	s_waitcnt vmcnt(8)
	s_waitcnt lgkmcnt(0)
	s_barrier
	s_setprio 1
	s_waitcnt lgkmcnt(0)
	v_mfma_f32_16x16x32_bf16 v[126:129], v[146:149], v[200:203], v[126:129]
	v_mfma_f32_16x16x32_bf16 v[122:125], v[154:157], v[200:203], v[122:125]
	v_mfma_f32_16x16x32_bf16 v[110:113], v[146:149], v[224:227], v[110:113]
	v_mfma_f32_16x16x32_bf16 v[106:109], v[154:157], v[224:227], v[106:109]
	v_mfma_f32_16x16x32_bf16 v[94:97], v[146:149], v[232:235], v[94:97]
	v_mfma_f32_16x16x32_bf16 v[90:93], v[154:157], v[232:235], v[90:93]
	v_mfma_f32_16x16x32_bf16 v[78:81], v[146:149], v[240:243], v[78:81]
	v_mfma_f32_16x16x32_bf16 v[74:77], v[154:157], v[240:243], v[74:77]
	v_mfma_f32_16x16x32_bf16 v[126:129], v[150:153], v[204:207], v[126:129]
	v_mfma_f32_16x16x32_bf16 v[122:125], v[180:183], v[204:207], v[122:125]
	v_mfma_f32_16x16x32_bf16 v[110:113], v[150:153], v[228:231], v[110:113]
	v_mfma_f32_16x16x32_bf16 v[106:109], v[180:183], v[228:231], v[106:109]
	v_mfma_f32_16x16x32_bf16 v[94:97], v[150:153], v[236:239], v[94:97]
	v_mfma_f32_16x16x32_bf16 v[90:93], v[180:183], v[236:239], v[90:93]
	v_mfma_f32_16x16x32_bf16 v[78:81], v[150:153], v[244:247], v[78:81]
	v_mfma_f32_16x16x32_bf16 v[74:77], v[180:183], v[244:247], v[74:77]
	s_setprio 0
	s_setprio 1
	v_mfma_f32_16x16x32_bf16 v[118:121], v[184:187], v[200:203], v[118:121]
	v_mfma_f32_16x16x32_bf16 v[114:117], v[192:195], v[200:203], v[114:117]
	v_mfma_f32_16x16x32_bf16 v[102:105], v[184:187], v[224:227], v[102:105]
	v_mfma_f32_16x16x32_bf16 v[98:101], v[192:195], v[224:227], v[98:101]
	v_mfma_f32_16x16x32_bf16 v[86:89], v[184:187], v[232:235], v[86:89]
	v_mfma_f32_16x16x32_bf16 v[82:85], v[192:195], v[232:235], v[82:85]
	v_mfma_f32_16x16x32_bf16 v[70:73], v[184:187], v[240:243], v[70:73]
	v_mfma_f32_16x16x32_bf16 v[66:69], v[192:195], v[240:243], v[66:69]
	v_mfma_f32_16x16x32_bf16 v[118:121], v[188:191], v[204:207], v[118:121]
	v_mfma_f32_16x16x32_bf16 v[114:117], v[196:199], v[204:207], v[114:117]
	v_mfma_f32_16x16x32_bf16 v[102:105], v[188:191], v[228:231], v[102:105]
	v_mfma_f32_16x16x32_bf16 v[98:101], v[196:199], v[228:231], v[98:101]
	v_mfma_f32_16x16x32_bf16 v[86:89], v[188:191], v[236:239], v[86:89]
	v_mfma_f32_16x16x32_bf16 v[82:85], v[196:199], v[236:239], v[82:85]
	v_mfma_f32_16x16x32_bf16 v[70:73], v[188:191], v[244:247], v[70:73]
	v_mfma_f32_16x16x32_bf16 v[66:69], v[196:199], v[244:247], v[66:69]
	s_setprio 0
	s_barrier
; #define PG8_STAGE(bufoff, gbase, voff) do { _Pragma("unroll") for (int _i = 0; _i < 2; ++_i) \
;         __builtin_amdgcn_global_load_lds((const unsigned*)((const char*)(gbase) + (voff)[_i]), (PG8_LAS unsigned*)(lds + (bufoff) + ldsw + _i * 8192), 16, 0, 0); } while (0)
; #define PG8_LDA(dst, b, h) do { _Pragma("unroll") for (int m = 0; m < 4; ++m) _Pragma("unroll") for (int k = 0; k < 2; ++k) dst[m][k] = *(const PG8_LAS bf16x8*)(lds + PG8_SA(b, h) + aoff + m * 2048 + k * 1024); } while (0)
; #define PG8_MMA(ai, bj, At, Bt) do { __builtin_amdgcn_s_setprio(1); _Pragma("unroll") for (int m = 0; m < 4; ++m) _Pragma("unroll") for (int n = 0; n < 2; ++n) _Pragma("unroll") for (int k = 0; k < 2; ++k) \
;         acc[ai][bj][m][n] = __builtin_amdgcn_mfma_f32_16x16x32_bf16(Bt[n][k], At[m][k], acc[ai][bj][m][n], 0, 0, 0); __builtin_amdgcn_s_setprio(0); } while (0)
; #define PG8_WAIT_V(n) asm volatile("s_waitcnt vmcnt(" #n ")" ::: "memory")
; #define PG8_WAIT_L(n) asm volatile("s_waitcnt lgkmcnt(" #n ")" ::: "memory")
; #define PG8_BAR __builtin_amdgcn_s_barrier()
; #define PG8_SCHED __builtin_amdgcn_sched_barrier(0)
; template <class Epi, class Sched, bool ALIGN_EPI = false, bool SP2 = false>
; __device__ __forceinline__ void gemm_phase(PG8_LAS unsigned char* lds, const Gemm g, const Sched& S, const Epi& E) {
;     ...
;             PG8_LDA(At, 1, 1); PG8_STAGE(PG8_SB(1, 0), b3, voffB); PG8_STAGE(PG8_SB(1, 1), b3 + hstep, voffB); PG8_STAGE(PG8_SA(1, 0), a3, voffA);
;             PG8_WAIT_V(8); PG8_WAIT_L(0); PG8_BAR; PG8_MMA(1, 0, At, B0); PG8_MMA(1, 1, At, B1); PG8_BAR; PG8_SCHED;
;     __device__ __forceinline__ void operator()(AccRef acc, const pg8::Unit& u, int wr, int wc, int fr, int fq) const {
;         const int pn = u.pn, row0 = u.pm * 256 + wr * 64 + fr, cl0 = wc * 32 + 8 * fq;
;         if (pn < 4) {
;             bf16_t* base = (bf16_t*)(ws + (WHICH ? WS_KAN : WS_QAN)) + pn * 256;
; #pragma unroll
;             for (int ai = 0; ai < 2; ++ai)
; #pragma unroll
;                 for (int m = 0; m < 4; ++m) { const int row = row0 + ai * 128 + m * 16; bf16_t* rp = base + (size_t)row * 1024 + cl0; const float r = rstd(row);
	s_add_i32 s14, s47, s26
	v_lshl_add_u64 v[158:159], v[158:159], 0, s[20:21]
	s_mov_b32 m0, s14
	ds_read_b128 v[200:203], v178 offset:49152
	ds_read_b128 v[204:207], v178 offset:50176
	ds_read_b128 v[224:227], v178 offset:51200
	ds_read_b128 v[228:231], v178 offset:52224
	ds_read_b128 v[232:235], v178 offset:53248
	ds_read_b128 v[236:239], v178 offset:54272
	ds_read_b128 v[240:243], v178 offset:55296
	ds_read_b128 v[244:247], v178 offset:56320
	global_load_lds_dwordx4 v[158:159], off
	s_add_i32 m0, s14, 0x2000
	s_add_u32 s12, s12, 0x20080
	v_lshl_add_u64 v[158:159], v[176:177], 0, s[20:21]
	s_addc_u32 s13, s13, 0
	s_add_i32 s14, s48, s26
	global_load_lds_dwordx4 v[158:159], off
	v_lshl_add_u64 v[158:159], s[12:13], 0, v[0:1]
	s_mov_b32 m0, s14
	s_nop 0
	global_load_lds_dwordx4 v[158:159], off
	v_lshl_add_u64 v[158:159], s[12:13], 0, v[130:131]
	s_add_i32 m0, s14, 0x2000
	s_nop 0
	global_load_lds_dwordx4 v[158:159], off
	v_lshl_add_u64 v[158:159], v[214:215], 0, s[20:21]
	s_mov_b32 m0, s36
	s_nop 0
	global_load_lds_dwordx4 v[158:159], off
	v_lshl_add_u64 v[158:159], v[248:249], 0, s[20:21]
	s_mov_b32 m0, s37
	s_nop 0
	global_load_lds_dwordx4 v[158:159], off
	s_waitcnt vmcnt(8)
	s_waitcnt lgkmcnt(0)
	s_barrier
	s_setprio 1
	s_waitcnt lgkmcnt(0)
	v_mfma_f32_16x16x32_bf16 v[62:65], v[146:149], v[200:203], v[62:65]
	v_mfma_f32_16x16x32_bf16 v[58:61], v[154:157], v[200:203], v[58:61]
	v_mfma_f32_16x16x32_bf16 v[46:49], v[146:149], v[224:227], v[46:49]
	v_mfma_f32_16x16x32_bf16 v[42:45], v[154:157], v[224:227], v[42:45]
	v_mfma_f32_16x16x32_bf16 v[30:33], v[146:149], v[232:235], v[30:33]
	v_mfma_f32_16x16x32_bf16 v[26:29], v[154:157], v[232:235], v[26:29]
	v_mfma_f32_16x16x32_bf16 v[14:17], v[146:149], v[240:243], v[14:17]
	v_mfma_f32_16x16x32_bf16 v[10:13], v[154:157], v[240:243], v[10:13]
	v_mfma_f32_16x16x32_bf16 v[62:65], v[150:153], v[204:207], v[62:65]
	v_mfma_f32_16x16x32_bf16 v[58:61], v[180:183], v[204:207], v[58:61]
	v_mfma_f32_16x16x32_bf16 v[46:49], v[150:153], v[228:231], v[46:49]
	v_mfma_f32_16x16x32_bf16 v[42:45], v[180:183], v[228:231], v[42:45]
	v_mfma_f32_16x16x32_bf16 v[30:33], v[150:153], v[236:239], v[30:33]
	v_mfma_f32_16x16x32_bf16 v[26:29], v[180:183], v[236:239], v[26:29]
	v_mfma_f32_16x16x32_bf16 v[14:17], v[150:153], v[244:247], v[14:17]
	v_mfma_f32_16x16x32_bf16 v[10:13], v[180:183], v[244:247], v[10:13]
	s_setprio 0
	s_setprio 1
	v_mfma_f32_16x16x32_bf16 v[54:57], v[184:187], v[200:203], v[54:57]
	v_mfma_f32_16x16x32_bf16 v[50:53], v[192:195], v[200:203], v[50:53]
	v_mfma_f32_16x16x32_bf16 v[38:41], v[184:187], v[224:227], v[38:41]
	v_mfma_f32_16x16x32_bf16 v[34:37], v[192:195], v[224:227], v[34:37]
	v_mfma_f32_16x16x32_bf16 v[22:25], v[184:187], v[232:235], v[22:25]
	v_mfma_f32_16x16x32_bf16 v[18:21], v[192:195], v[232:235], v[18:21]
	v_mfma_f32_16x16x32_bf16 v[6:9], v[184:187], v[240:243], v[6:9]
	v_mfma_f32_16x16x32_bf16 v[2:5], v[192:195], v[240:243], v[2:5]
	v_mfma_f32_16x16x32_bf16 v[54:57], v[188:191], v[204:207], v[54:57]
	v_mfma_f32_16x16x32_bf16 v[50:53], v[196:199], v[204:207], v[50:53]
	v_mfma_f32_16x16x32_bf16 v[38:41], v[188:191], v[228:231], v[38:41]
	v_mfma_f32_16x16x32_bf16 v[34:37], v[196:199], v[228:231], v[34:37]
	v_mfma_f32_16x16x32_bf16 v[22:25], v[188:191], v[236:239], v[22:25]
	v_mfma_f32_16x16x32_bf16 v[18:21], v[196:199], v[236:239], v[18:21]
	v_mfma_f32_16x16x32_bf16 v[6:9], v[188:191], v[244:247], v[6:9]
	v_mfma_f32_16x16x32_bf16 v[2:5], v[196:199], v[244:247], v[2:5]
	s_setprio 0
	s_barrier
	s_add_i32 s46, s46, 2
	s_add_u32 s44, s44, 0x100
	s_addc_u32 s45, s45, 0
	s_add_u32 s2, s2, 0x100
	s_addc_u32 s3, s3, 0
	s_cmp_gt_u32 s46, 5
	s_cbranch_scc0 .LBB0_909
	v_lshl_add_u32 v146, s0, 8, v161
	v_lshlrev_b32_e32 v147, 6, v146
	s_lshl_b32 s0, s1, 9
	s_cmp_gt_i32 s1, 3
	s_cbranch_scc1 .Lep2q_rope
	v_add_u32_e32 v148, 0, v147
	global_load_dwordx4 v[150:153], v148, s[4:5]
	global_load_dwordx4 v[154:157], v148, s[4:5] offset:16
	v_add_u32_e32 v148, 1024, v147
	global_load_dwordx4 v[176:179], v148, s[4:5]
	global_load_dwordx4 v[180:183], v148, s[4:5] offset:16
	v_add_u32_e32 v148, 2048, v147
	global_load_dwordx4 v[184:187], v148, s[4:5]
	global_load_dwordx4 v[188:191], v148, s[4:5] offset:16
	v_add_u32_e32 v148, 3072, v147
	global_load_dwordx4 v[192:195], v148, s[4:5]
	global_load_dwordx4 v[196:199], v148, s[4:5] offset:16
	v_add_u32_e32 v148, 8192, v147
	global_load_dwordx4 v[200:203], v148, s[4:5]
	global_load_dwordx4 v[204:207], v148, s[4:5] offset:16
	v_add_u32_e32 v148, 9216, v147
	global_load_dwordx4 v[224:227], v148, s[4:5]
	global_load_dwordx4 v[228:231], v148, s[4:5] offset:16
	v_add_u32_e32 v148, 10240, v147
	global_load_dwordx4 v[232:235], v148, s[4:5]
	global_load_dwordx4 v[236:239], v148, s[4:5] offset:16
	v_add_u32_e32 v148, 11264, v147
	global_load_dwordx4 v[240:243], v148, s[4:5]
	global_load_dwordx4 v[244:247], v148, s[4:5] offset:16
	s_waitcnt vmcnt(0)
; __device__ __forceinline__ unsigned pk2(float lo, float hi) { f32x2 v = {lo, hi}; bf16x2_t b = __builtin_convertvector(v, bf16x2_t); return __builtin_bit_cast(unsigned, b); }
;     __device__ __forceinline__ float rstd(int row) const {
;         const float* ssq = (const float*)(ws + WS_SSQ) + (size_t)row * 16 + (WHICH ? 8 : 0);
;         const f32x4 a = *(const f32x4*)ssq; float s = (a[0] + a[1]) + (a[2] + a[3]);
;         if (WHICH == 0) { const f32x4 b = *(const f32x4*)(ssq + 4); s += (b[0] + b[1]) + (b[2] + b[3]); }
;         return rsqrtf(s * (WHICH ? (1.f / 256.f) : (1.f / 512.f)) + 1e-6f);
;     }
;     __device__ __forceinline__ void operator()(AccRef acc, const pg8::Unit& u, int wr, int wc, int fr, int fq) const {
;         const int pn = u.pn, row0 = u.pm * 256 + wr * 64 + fr, cl0 = wc * 32 + 8 * fq;
;         if (pn < 4) {
;             bf16_t* base = (bf16_t*)(ws + (WHICH ? WS_KAN : WS_QAN)) + pn * 256;
; #pragma unroll
;             for (int ai = 0; ai < 2; ++ai)
; #pragma unroll
;                 for (int m = 0; m < 4; ++m) { const int row = row0 + ai * 128 + m * 16; bf16_t* rp = base + (size_t)row * 1024 + cl0; const float r = rstd(row);
; #pragma unroll
;                     for (int bj = 0; bj < 2; ++bj) { const f32x4 v0 = acc[ai][bj][m][0] * r, v1 = acc[ai][bj][m][1] * r;
;                         u32x4 w; w.x = pk2(v0[0], v0[1]); w.y = pk2(v0[2], v0[3]); w.z = pk2(v1[0], v1[1]); w.w = pk2(v1[2], v1[3]);
;                         *(u32x4*)(rp + bj * 128) = w; }
	v_add_f32_e32 v150, v150, v151
	v_add_f32_e32 v152, v152, v153
	v_add_f32_e32 v154, v154, v155
	v_add_f32_e32 v156, v156, v157
	v_add_f32_e32 v150, v150, v152
	v_add_f32_e32 v154, v154, v156
	v_add_f32_e32 v150, v150, v154
	v_fmamk_f32 v150, v150, 0x3b000000, v220
	v_rsq_f32_e32 v150, v150
	v_add_f32_e32 v176, v176, v177
	v_add_f32_e32 v178, v178, v179
	v_add_f32_e32 v180, v180, v181
	v_add_f32_e32 v182, v182, v183
	v_add_f32_e32 v176, v176, v178
	v_add_f32_e32 v180, v180, v182
	v_add_f32_e32 v176, v176, v180
	v_fmamk_f32 v176, v176, 0x3b000000, v220
	v_rsq_f32_e32 v176, v176
	v_add_f32_e32 v184, v184, v185
	v_add_f32_e32 v186, v186, v187
	v_add_f32_e32 v188, v188, v189
	v_add_f32_e32 v190, v190, v191
	v_add_f32_e32 v184, v184, v186
	v_add_f32_e32 v188, v188, v190
	v_add_f32_e32 v184, v184, v188
	v_fmamk_f32 v184, v184, 0x3b000000, v220
	v_rsq_f32_e32 v184, v184
	v_add_f32_e32 v192, v192, v193
	v_add_f32_e32 v194, v194, v195
	v_add_f32_e32 v196, v196, v197
	v_add_f32_e32 v198, v198, v199
	v_add_f32_e32 v192, v192, v194
	v_add_f32_e32 v196, v196, v198
	v_add_f32_e32 v192, v192, v196
	v_fmamk_f32 v192, v192, 0x3b000000, v220
	v_rsq_f32_e32 v192, v192
	v_add_f32_e32 v200, v200, v201
	v_add_f32_e32 v202, v202, v203
	v_add_f32_e32 v204, v204, v205
	v_add_f32_e32 v206, v206, v207
	v_add_f32_e32 v200, v200, v202
	v_add_f32_e32 v204, v204, v206
	v_add_f32_e32 v200, v200, v204
	v_fmamk_f32 v200, v200, 0x3b000000, v220
	v_rsq_f32_e32 v200, v200
	v_add_f32_e32 v224, v224, v225
	v_add_f32_e32 v226, v226, v227
	v_add_f32_e32 v228, v228, v229
	v_add_f32_e32 v230, v230, v231
	v_add_f32_e32 v224, v224, v226
	v_add_f32_e32 v228, v228, v230
	v_add_f32_e32 v224, v224, v228
	v_fmamk_f32 v224, v224, 0x3b000000, v220
	v_rsq_f32_e32 v224, v224
	v_add_f32_e32 v232, v232, v233
	v_add_f32_e32 v234, v234, v235
	v_add_f32_e32 v236, v236, v237
	v_add_f32_e32 v238, v238, v239
	v_add_f32_e32 v232, v232, v234
	v_add_f32_e32 v236, v236, v238
	v_add_f32_e32 v232, v232, v236
	v_fmamk_f32 v232, v232, 0x3b000000, v220
	v_rsq_f32_e32 v232, v232
	v_add_f32_e32 v240, v240, v241
	v_add_f32_e32 v242, v242, v243
	v_add_f32_e32 v244, v244, v245
	v_add_f32_e32 v246, v246, v247
	v_add_f32_e32 v240, v240, v242
	v_add_f32_e32 v244, v244, v246
	v_add_f32_e32 v240, v240, v244
	v_fmamk_f32 v240, v240, 0x3b000000, v220
	v_rsq_f32_e32 v240, v240
	s_nop 0
	v_add_u32_e32 v158, 0, v146
	v_lshlrev_b32_e32 v158, 11, v158
	v_add_u32_e32 v158, s0, v158
	v_mov_b32_e32 v159, 0
	v_lshl_add_u64 v[158:159], v[158:159], 0, v[140:141]
	v_pk_mul_f32 v[126:127], v[126:127], v[150:151] op_sel_hi:[1,0]
	v_pk_mul_f32 v[128:129], v[128:129], v[150:151] op_sel_hi:[1,0]
	v_pk_mul_f32 v[122:123], v[122:123], v[150:151] op_sel_hi:[1,0]
	v_pk_mul_f32 v[124:125], v[124:125], v[150:151] op_sel_hi:[1,0]
	v_cvt_pk_bf16_f32 v126, v126, v127
	v_cvt_pk_bf16_f32 v127, v128, v129
	v_cvt_pk_bf16_f32 v128, v122, v123
	v_cvt_pk_bf16_f32 v129, v124, v125
	global_store_dwordx4 v[158:159], v[126:129], off offset:0
	v_pk_mul_f32 v[118:119], v[118:119], v[150:151] op_sel_hi:[1,0]
	v_pk_mul_f32 v[120:121], v[120:121], v[150:151] op_sel_hi:[1,0]
	v_pk_mul_f32 v[114:115], v[114:115], v[150:151] op_sel_hi:[1,0]
	v_pk_mul_f32 v[116:117], v[116:117], v[150:151] op_sel_hi:[1,0]
	v_cvt_pk_bf16_f32 v118, v118, v119
	v_cvt_pk_bf16_f32 v119, v120, v121
	v_cvt_pk_bf16_f32 v120, v114, v115
	v_cvt_pk_bf16_f32 v121, v116, v117
	global_store_dwordx4 v[158:159], v[118:121], off offset:256
	v_add_u32_e32 v158, 16, v146
	v_lshlrev_b32_e32 v158, 11, v158
	v_add_u32_e32 v158, s0, v158
	v_mov_b32_e32 v159, 0
	v_lshl_add_u64 v[158:159], v[158:159], 0, v[140:141]
	v_pk_mul_f32 v[110:111], v[110:111], v[176:177] op_sel_hi:[1,0]
	v_pk_mul_f32 v[112:113], v[112:113], v[176:177] op_sel_hi:[1,0]
	v_pk_mul_f32 v[106:107], v[106:107], v[176:177] op_sel_hi:[1,0]
	v_pk_mul_f32 v[108:109], v[108:109], v[176:177] op_sel_hi:[1,0]
	v_cvt_pk_bf16_f32 v110, v110, v111
	v_cvt_pk_bf16_f32 v111, v112, v113
	v_cvt_pk_bf16_f32 v112, v106, v107
	v_cvt_pk_bf16_f32 v113, v108, v109
	global_store_dwordx4 v[158:159], v[110:113], off offset:0
	v_pk_mul_f32 v[102:103], v[102:103], v[176:177] op_sel_hi:[1,0]
	v_pk_mul_f32 v[104:105], v[104:105], v[176:177] op_sel_hi:[1,0]
	v_pk_mul_f32 v[98:99], v[98:99], v[176:177] op_sel_hi:[1,0]
	v_pk_mul_f32 v[100:101], v[100:101], v[176:177] op_sel_hi:[1,0]
	v_cvt_pk_bf16_f32 v102, v102, v103
	v_cvt_pk_bf16_f32 v103, v104, v105
	v_cvt_pk_bf16_f32 v104, v98, v99
	v_cvt_pk_bf16_f32 v105, v100, v101
	global_store_dwordx4 v[158:159], v[102:105], off offset:256
	v_add_u32_e32 v158, 32, v146
	v_lshlrev_b32_e32 v158, 11, v158
	v_add_u32_e32 v158, s0, v158
	v_mov_b32_e32 v159, 0
	v_lshl_add_u64 v[158:159], v[158:159], 0, v[140:141]
	v_pk_mul_f32 v[94:95], v[94:95], v[184:185] op_sel_hi:[1,0]
	v_pk_mul_f32 v[96:97], v[96:97], v[184:185] op_sel_hi:[1,0]
	v_pk_mul_f32 v[90:91], v[90:91], v[184:185] op_sel_hi:[1,0]
	v_pk_mul_f32 v[92:93], v[92:93], v[184:185] op_sel_hi:[1,0]
	v_cvt_pk_bf16_f32 v94, v94, v95
	v_cvt_pk_bf16_f32 v95, v96, v97
	v_cvt_pk_bf16_f32 v96, v90, v91
	v_cvt_pk_bf16_f32 v97, v92, v93
	global_store_dwordx4 v[158:159], v[94:97], off offset:0
	v_pk_mul_f32 v[86:87], v[86:87], v[184:185] op_sel_hi:[1,0]
	v_pk_mul_f32 v[88:89], v[88:89], v[184:185] op_sel_hi:[1,0]
	v_pk_mul_f32 v[82:83], v[82:83], v[184:185] op_sel_hi:[1,0]
	v_pk_mul_f32 v[84:85], v[84:85], v[184:185] op_sel_hi:[1,0]
	v_cvt_pk_bf16_f32 v86, v86, v87
	v_cvt_pk_bf16_f32 v87, v88, v89
	v_cvt_pk_bf16_f32 v88, v82, v83
	v_cvt_pk_bf16_f32 v89, v84, v85
	global_store_dwordx4 v[158:159], v[86:89], off offset:256
	v_add_u32_e32 v158, 48, v146
	v_lshlrev_b32_e32 v158, 11, v158
; __device__ __forceinline__ unsigned pk2(float lo, float hi) { f32x2 v = {lo, hi}; bf16x2_t b = __builtin_convertvector(v, bf16x2_t); return __builtin_bit_cast(unsigned, b); }
;     __device__ __forceinline__ void operator()(AccRef acc, const pg8::Unit& u, int wr, int wc, int fr, int fq) const {
;     ...
;             for (int ai = 0; ai < 2; ++ai)
; #pragma unroll
;                 for (int m = 0; m < 4; ++m) { const int row = row0 + ai * 128 + m * 16; bf16_t* rp = base + (size_t)row * 1024 + cl0; const float r = rstd(row);
; #pragma unroll
;                     for (int bj = 0; bj < 2; ++bj) { const f32x4 v0 = acc[ai][bj][m][0] * r, v1 = acc[ai][bj][m][1] * r;
;                         u32x4 w; w.x = pk2(v0[0], v0[1]); w.y = pk2(v0[2], v0[3]); w.z = pk2(v1[0], v1[1]); w.w = pk2(v1[2], v1[3]);
;                         *(u32x4*)(rp + bj * 128) = w; }
	v_add_u32_e32 v158, s0, v158
	v_mov_b32_e32 v159, 0
	v_lshl_add_u64 v[158:159], v[158:159], 0, v[140:141]
	v_pk_mul_f32 v[78:79], v[78:79], v[192:193] op_sel_hi:[1,0]
	v_pk_mul_f32 v[80:81], v[80:81], v[192:193] op_sel_hi:[1,0]
	v_pk_mul_f32 v[74:75], v[74:75], v[192:193] op_sel_hi:[1,0]
	v_pk_mul_f32 v[76:77], v[76:77], v[192:193] op_sel_hi:[1,0]
	v_cvt_pk_bf16_f32 v78, v78, v79
	v_cvt_pk_bf16_f32 v79, v80, v81
	v_cvt_pk_bf16_f32 v80, v74, v75
	v_cvt_pk_bf16_f32 v81, v76, v77
	global_store_dwordx4 v[158:159], v[78:81], off offset:0
	v_pk_mul_f32 v[70:71], v[70:71], v[192:193] op_sel_hi:[1,0]
	v_pk_mul_f32 v[72:73], v[72:73], v[192:193] op_sel_hi:[1,0]
	v_pk_mul_f32 v[66:67], v[66:67], v[192:193] op_sel_hi:[1,0]
	v_pk_mul_f32 v[68:69], v[68:69], v[192:193] op_sel_hi:[1,0]
	v_cvt_pk_bf16_f32 v70, v70, v71
	v_cvt_pk_bf16_f32 v71, v72, v73
	v_cvt_pk_bf16_f32 v72, v66, v67
	v_cvt_pk_bf16_f32 v73, v68, v69
	global_store_dwordx4 v[158:159], v[70:73], off offset:256
	v_add_u32_e32 v158, 128, v146
	v_lshlrev_b32_e32 v158, 11, v158
	v_add_u32_e32 v158, s0, v158
	v_mov_b32_e32 v159, 0
	v_lshl_add_u64 v[158:159], v[158:159], 0, v[140:141]
	v_pk_mul_f32 v[62:63], v[62:63], v[200:201] op_sel_hi:[1,0]
	v_pk_mul_f32 v[64:65], v[64:65], v[200:201] op_sel_hi:[1,0]
	v_pk_mul_f32 v[58:59], v[58:59], v[200:201] op_sel_hi:[1,0]
	v_pk_mul_f32 v[60:61], v[60:61], v[200:201] op_sel_hi:[1,0]
	v_cvt_pk_bf16_f32 v62, v62, v63
	v_cvt_pk_bf16_f32 v63, v64, v65
	v_cvt_pk_bf16_f32 v64, v58, v59
	v_cvt_pk_bf16_f32 v65, v60, v61
	global_store_dwordx4 v[158:159], v[62:65], off offset:0
	v_pk_mul_f32 v[54:55], v[54:55], v[200:201] op_sel_hi:[1,0]
	v_pk_mul_f32 v[56:57], v[56:57], v[200:201] op_sel_hi:[1,0]
	v_pk_mul_f32 v[50:51], v[50:51], v[200:201] op_sel_hi:[1,0]
	v_pk_mul_f32 v[52:53], v[52:53], v[200:201] op_sel_hi:[1,0]
	v_cvt_pk_bf16_f32 v54, v54, v55
	v_cvt_pk_bf16_f32 v55, v56, v57
	v_cvt_pk_bf16_f32 v56, v50, v51
	v_cvt_pk_bf16_f32 v57, v52, v53
	global_store_dwordx4 v[158:159], v[54:57], off offset:256
	v_add_u32_e32 v158, 144, v146
	v_lshlrev_b32_e32 v158, 11, v158
	v_add_u32_e32 v158, s0, v158
	v_mov_b32_e32 v159, 0
	v_lshl_add_u64 v[158:159], v[158:159], 0, v[140:141]
	v_pk_mul_f32 v[46:47], v[46:47], v[224:225] op_sel_hi:[1,0]
	v_pk_mul_f32 v[48:49], v[48:49], v[224:225] op_sel_hi:[1,0]
	v_pk_mul_f32 v[42:43], v[42:43], v[224:225] op_sel_hi:[1,0]
	v_pk_mul_f32 v[44:45], v[44:45], v[224:225] op_sel_hi:[1,0]
	v_cvt_pk_bf16_f32 v46, v46, v47
	v_cvt_pk_bf16_f32 v47, v48, v49
	v_cvt_pk_bf16_f32 v48, v42, v43
	v_cvt_pk_bf16_f32 v49, v44, v45
	global_store_dwordx4 v[158:159], v[46:49], off offset:0
	v_pk_mul_f32 v[38:39], v[38:39], v[224:225] op_sel_hi:[1,0]
	v_pk_mul_f32 v[40:41], v[40:41], v[224:225] op_sel_hi:[1,0]
	v_pk_mul_f32 v[34:35], v[34:35], v[224:225] op_sel_hi:[1,0]
	v_pk_mul_f32 v[36:37], v[36:37], v[224:225] op_sel_hi:[1,0]
	v_cvt_pk_bf16_f32 v38, v38, v39
	v_cvt_pk_bf16_f32 v39, v40, v41
	v_cvt_pk_bf16_f32 v40, v34, v35
	v_cvt_pk_bf16_f32 v41, v36, v37
	global_store_dwordx4 v[158:159], v[38:41], off offset:256
	v_add_u32_e32 v158, 160, v146
	v_lshlrev_b32_e32 v158, 11, v158
	v_add_u32_e32 v158, s0, v158
	v_mov_b32_e32 v159, 0
	v_lshl_add_u64 v[158:159], v[158:159], 0, v[140:141]
	v_pk_mul_f32 v[30:31], v[30:31], v[232:233] op_sel_hi:[1,0]
	v_pk_mul_f32 v[32:33], v[32:33], v[232:233] op_sel_hi:[1,0]
	v_pk_mul_f32 v[26:27], v[26:27], v[232:233] op_sel_hi:[1,0]
	v_pk_mul_f32 v[28:29], v[28:29], v[232:233] op_sel_hi:[1,0]
	v_cvt_pk_bf16_f32 v30, v30, v31
	v_cvt_pk_bf16_f32 v31, v32, v33
	v_cvt_pk_bf16_f32 v32, v26, v27
	v_cvt_pk_bf16_f32 v33, v28, v29
	global_store_dwordx4 v[158:159], v[30:33], off offset:0
	v_pk_mul_f32 v[22:23], v[22:23], v[232:233] op_sel_hi:[1,0]
	v_pk_mul_f32 v[24:25], v[24:25], v[232:233] op_sel_hi:[1,0]
	v_pk_mul_f32 v[18:19], v[18:19], v[232:233] op_sel_hi:[1,0]
	v_pk_mul_f32 v[20:21], v[20:21], v[232:233] op_sel_hi:[1,0]
	v_cvt_pk_bf16_f32 v22, v22, v23
	v_cvt_pk_bf16_f32 v23, v24, v25
	v_cvt_pk_bf16_f32 v24, v18, v19
	v_cvt_pk_bf16_f32 v25, v20, v21
	global_store_dwordx4 v[158:159], v[22:25], off offset:256
	v_add_u32_e32 v158, 176, v146
	v_lshlrev_b32_e32 v158, 11, v158
	v_add_u32_e32 v158, s0, v158
	v_mov_b32_e32 v159, 0
	v_lshl_add_u64 v[158:159], v[158:159], 0, v[140:141]
	v_pk_mul_f32 v[14:15], v[14:15], v[240:241] op_sel_hi:[1,0]
	v_pk_mul_f32 v[16:17], v[16:17], v[240:241] op_sel_hi:[1,0]
	v_pk_mul_f32 v[10:11], v[10:11], v[240:241] op_sel_hi:[1,0]
	v_pk_mul_f32 v[12:13], v[12:13], v[240:241] op_sel_hi:[1,0]
	v_cvt_pk_bf16_f32 v14, v14, v15
	v_cvt_pk_bf16_f32 v15, v16, v17
	v_cvt_pk_bf16_f32 v16, v10, v11
	v_cvt_pk_bf16_f32 v17, v12, v13
	global_store_dwordx4 v[158:159], v[14:17], off offset:0
	v_pk_mul_f32 v[6:7], v[6:7], v[240:241] op_sel_hi:[1,0]
	v_pk_mul_f32 v[8:9], v[8:9], v[240:241] op_sel_hi:[1,0]
	v_pk_mul_f32 v[2:3], v[2:3], v[240:241] op_sel_hi:[1,0]
	v_pk_mul_f32 v[4:5], v[4:5], v[240:241] op_sel_hi:[1,0]
	v_cvt_pk_bf16_f32 v6, v6, v7
	v_cvt_pk_bf16_f32 v7, v8, v9
	v_cvt_pk_bf16_f32 v8, v2, v3
	v_cvt_pk_bf16_f32 v9, v4, v5
	global_store_dwordx4 v[158:159], v[6:9], off offset:256
	s_branch .LBB0_905
; __device__ __forceinline__ unsigned pk2(float lo, float hi) { f32x2 v = {lo, hi}; bf16x2_t b = __builtin_convertvector(v, bf16x2_t); return __builtin_bit_cast(unsigned, b); }
;     __device__ __forceinline__ float rstd(int row) const {
;         const float* ssq = (const float*)(ws + WS_SSQ) + (size_t)row * 16 + (WHICH ? 8 : 0);
;         const f32x4 a = *(const f32x4*)ssq; float s = (a[0] + a[1]) + (a[2] + a[3]);
;         if (WHICH == 0) { const f32x4 b = *(const f32x4*)(ssq + 4); s += (b[0] + b[1]) + (b[2] + b[3]); }
;         return rsqrtf(s * (WHICH ? (1.f / 256.f) : (1.f / 512.f)) + 1e-6f);
;     __device__ __forceinline__ void operator()(AccRef acc, const pg8::Unit& u, int wr, int wc, int fr, int fq) const {
;     ...
;         } else {
;             bf16_t* base = (bf16_t*)(ws + WS_QAR) + (pn - 4) * 256;
;             const f32x2* cs = (const f32x2*)(ws + WS_CS);
; #pragma unroll
;             for (int ai = 0; ai < 2; ++ai)
; #pragma unroll
;                 for (int m = 0; m < 4; ++m) { const int row = row0 + ai * 128 + m * 16; bf16_t* rp = base + (size_t)row * 512 + cl0; const float r = rstd(row);
; #pragma unroll
;                     for (int bj = 0; bj < 2; ++bj) { const int j0 = ((bj * 128 + cl0) & 63) >> 1;
;                         const f32x4 c01 = *(const f32x4*)(cs + (size_t)row * 32 + j0), c23 = *(const f32x4*)(cs + (size_t)row * 32 + j0 + 2);
;                         const f32x4 v0 = acc[ai][bj][m][0] * r, v1 = acc[ai][bj][m][1] * r;
;                         u32x4 w;
;                         w.x = pk2(v0[0] * c01[0] - v0[1] * c01[1], v0[1] * c01[0] + v0[0] * c01[1]);
;                         w.y = pk2(v0[2] * c01[2] - v0[3] * c01[3], v0[3] * c01[2] + v0[2] * c01[3]);
;                         w.z = pk2(v1[0] * c23[0] - v1[1] * c23[1], v1[1] * c23[0] + v1[0] * c23[1]);
;                         w.w = pk2(v1[2] * c23[2] - v1[3] * c23[3], v1[3] * c23[2] + v1[2] * c23[3]);
;                         *(u32x4*)(rp + bj * 128) = w; }
.Lep2q_rope:
	s_add_i32 s0, s0, 0xfffff800
	v_add_u32_e32 v160, 0, v147
	global_load_dwordx4 v[150:153], v160, s[4:5]
	global_load_dwordx4 v[154:157], v160, s[4:5] offset:16
	v_add_u32_e32 v158, 0, v146
	v_lshlrev_b32_e32 v158, 8, v158
	v_mov_b32_e32 v159, 0
	v_lshl_add_u64 v[158:159], v[158:159], 0, v[138:139]
	global_load_dwordx4 v[176:179], v[158:159], off
	global_load_dwordx4 v[180:183], v[158:159], off offset:16
	v_add_u32_e32 v160, 1024, v147
	global_load_dwordx4 v[184:187], v160, s[4:5]
	global_load_dwordx4 v[188:191], v160, s[4:5] offset:16
	v_add_u32_e32 v158, 16, v146
	v_lshlrev_b32_e32 v158, 8, v158
	v_mov_b32_e32 v159, 0
	v_lshl_add_u64 v[158:159], v[158:159], 0, v[138:139]
	global_load_dwordx4 v[192:195], v[158:159], off
	global_load_dwordx4 v[196:199], v[158:159], off offset:16
	v_add_u32_e32 v160, 2048, v147
	global_load_dwordx4 v[200:203], v160, s[4:5]
	global_load_dwordx4 v[204:207], v160, s[4:5] offset:16
	v_add_u32_e32 v158, 32, v146
	v_lshlrev_b32_e32 v158, 8, v158
	v_mov_b32_e32 v159, 0
	v_lshl_add_u64 v[158:159], v[158:159], 0, v[138:139]
	global_load_dwordx4 v[224:227], v[158:159], off
	global_load_dwordx4 v[228:231], v[158:159], off offset:16
	v_add_u32_e32 v160, 3072, v147
	global_load_dwordx4 v[232:235], v160, s[4:5]
	global_load_dwordx4 v[236:239], v160, s[4:5] offset:16
	v_add_u32_e32 v158, 48, v146
	v_lshlrev_b32_e32 v158, 8, v158
	v_mov_b32_e32 v159, 0
	v_lshl_add_u64 v[158:159], v[158:159], 0, v[138:139]
	global_load_dwordx4 v[240:243], v[158:159], off
	global_load_dwordx4 v[244:247], v[158:159], off offset:16
	s_waitcnt vmcnt(0)
	v_add_f32_e32 v150, v150, v151
	v_add_f32_e32 v152, v152, v153
	v_add_f32_e32 v154, v154, v155
	v_add_f32_e32 v156, v156, v157
	v_add_f32_e32 v150, v150, v152
	v_add_f32_e32 v154, v154, v156
	v_add_f32_e32 v150, v150, v154
	v_fmamk_f32 v150, v150, 0x3b000000, v220
	v_rsq_f32_e32 v150, v150
	v_add_f32_e32 v184, v184, v185
	v_add_f32_e32 v186, v186, v187
	v_add_f32_e32 v188, v188, v189
	v_add_f32_e32 v190, v190, v191
	v_add_f32_e32 v184, v184, v186
	v_add_f32_e32 v188, v188, v190
	v_add_f32_e32 v184, v184, v188
	v_fmamk_f32 v184, v184, 0x3b000000, v220
	v_rsq_f32_e32 v184, v184
	v_add_f32_e32 v200, v200, v201
	v_add_f32_e32 v202, v202, v203
	v_add_f32_e32 v204, v204, v205
	v_add_f32_e32 v206, v206, v207
	v_add_f32_e32 v200, v200, v202
	v_add_f32_e32 v204, v204, v206
	v_add_f32_e32 v200, v200, v204
	v_fmamk_f32 v200, v200, 0x3b000000, v220
	v_rsq_f32_e32 v200, v200
	v_add_f32_e32 v232, v232, v233
	v_add_f32_e32 v234, v234, v235
	v_add_f32_e32 v236, v236, v237
	v_add_f32_e32 v238, v238, v239
	v_add_f32_e32 v232, v232, v234
	v_add_f32_e32 v236, v236, v238
	v_add_f32_e32 v232, v232, v236
	v_fmamk_f32 v232, v232, 0x3b000000, v220
	v_rsq_f32_e32 v232, v232
	s_nop 0
	v_add_u32_e32 v158, 0, v146
	v_lshlrev_b32_e32 v158, 10, v158
	v_add_u32_e32 v158, s0, v158
	v_mov_b32_e32 v159, 0
	v_lshl_add_u64 v[158:159], v[158:159], 0, v[136:137]
	v_pk_mul_f32 v[126:127], v[126:127], v[150:151] op_sel_hi:[1,0]
	v_pk_mul_f32 v[128:129], v[128:129], v[150:151] op_sel_hi:[1,0]
	v_pk_mul_f32 v[122:123], v[122:123], v[150:151] op_sel_hi:[1,0]
	v_pk_mul_f32 v[124:125], v[124:125], v[150:151] op_sel_hi:[1,0]
	v_mul_f32_e32 v148, v127, v177
	v_mul_f32_e32 v149, v126, v177
	v_fma_f32 v148, v126, v176, -v148
	v_fma_f32 v149, v127, v176, v149
	v_cvt_pk_bf16_f32 v126, v148, v149
	v_mul_f32_e32 v148, v129, v179
	v_mul_f32_e32 v149, v128, v179
	v_fma_f32 v148, v128, v178, -v148
	v_fma_f32 v149, v129, v178, v149
	v_cvt_pk_bf16_f32 v127, v148, v149
	v_mul_f32_e32 v148, v123, v181
	v_mul_f32_e32 v149, v122, v181
	v_fma_f32 v148, v122, v180, -v148
	v_fma_f32 v149, v123, v180, v149
	v_cvt_pk_bf16_f32 v128, v148, v149
	v_mul_f32_e32 v148, v125, v183
	v_mul_f32_e32 v149, v124, v183
	v_fma_f32 v148, v124, v182, -v148
	v_fma_f32 v149, v125, v182, v149
	v_cvt_pk_bf16_f32 v129, v148, v149
	global_store_dwordx4 v[158:159], v[126:129], off offset:0
	v_pk_mul_f32 v[118:119], v[118:119], v[150:151] op_sel_hi:[1,0]
	v_pk_mul_f32 v[120:121], v[120:121], v[150:151] op_sel_hi:[1,0]
	v_pk_mul_f32 v[114:115], v[114:115], v[150:151] op_sel_hi:[1,0]
	v_pk_mul_f32 v[116:117], v[116:117], v[150:151] op_sel_hi:[1,0]
	v_mul_f32_e32 v148, v119, v177
	v_mul_f32_e32 v149, v118, v177
	v_fma_f32 v148, v118, v176, -v148
	v_fma_f32 v149, v119, v176, v149
	v_cvt_pk_bf16_f32 v118, v148, v149
	v_mul_f32_e32 v148, v121, v179
	v_mul_f32_e32 v149, v120, v179
	v_fma_f32 v148, v120, v178, -v148
	v_fma_f32 v149, v121, v178, v149
	v_cvt_pk_bf16_f32 v119, v148, v149
	v_mul_f32_e32 v148, v115, v181
	v_mul_f32_e32 v149, v114, v181
	v_fma_f32 v148, v114, v180, -v148
	v_fma_f32 v149, v115, v180, v149
	v_cvt_pk_bf16_f32 v120, v148, v149
	v_mul_f32_e32 v148, v117, v183
	v_mul_f32_e32 v149, v116, v183
	v_fma_f32 v148, v116, v182, -v148
	v_fma_f32 v149, v117, v182, v149
	v_cvt_pk_bf16_f32 v121, v148, v149
	global_store_dwordx4 v[158:159], v[118:121], off offset:256
	v_add_u32_e32 v158, 16, v146
	v_lshlrev_b32_e32 v158, 10, v158
	v_add_u32_e32 v158, s0, v158
	v_mov_b32_e32 v159, 0
	v_lshl_add_u64 v[158:159], v[158:159], 0, v[136:137]
	v_pk_mul_f32 v[110:111], v[110:111], v[184:185] op_sel_hi:[1,0]
	v_pk_mul_f32 v[112:113], v[112:113], v[184:185] op_sel_hi:[1,0]
	v_pk_mul_f32 v[106:107], v[106:107], v[184:185] op_sel_hi:[1,0]
	v_pk_mul_f32 v[108:109], v[108:109], v[184:185] op_sel_hi:[1,0]
	v_mul_f32_e32 v148, v111, v193
	v_mul_f32_e32 v149, v110, v193
	v_fma_f32 v148, v110, v192, -v148
	v_fma_f32 v149, v111, v192, v149
	v_cvt_pk_bf16_f32 v110, v148, v149
	v_mul_f32_e32 v148, v113, v195
	v_mul_f32_e32 v149, v112, v195
	v_fma_f32 v148, v112, v194, -v148
; __device__ __forceinline__ unsigned pk2(float lo, float hi) { f32x2 v = {lo, hi}; bf16x2_t b = __builtin_convertvector(v, bf16x2_t); return __builtin_bit_cast(unsigned, b); }
;     __device__ __forceinline__ void operator()(AccRef acc, const pg8::Unit& u, int wr, int wc, int fr, int fq) const {
;     ...
; #pragma unroll
;             for (int ai = 0; ai < 2; ++ai)
; #pragma unroll
;                 for (int m = 0; m < 4; ++m) { const int row = row0 + ai * 128 + m * 16; bf16_t* rp = base + (size_t)row * 512 + cl0; const float r = rstd(row);
; #pragma unroll
;                     for (int bj = 0; bj < 2; ++bj) { const int j0 = ((bj * 128 + cl0) & 63) >> 1;
;                         const f32x4 c01 = *(const f32x4*)(cs + (size_t)row * 32 + j0), c23 = *(const f32x4*)(cs + (size_t)row * 32 + j0 + 2);
;                         const f32x4 v0 = acc[ai][bj][m][0] * r, v1 = acc[ai][bj][m][1] * r;
;                         u32x4 w;
;                         w.x = pk2(v0[0] * c01[0] - v0[1] * c01[1], v0[1] * c01[0] + v0[0] * c01[1]);
;                         w.y = pk2(v0[2] * c01[2] - v0[3] * c01[3], v0[3] * c01[2] + v0[2] * c01[3]);
;                         w.z = pk2(v1[0] * c23[0] - v1[1] * c23[1], v1[1] * c23[0] + v1[0] * c23[1]);
;                         w.w = pk2(v1[2] * c23[2] - v1[3] * c23[3], v1[3] * c23[2] + v1[2] * c23[3]);
;                         *(u32x4*)(rp + bj * 128) = w; }
	v_fma_f32 v149, v113, v194, v149
	v_cvt_pk_bf16_f32 v111, v148, v149
	v_mul_f32_e32 v148, v107, v197
	v_mul_f32_e32 v149, v106, v197
	v_fma_f32 v148, v106, v196, -v148
	v_fma_f32 v149, v107, v196, v149
	v_cvt_pk_bf16_f32 v112, v148, v149
	v_mul_f32_e32 v148, v109, v199
	v_mul_f32_e32 v149, v108, v199
	v_fma_f32 v148, v108, v198, -v148
	v_fma_f32 v149, v109, v198, v149
	v_cvt_pk_bf16_f32 v113, v148, v149
	global_store_dwordx4 v[158:159], v[110:113], off offset:0
	v_pk_mul_f32 v[102:103], v[102:103], v[184:185] op_sel_hi:[1,0]
	v_pk_mul_f32 v[104:105], v[104:105], v[184:185] op_sel_hi:[1,0]
	v_pk_mul_f32 v[98:99], v[98:99], v[184:185] op_sel_hi:[1,0]
	v_pk_mul_f32 v[100:101], v[100:101], v[184:185] op_sel_hi:[1,0]
	v_mul_f32_e32 v148, v103, v193
	v_mul_f32_e32 v149, v102, v193
	v_fma_f32 v148, v102, v192, -v148
	v_fma_f32 v149, v103, v192, v149
	v_cvt_pk_bf16_f32 v102, v148, v149
	v_mul_f32_e32 v148, v105, v195
	v_mul_f32_e32 v149, v104, v195
	v_fma_f32 v148, v104, v194, -v148
	v_fma_f32 v149, v105, v194, v149
	v_cvt_pk_bf16_f32 v103, v148, v149
	v_mul_f32_e32 v148, v99, v197
	v_mul_f32_e32 v149, v98, v197
	v_fma_f32 v148, v98, v196, -v148
	v_fma_f32 v149, v99, v196, v149
	v_cvt_pk_bf16_f32 v104, v148, v149
	v_mul_f32_e32 v148, v101, v199
	v_mul_f32_e32 v149, v100, v199
	v_fma_f32 v148, v100, v198, -v148
	v_fma_f32 v149, v101, v198, v149
	v_cvt_pk_bf16_f32 v105, v148, v149
	global_store_dwordx4 v[158:159], v[102:105], off offset:256
	v_add_u32_e32 v158, 32, v146
	v_lshlrev_b32_e32 v158, 10, v158
	v_add_u32_e32 v158, s0, v158
	v_mov_b32_e32 v159, 0
	v_lshl_add_u64 v[158:159], v[158:159], 0, v[136:137]
	v_pk_mul_f32 v[94:95], v[94:95], v[200:201] op_sel_hi:[1,0]
	v_pk_mul_f32 v[96:97], v[96:97], v[200:201] op_sel_hi:[1,0]
	v_pk_mul_f32 v[90:91], v[90:91], v[200:201] op_sel_hi:[1,0]
	v_pk_mul_f32 v[92:93], v[92:93], v[200:201] op_sel_hi:[1,0]
	v_mul_f32_e32 v148, v95, v225
	v_mul_f32_e32 v149, v94, v225
	v_fma_f32 v148, v94, v224, -v148
	v_fma_f32 v149, v95, v224, v149
	v_cvt_pk_bf16_f32 v94, v148, v149
	v_mul_f32_e32 v148, v97, v227
	v_mul_f32_e32 v149, v96, v227
	v_fma_f32 v148, v96, v226, -v148
	v_fma_f32 v149, v97, v226, v149
	v_cvt_pk_bf16_f32 v95, v148, v149
	v_mul_f32_e32 v148, v91, v229
	v_mul_f32_e32 v149, v90, v229
	v_fma_f32 v148, v90, v228, -v148
	v_fma_f32 v149, v91, v228, v149
	v_cvt_pk_bf16_f32 v96, v148, v149
	v_mul_f32_e32 v148, v93, v231
	v_mul_f32_e32 v149, v92, v231
	v_fma_f32 v148, v92, v230, -v148
	v_fma_f32 v149, v93, v230, v149
	v_cvt_pk_bf16_f32 v97, v148, v149
	global_store_dwordx4 v[158:159], v[94:97], off offset:0
	v_pk_mul_f32 v[86:87], v[86:87], v[200:201] op_sel_hi:[1,0]
	v_pk_mul_f32 v[88:89], v[88:89], v[200:201] op_sel_hi:[1,0]
	v_pk_mul_f32 v[82:83], v[82:83], v[200:201] op_sel_hi:[1,0]
	v_pk_mul_f32 v[84:85], v[84:85], v[200:201] op_sel_hi:[1,0]
	v_mul_f32_e32 v148, v87, v225
	v_mul_f32_e32 v149, v86, v225
	v_fma_f32 v148, v86, v224, -v148
	v_fma_f32 v149, v87, v224, v149
	v_cvt_pk_bf16_f32 v86, v148, v149
	v_mul_f32_e32 v148, v89, v227
	v_mul_f32_e32 v149, v88, v227
	v_fma_f32 v148, v88, v226, -v148
	v_fma_f32 v149, v89, v226, v149
	v_cvt_pk_bf16_f32 v87, v148, v149
	v_mul_f32_e32 v148, v83, v229
	v_mul_f32_e32 v149, v82, v229
	v_fma_f32 v148, v82, v228, -v148
	v_fma_f32 v149, v83, v228, v149
	v_cvt_pk_bf16_f32 v88, v148, v149
	v_mul_f32_e32 v148, v85, v231
	v_mul_f32_e32 v149, v84, v231
	v_fma_f32 v148, v84, v230, -v148
	v_fma_f32 v149, v85, v230, v149
	v_cvt_pk_bf16_f32 v89, v148, v149
	global_store_dwordx4 v[158:159], v[86:89], off offset:256
	v_add_u32_e32 v158, 48, v146
	v_lshlrev_b32_e32 v158, 10, v158
	v_add_u32_e32 v158, s0, v158
	v_mov_b32_e32 v159, 0
	v_lshl_add_u64 v[158:159], v[158:159], 0, v[136:137]
	v_pk_mul_f32 v[78:79], v[78:79], v[232:233] op_sel_hi:[1,0]
	v_pk_mul_f32 v[80:81], v[80:81], v[232:233] op_sel_hi:[1,0]
	v_pk_mul_f32 v[74:75], v[74:75], v[232:233] op_sel_hi:[1,0]
	v_pk_mul_f32 v[76:77], v[76:77], v[232:233] op_sel_hi:[1,0]
	v_mul_f32_e32 v148, v79, v241
	v_mul_f32_e32 v149, v78, v241
	v_fma_f32 v148, v78, v240, -v148
	v_fma_f32 v149, v79, v240, v149
	v_cvt_pk_bf16_f32 v78, v148, v149
	v_mul_f32_e32 v148, v81, v243
	v_mul_f32_e32 v149, v80, v243
	v_fma_f32 v148, v80, v242, -v148
	v_fma_f32 v149, v81, v242, v149
	v_cvt_pk_bf16_f32 v79, v148, v149
	v_mul_f32_e32 v148, v75, v245
	v_mul_f32_e32 v149, v74, v245
	v_fma_f32 v148, v74, v244, -v148
	v_fma_f32 v149, v75, v244, v149
	v_cvt_pk_bf16_f32 v80, v148, v149
	v_mul_f32_e32 v148, v77, v247
	v_mul_f32_e32 v149, v76, v247
	v_fma_f32 v148, v76, v246, -v148
	v_fma_f32 v149, v77, v246, v149
	v_cvt_pk_bf16_f32 v81, v148, v149
	global_store_dwordx4 v[158:159], v[78:81], off offset:0
	v_pk_mul_f32 v[70:71], v[70:71], v[232:233] op_sel_hi:[1,0]
	v_pk_mul_f32 v[72:73], v[72:73], v[232:233] op_sel_hi:[1,0]
	v_pk_mul_f32 v[66:67], v[66:67], v[232:233] op_sel_hi:[1,0]
	v_pk_mul_f32 v[68:69], v[68:69], v[232:233] op_sel_hi:[1,0]
	v_mul_f32_e32 v148, v71, v241
	v_mul_f32_e32 v149, v70, v241
	v_fma_f32 v148, v70, v240, -v148
	v_fma_f32 v149, v71, v240, v149
	v_cvt_pk_bf16_f32 v70, v148, v149
	v_mul_f32_e32 v148, v73, v243
	v_mul_f32_e32 v149, v72, v243
	v_fma_f32 v148, v72, v242, -v148
	v_fma_f32 v149, v73, v242, v149
	v_cvt_pk_bf16_f32 v71, v148, v149
	v_mul_f32_e32 v148, v67, v245
	v_mul_f32_e32 v149, v66, v245
	v_fma_f32 v148, v66, v244, -v148
	v_fma_f32 v149, v67, v244, v149
	v_cvt_pk_bf16_f32 v72, v148, v149
	v_mul_f32_e32 v148, v69, v247
	v_mul_f32_e32 v149, v68, v247
	v_fma_f32 v148, v68, v246, -v148
	v_fma_f32 v149, v69, v246, v149
	v_cvt_pk_bf16_f32 v73, v148, v149
	global_store_dwordx4 v[158:159], v[70:73], off offset:256
; __device__ __forceinline__ unsigned pk2(float lo, float hi) { f32x2 v = {lo, hi}; bf16x2_t b = __builtin_convertvector(v, bf16x2_t); return __builtin_bit_cast(unsigned, b); }
;     __device__ __forceinline__ float rstd(int row) const {
;         const float* ssq = (const float*)(ws + WS_SSQ) + (size_t)row * 16 + (WHICH ? 8 : 0);
;         const f32x4 a = *(const f32x4*)ssq; float s = (a[0] + a[1]) + (a[2] + a[3]);
;         if (WHICH == 0) { const f32x4 b = *(const f32x4*)(ssq + 4); s += (b[0] + b[1]) + (b[2] + b[3]); }
;         return rsqrtf(s * (WHICH ? (1.f / 256.f) : (1.f / 512.f)) + 1e-6f);
;     __device__ __forceinline__ void operator()(AccRef acc, const pg8::Unit& u, int wr, int wc, int fr, int fq) const {
;     ...
; #pragma unroll
;             for (int ai = 0; ai < 2; ++ai)
; #pragma unroll
;                 for (int m = 0; m < 4; ++m) { const int row = row0 + ai * 128 + m * 16; bf16_t* rp = base + (size_t)row * 512 + cl0; const float r = rstd(row);
; #pragma unroll
;                     for (int bj = 0; bj < 2; ++bj) { const int j0 = ((bj * 128 + cl0) & 63) >> 1;
;                         const f32x4 c01 = *(const f32x4*)(cs + (size_t)row * 32 + j0), c23 = *(const f32x4*)(cs + (size_t)row * 32 + j0 + 2);
;                         const f32x4 v0 = acc[ai][bj][m][0] * r, v1 = acc[ai][bj][m][1] * r;
;                         u32x4 w;
;                         w.x = pk2(v0[0] * c01[0] - v0[1] * c01[1], v0[1] * c01[0] + v0[0] * c01[1]);
;                         w.y = pk2(v0[2] * c01[2] - v0[3] * c01[3], v0[3] * c01[2] + v0[2] * c01[3]);
;                         w.z = pk2(v1[0] * c23[0] - v1[1] * c23[1], v1[1] * c23[0] + v1[0] * c23[1]);
;                         w.w = pk2(v1[2] * c23[2] - v1[3] * c23[3], v1[3] * c23[2] + v1[2] * c23[3]);
;                         *(u32x4*)(rp + bj * 128) = w; }
	v_add_u32_e32 v160, 8192, v147
	global_load_dwordx4 v[150:153], v160, s[4:5]
	global_load_dwordx4 v[154:157], v160, s[4:5] offset:16
	v_add_u32_e32 v158, 128, v146
	v_lshlrev_b32_e32 v158, 8, v158
	v_mov_b32_e32 v159, 0
	v_lshl_add_u64 v[158:159], v[158:159], 0, v[138:139]
	global_load_dwordx4 v[176:179], v[158:159], off
	global_load_dwordx4 v[180:183], v[158:159], off offset:16
	v_add_u32_e32 v160, 9216, v147
	global_load_dwordx4 v[184:187], v160, s[4:5]
	global_load_dwordx4 v[188:191], v160, s[4:5] offset:16
	v_add_u32_e32 v158, 144, v146
	v_lshlrev_b32_e32 v158, 8, v158
	v_mov_b32_e32 v159, 0
	v_lshl_add_u64 v[158:159], v[158:159], 0, v[138:139]
	global_load_dwordx4 v[192:195], v[158:159], off
	global_load_dwordx4 v[196:199], v[158:159], off offset:16
	v_add_u32_e32 v160, 10240, v147
	global_load_dwordx4 v[200:203], v160, s[4:5]
	global_load_dwordx4 v[204:207], v160, s[4:5] offset:16
	v_add_u32_e32 v158, 160, v146
	v_lshlrev_b32_e32 v158, 8, v158
	v_mov_b32_e32 v159, 0
	v_lshl_add_u64 v[158:159], v[158:159], 0, v[138:139]
	global_load_dwordx4 v[224:227], v[158:159], off
	global_load_dwordx4 v[228:231], v[158:159], off offset:16
	v_add_u32_e32 v160, 11264, v147
	global_load_dwordx4 v[232:235], v160, s[4:5]
	global_load_dwordx4 v[236:239], v160, s[4:5] offset:16
	v_add_u32_e32 v158, 176, v146
	v_lshlrev_b32_e32 v158, 8, v158
	v_mov_b32_e32 v159, 0
	v_lshl_add_u64 v[158:159], v[158:159], 0, v[138:139]
	global_load_dwordx4 v[240:243], v[158:159], off
	global_load_dwordx4 v[244:247], v[158:159], off offset:16
	s_waitcnt vmcnt(0)
	v_add_f32_e32 v150, v150, v151
	v_add_f32_e32 v152, v152, v153
	v_add_f32_e32 v154, v154, v155
	v_add_f32_e32 v156, v156, v157
	v_add_f32_e32 v150, v150, v152
	v_add_f32_e32 v154, v154, v156
	v_add_f32_e32 v150, v150, v154
	v_fmamk_f32 v150, v150, 0x3b000000, v220
	v_rsq_f32_e32 v150, v150
	v_add_f32_e32 v184, v184, v185
	v_add_f32_e32 v186, v186, v187
	v_add_f32_e32 v188, v188, v189
	v_add_f32_e32 v190, v190, v191
	v_add_f32_e32 v184, v184, v186
	v_add_f32_e32 v188, v188, v190
	v_add_f32_e32 v184, v184, v188
	v_fmamk_f32 v184, v184, 0x3b000000, v220
	v_rsq_f32_e32 v184, v184
	v_add_f32_e32 v200, v200, v201
	v_add_f32_e32 v202, v202, v203
	v_add_f32_e32 v204, v204, v205
	v_add_f32_e32 v206, v206, v207
	v_add_f32_e32 v200, v200, v202
	v_add_f32_e32 v204, v204, v206
	v_add_f32_e32 v200, v200, v204
	v_fmamk_f32 v200, v200, 0x3b000000, v220
	v_rsq_f32_e32 v200, v200
	v_add_f32_e32 v232, v232, v233
	v_add_f32_e32 v234, v234, v235
	v_add_f32_e32 v236, v236, v237
	v_add_f32_e32 v238, v238, v239
	v_add_f32_e32 v232, v232, v234
	v_add_f32_e32 v236, v236, v238
	v_add_f32_e32 v232, v232, v236
	v_fmamk_f32 v232, v232, 0x3b000000, v220
	v_rsq_f32_e32 v232, v232
	s_nop 0
	v_add_u32_e32 v158, 128, v146
	v_lshlrev_b32_e32 v158, 10, v158
	v_add_u32_e32 v158, s0, v158
	v_mov_b32_e32 v159, 0
	v_lshl_add_u64 v[158:159], v[158:159], 0, v[136:137]
	v_pk_mul_f32 v[62:63], v[62:63], v[150:151] op_sel_hi:[1,0]
	v_pk_mul_f32 v[64:65], v[64:65], v[150:151] op_sel_hi:[1,0]
	v_pk_mul_f32 v[58:59], v[58:59], v[150:151] op_sel_hi:[1,0]
	v_pk_mul_f32 v[60:61], v[60:61], v[150:151] op_sel_hi:[1,0]
	v_mul_f32_e32 v148, v63, v177
	v_mul_f32_e32 v149, v62, v177
	v_fma_f32 v148, v62, v176, -v148
	v_fma_f32 v149, v63, v176, v149
	v_cvt_pk_bf16_f32 v62, v148, v149
	v_mul_f32_e32 v148, v65, v179
	v_mul_f32_e32 v149, v64, v179
	v_fma_f32 v148, v64, v178, -v148
	v_fma_f32 v149, v65, v178, v149
	v_cvt_pk_bf16_f32 v63, v148, v149
	v_mul_f32_e32 v148, v59, v181
	v_mul_f32_e32 v149, v58, v181
	v_fma_f32 v148, v58, v180, -v148
	v_fma_f32 v149, v59, v180, v149
	v_cvt_pk_bf16_f32 v64, v148, v149
	v_mul_f32_e32 v148, v61, v183
	v_mul_f32_e32 v149, v60, v183
	v_fma_f32 v148, v60, v182, -v148
	v_fma_f32 v149, v61, v182, v149
	v_cvt_pk_bf16_f32 v65, v148, v149
	global_store_dwordx4 v[158:159], v[62:65], off offset:0
	v_pk_mul_f32 v[54:55], v[54:55], v[150:151] op_sel_hi:[1,0]
	v_pk_mul_f32 v[56:57], v[56:57], v[150:151] op_sel_hi:[1,0]
	v_pk_mul_f32 v[50:51], v[50:51], v[150:151] op_sel_hi:[1,0]
	v_pk_mul_f32 v[52:53], v[52:53], v[150:151] op_sel_hi:[1,0]
	v_mul_f32_e32 v148, v55, v177
	v_mul_f32_e32 v149, v54, v177
	v_fma_f32 v148, v54, v176, -v148
	v_fma_f32 v149, v55, v176, v149
	v_cvt_pk_bf16_f32 v54, v148, v149
	v_mul_f32_e32 v148, v57, v179
	v_mul_f32_e32 v149, v56, v179
	v_fma_f32 v148, v56, v178, -v148
	v_fma_f32 v149, v57, v178, v149
	v_cvt_pk_bf16_f32 v55, v148, v149
	v_mul_f32_e32 v148, v51, v181
	v_mul_f32_e32 v149, v50, v181
	v_fma_f32 v148, v50, v180, -v148
	v_fma_f32 v149, v51, v180, v149
	v_cvt_pk_bf16_f32 v56, v148, v149
	v_mul_f32_e32 v148, v53, v183
	v_mul_f32_e32 v149, v52, v183
	v_fma_f32 v148, v52, v182, -v148
	v_fma_f32 v149, v53, v182, v149
	v_cvt_pk_bf16_f32 v57, v148, v149
	global_store_dwordx4 v[158:159], v[54:57], off offset:256
	v_add_u32_e32 v158, 144, v146
	v_lshlrev_b32_e32 v158, 10, v158
	v_add_u32_e32 v158, s0, v158
	v_mov_b32_e32 v159, 0
	v_lshl_add_u64 v[158:159], v[158:159], 0, v[136:137]
	v_pk_mul_f32 v[46:47], v[46:47], v[184:185] op_sel_hi:[1,0]
	v_pk_mul_f32 v[48:49], v[48:49], v[184:185] op_sel_hi:[1,0]
	v_pk_mul_f32 v[42:43], v[42:43], v[184:185] op_sel_hi:[1,0]
	v_pk_mul_f32 v[44:45], v[44:45], v[184:185] op_sel_hi:[1,0]
	v_mul_f32_e32 v148, v47, v193
	v_mul_f32_e32 v149, v46, v193
	v_fma_f32 v148, v46, v192, -v148
	v_fma_f32 v149, v47, v192, v149
	v_cvt_pk_bf16_f32 v46, v148, v149
	v_mul_f32_e32 v148, v49, v195
	v_mul_f32_e32 v149, v48, v195
	v_fma_f32 v148, v48, v194, -v148
	v_fma_f32 v149, v49, v194, v149
; __device__ __forceinline__ unsigned pk2(float lo, float hi) { f32x2 v = {lo, hi}; bf16x2_t b = __builtin_convertvector(v, bf16x2_t); return __builtin_bit_cast(unsigned, b); }
;     __device__ __forceinline__ void operator()(AccRef acc, const pg8::Unit& u, int wr, int wc, int fr, int fq) const {
;     ...
; #pragma unroll
;             for (int ai = 0; ai < 2; ++ai)
; #pragma unroll
;                 for (int m = 0; m < 4; ++m) { const int row = row0 + ai * 128 + m * 16; bf16_t* rp = base + (size_t)row * 512 + cl0; const float r = rstd(row);
; #pragma unroll
;                     for (int bj = 0; bj < 2; ++bj) { const int j0 = ((bj * 128 + cl0) & 63) >> 1;
;                         const f32x4 c01 = *(const f32x4*)(cs + (size_t)row * 32 + j0), c23 = *(const f32x4*)(cs + (size_t)row * 32 + j0 + 2);
;                         const f32x4 v0 = acc[ai][bj][m][0] * r, v1 = acc[ai][bj][m][1] * r;
;                         u32x4 w;
;                         w.x = pk2(v0[0] * c01[0] - v0[1] * c01[1], v0[1] * c01[0] + v0[0] * c01[1]);
;                         w.y = pk2(v0[2] * c01[2] - v0[3] * c01[3], v0[3] * c01[2] + v0[2] * c01[3]);
;                         w.z = pk2(v1[0] * c23[0] - v1[1] * c23[1], v1[1] * c23[0] + v1[0] * c23[1]);
;                         w.w = pk2(v1[2] * c23[2] - v1[3] * c23[3], v1[3] * c23[2] + v1[2] * c23[3]);
;                         *(u32x4*)(rp + bj * 128) = w; }
;                     asm volatile("" ::: "memory"); }
;         }
	v_cvt_pk_bf16_f32 v47, v148, v149
	v_mul_f32_e32 v148, v43, v197
	v_mul_f32_e32 v149, v42, v197
	v_fma_f32 v148, v42, v196, -v148
	v_fma_f32 v149, v43, v196, v149
	v_cvt_pk_bf16_f32 v48, v148, v149
	v_mul_f32_e32 v148, v45, v199
	v_mul_f32_e32 v149, v44, v199
	v_fma_f32 v148, v44, v198, -v148
	v_fma_f32 v149, v45, v198, v149
	v_cvt_pk_bf16_f32 v49, v148, v149
	global_store_dwordx4 v[158:159], v[46:49], off offset:0
	v_pk_mul_f32 v[38:39], v[38:39], v[184:185] op_sel_hi:[1,0]
	v_pk_mul_f32 v[40:41], v[40:41], v[184:185] op_sel_hi:[1,0]
	v_pk_mul_f32 v[34:35], v[34:35], v[184:185] op_sel_hi:[1,0]
	v_pk_mul_f32 v[36:37], v[36:37], v[184:185] op_sel_hi:[1,0]
	v_mul_f32_e32 v148, v39, v193
	v_mul_f32_e32 v149, v38, v193
	v_fma_f32 v148, v38, v192, -v148
	v_fma_f32 v149, v39, v192, v149
	v_cvt_pk_bf16_f32 v38, v148, v149
	v_mul_f32_e32 v148, v41, v195
	v_mul_f32_e32 v149, v40, v195
	v_fma_f32 v148, v40, v194, -v148
	v_fma_f32 v149, v41, v194, v149
	v_cvt_pk_bf16_f32 v39, v148, v149
	v_mul_f32_e32 v148, v35, v197
	v_mul_f32_e32 v149, v34, v197
	v_fma_f32 v148, v34, v196, -v148
	v_fma_f32 v149, v35, v196, v149
	v_cvt_pk_bf16_f32 v40, v148, v149
	v_mul_f32_e32 v148, v37, v199
	v_mul_f32_e32 v149, v36, v199
	v_fma_f32 v148, v36, v198, -v148
	v_fma_f32 v149, v37, v198, v149
	v_cvt_pk_bf16_f32 v41, v148, v149
	global_store_dwordx4 v[158:159], v[38:41], off offset:256
	v_add_u32_e32 v158, 160, v146
	v_lshlrev_b32_e32 v158, 10, v158
	v_add_u32_e32 v158, s0, v158
	v_mov_b32_e32 v159, 0
	v_lshl_add_u64 v[158:159], v[158:159], 0, v[136:137]
	v_pk_mul_f32 v[30:31], v[30:31], v[200:201] op_sel_hi:[1,0]
	v_pk_mul_f32 v[32:33], v[32:33], v[200:201] op_sel_hi:[1,0]
	v_pk_mul_f32 v[26:27], v[26:27], v[200:201] op_sel_hi:[1,0]
	v_pk_mul_f32 v[28:29], v[28:29], v[200:201] op_sel_hi:[1,0]
	v_mul_f32_e32 v148, v31, v225
	v_mul_f32_e32 v149, v30, v225
	v_fma_f32 v148, v30, v224, -v148
	v_fma_f32 v149, v31, v224, v149
	v_cvt_pk_bf16_f32 v30, v148, v149
	v_mul_f32_e32 v148, v33, v227
	v_mul_f32_e32 v149, v32, v227
	v_fma_f32 v148, v32, v226, -v148
	v_fma_f32 v149, v33, v226, v149
	v_cvt_pk_bf16_f32 v31, v148, v149
	v_mul_f32_e32 v148, v27, v229
	v_mul_f32_e32 v149, v26, v229
	v_fma_f32 v148, v26, v228, -v148
	v_fma_f32 v149, v27, v228, v149
	v_cvt_pk_bf16_f32 v32, v148, v149
	v_mul_f32_e32 v148, v29, v231
	v_mul_f32_e32 v149, v28, v231
	v_fma_f32 v148, v28, v230, -v148
	v_fma_f32 v149, v29, v230, v149
	v_cvt_pk_bf16_f32 v33, v148, v149
	global_store_dwordx4 v[158:159], v[30:33], off offset:0
	v_pk_mul_f32 v[22:23], v[22:23], v[200:201] op_sel_hi:[1,0]
	v_pk_mul_f32 v[24:25], v[24:25], v[200:201] op_sel_hi:[1,0]
	v_pk_mul_f32 v[18:19], v[18:19], v[200:201] op_sel_hi:[1,0]
	v_pk_mul_f32 v[20:21], v[20:21], v[200:201] op_sel_hi:[1,0]
	v_mul_f32_e32 v148, v23, v225
	v_mul_f32_e32 v149, v22, v225
	v_fma_f32 v148, v22, v224, -v148
	v_fma_f32 v149, v23, v224, v149
	v_cvt_pk_bf16_f32 v22, v148, v149
	v_mul_f32_e32 v148, v25, v227
	v_mul_f32_e32 v149, v24, v227
	v_fma_f32 v148, v24, v226, -v148
	v_fma_f32 v149, v25, v226, v149
	v_cvt_pk_bf16_f32 v23, v148, v149
	v_mul_f32_e32 v148, v19, v229
	v_mul_f32_e32 v149, v18, v229
	v_fma_f32 v148, v18, v228, -v148
	v_fma_f32 v149, v19, v228, v149
	v_cvt_pk_bf16_f32 v24, v148, v149
	v_mul_f32_e32 v148, v21, v231
	v_mul_f32_e32 v149, v20, v231
	v_fma_f32 v148, v20, v230, -v148
	v_fma_f32 v149, v21, v230, v149
	v_cvt_pk_bf16_f32 v25, v148, v149
	global_store_dwordx4 v[158:159], v[22:25], off offset:256
	v_add_u32_e32 v158, 176, v146
	v_lshlrev_b32_e32 v158, 10, v158
	v_add_u32_e32 v158, s0, v158
	v_mov_b32_e32 v159, 0
	v_lshl_add_u64 v[158:159], v[158:159], 0, v[136:137]
	v_pk_mul_f32 v[14:15], v[14:15], v[232:233] op_sel_hi:[1,0]
	v_pk_mul_f32 v[16:17], v[16:17], v[232:233] op_sel_hi:[1,0]
	v_pk_mul_f32 v[10:11], v[10:11], v[232:233] op_sel_hi:[1,0]
	v_pk_mul_f32 v[12:13], v[12:13], v[232:233] op_sel_hi:[1,0]
	v_mul_f32_e32 v148, v15, v241
	v_mul_f32_e32 v149, v14, v241
	v_fma_f32 v148, v14, v240, -v148
	v_fma_f32 v149, v15, v240, v149
	v_cvt_pk_bf16_f32 v14, v148, v149
	v_mul_f32_e32 v148, v17, v243
	v_mul_f32_e32 v149, v16, v243
	v_fma_f32 v148, v16, v242, -v148
	v_fma_f32 v149, v17, v242, v149
	v_cvt_pk_bf16_f32 v15, v148, v149
	v_mul_f32_e32 v148, v11, v245
	v_mul_f32_e32 v149, v10, v245
	v_fma_f32 v148, v10, v244, -v148
	v_fma_f32 v149, v11, v244, v149
	v_cvt_pk_bf16_f32 v16, v148, v149
	v_mul_f32_e32 v148, v13, v247
	v_mul_f32_e32 v149, v12, v247
	v_fma_f32 v148, v12, v246, -v148
	v_fma_f32 v149, v13, v246, v149
	v_cvt_pk_bf16_f32 v17, v148, v149
	global_store_dwordx4 v[158:159], v[14:17], off offset:0
	v_pk_mul_f32 v[6:7], v[6:7], v[232:233] op_sel_hi:[1,0]
	v_pk_mul_f32 v[8:9], v[8:9], v[232:233] op_sel_hi:[1,0]
	v_pk_mul_f32 v[2:3], v[2:3], v[232:233] op_sel_hi:[1,0]
	v_pk_mul_f32 v[4:5], v[4:5], v[232:233] op_sel_hi:[1,0]
	v_mul_f32_e32 v148, v7, v241
	v_mul_f32_e32 v149, v6, v241
	v_fma_f32 v148, v6, v240, -v148
	v_fma_f32 v149, v7, v240, v149
	v_cvt_pk_bf16_f32 v6, v148, v149
	v_mul_f32_e32 v148, v9, v243
	v_mul_f32_e32 v149, v8, v243
	v_fma_f32 v148, v8, v242, -v148
	v_fma_f32 v149, v9, v242, v149
	v_cvt_pk_bf16_f32 v7, v148, v149
	v_mul_f32_e32 v148, v3, v245
	v_mul_f32_e32 v149, v2, v245
	v_fma_f32 v148, v2, v244, -v148
	v_fma_f32 v149, v3, v244, v149
	v_cvt_pk_bf16_f32 v8, v148, v149
	v_mul_f32_e32 v148, v5, v247
	v_mul_f32_e32 v149, v4, v247
	v_fma_f32 v148, v4, v246, -v148
	v_fma_f32 v149, v5, v246, v149
	v_cvt_pk_bf16_f32 v9, v148, v149
	global_store_dwordx4 v[158:159], v[6:9], off offset:256
	s_branch .LBB0_905
